# combo11 + GEMM K-loops rotated: loop-counter/pointer increments and the loop-top address selects are computed inside the last MFMA segment of the previous iteration (back-edge lands on the first LDS r
# baseline (speedup 1.0000x reference)
; #define PG8_STAGE(bufoff, gbase, voff) do { _Pragma("unroll") for (int _i = 0; _i < 2; ++_i) \
;         __builtin_amdgcn_global_load_lds((const unsigned*)((const char*)(gbase) + (voff)[_i]), (LAS unsigned*)(lds + (bufoff) + ldsw + _i * 8192), 16, 0, 0); } while (0)
; #define PG8_LDA(dst, b, h) do { _Pragma("unroll") for (int m = 0; m < 4; ++m) _Pragma("unroll") for (int k = 0; k < 2; ++k) dst[m][k] = *(const LAS bf16x8*)(lds + PG8_SA(b, h) + aoff + m * 2048 + k * 1024); } while (0)
; #define PG8_LDB(dst, b, h) do { _Pragma("unroll") for (int n = 0; n < 2; ++n) _Pragma("unroll") for (int k = 0; k < 2; ++k) dst[n][k] = *(const LAS bf16x8*)(lds + PG8_SB(b, h) + boff + n * 2048 + k * 1024); } while (0)
; #define PG8_MMA(ai, bj, At, Bt) do { __builtin_amdgcn_s_setprio(1); _Pragma("unroll") for (int m = 0; m < 4; ++m) _Pragma("unroll") for (int n = 0; n < 2; ++n) _Pragma("unroll") for (int k = 0; k < 2; ++k) \
;         acc[ai][bj][m][n] = __builtin_amdgcn_mfma_f32_16x16x32_bf16(Bt[n][k], At[m][k], acc[ai][bj][m][n], 0, 0, 0); __builtin_amdgcn_s_setprio(0); } while (0)
; #define PG8_WAIT_V(n) asm volatile("s_waitcnt vmcnt(" #n ")" ::: "memory")
; #define PG8_WAIT_L(n) asm volatile("s_waitcnt lgkmcnt(" #n ")" ::: "memory")
; #define PG8_BAR __builtin_amdgcn_s_barrier()
; #define PG8_SCHED __builtin_amdgcn_sched_barrier(0)
; template <class Epi>
; __device__ __forceinline__ void gemm_phase(LAS unsigned char* lds, const Gemm g, const StaticOrder& S, const Epi& E, const int tid) {
;     ...
;             PG8_LDB(B0, 0, 0); PG8_LDB(B1, 0, 1); PG8_SCHED; PG8_LDA(At, 0, 0); PG8_STAGE(PG8_SA(1, 1), a1 + hsA, voffA);
;             PG8_WAIT_V(8); PG8_WAIT_L(0); PG8_BAR; PG8_MMA(0, 0, At, B0); PG8_MMA(0, 1, At, B1); PG8_BAR; PG8_SCHED;
;             PG8_LDA(At, 0, 1); PG8_STAGE(PG8_SB(0, 0), b2, voffB); PG8_STAGE(PG8_SB(0, 1), b2 + hsB, voffB); PG8_STAGE(PG8_SA(0, 0), a2, voffA);
;             PG8_WAIT_V(8); PG8_WAIT_L(0); PG8_BAR; PG8_MMA(1, 0, At, B0); PG8_MMA(1, 1, At, B1); PG8_BAR; PG8_SCHED;
.Lkrot_a:
	v_add_u32_e32 v154, s24, v143
	v_add_u32_e32 v166, s25, v143
	ds_read_b128 v[138:141], v154
	ds_read_b128 v[146:149], v154 offset:1024
	ds_read_b128 v[150:153], v154 offset:2048
	ds_read_b128 v[154:157], v154 offset:3072
	ds_read_b128 v[158:161], v166
	ds_read_b128 v[162:165], v166 offset:1024
	ds_read_b128 v[184:187], v166 offset:2048
	ds_read_b128 v[188:191], v166 offset:3072
	v_lshl_add_u64 v[166:167], s[34:35], 0, v[134:135]
	s_add_i32 m0, s42, 0xc000
	ds_read_b128 v[192:195], v145
	ds_read_b128 v[196:199], v145 offset:1024
	ds_read_b128 v[200:203], v145 offset:2048
	ds_read_b128 v[204:207], v145 offset:3072
	ds_read_b128 v[208:211], v145 offset:4096
	ds_read_b128 v[230:233], v145 offset:5120
	ds_read_b128 v[234:237], v145 offset:6144
	ds_read_b128 v[238:241], v145 offset:7168
	global_load_lds_dwordx4 v[166:167], off
	v_lshl_add_u64 v[166:167], s[34:35], 0, v[136:137]
	s_add_i32 m0, s42, 0xe000
	s_nop 0
	global_load_lds_dwordx4 v[166:167], off
	s_waitcnt vmcnt(8)
	s_waitcnt lgkmcnt(0)
	s_barrier
	v_mfma_f32_16x16x32_bf16 v[124:127], v[138:141], v[192:195], v[124:127]
	v_mfma_f32_16x16x32_bf16 v[116:119], v[150:153], v[192:195], v[116:119]
	v_mfma_f32_16x16x32_bf16 v[108:111], v[138:141], v[200:203], v[108:111]
	v_mfma_f32_16x16x32_bf16 v[100:103], v[150:153], v[200:203], v[100:103]
	v_mfma_f32_16x16x32_bf16 v[92:95], v[138:141], v[208:211], v[92:95]
	v_mfma_f32_16x16x32_bf16 v[84:87], v[150:153], v[208:211], v[84:87]
	v_mfma_f32_16x16x32_bf16 v[76:79], v[138:141], v[234:237], v[76:79]
	v_mfma_f32_16x16x32_bf16 v[68:71], v[150:153], v[234:237], v[68:71]
	v_mfma_f32_16x16x32_bf16 v[124:127], v[146:149], v[196:199], v[124:127]
	v_mfma_f32_16x16x32_bf16 v[116:119], v[154:157], v[196:199], v[116:119]
	v_mfma_f32_16x16x32_bf16 v[108:111], v[146:149], v[204:207], v[108:111]
	v_mfma_f32_16x16x32_bf16 v[100:103], v[154:157], v[204:207], v[100:103]
	v_mfma_f32_16x16x32_bf16 v[92:95], v[146:149], v[230:233], v[92:95]
	v_mfma_f32_16x16x32_bf16 v[84:87], v[154:157], v[230:233], v[84:87]
	v_mfma_f32_16x16x32_bf16 v[76:79], v[146:149], v[238:241], v[76:79]
	v_mfma_f32_16x16x32_bf16 v[68:71], v[154:157], v[238:241], v[68:71]
	v_mfma_f32_16x16x32_bf16 v[120:123], v[158:161], v[192:195], v[120:123]
	v_mfma_f32_16x16x32_bf16 v[112:115], v[184:187], v[192:195], v[112:115]
	v_mfma_f32_16x16x32_bf16 v[104:107], v[158:161], v[200:203], v[104:107]
	v_mfma_f32_16x16x32_bf16 v[96:99], v[184:187], v[200:203], v[96:99]
	v_mfma_f32_16x16x32_bf16 v[88:91], v[158:161], v[208:211], v[88:91]
	v_mfma_f32_16x16x32_bf16 v[80:83], v[184:187], v[208:211], v[80:83]
	v_mfma_f32_16x16x32_bf16 v[72:75], v[158:161], v[234:237], v[72:75]
	v_mfma_f32_16x16x32_bf16 v[64:67], v[184:187], v[234:237], v[64:67]
	v_mfma_f32_16x16x32_bf16 v[120:123], v[162:165], v[196:199], v[120:123]
	v_mfma_f32_16x16x32_bf16 v[112:115], v[188:191], v[196:199], v[112:115]
	v_mfma_f32_16x16x32_bf16 v[104:107], v[162:165], v[204:207], v[104:107]
	v_mfma_f32_16x16x32_bf16 v[96:99], v[188:191], v[204:207], v[96:99]
	v_mfma_f32_16x16x32_bf16 v[88:91], v[162:165], v[230:233], v[88:91]
	v_mfma_f32_16x16x32_bf16 v[80:83], v[188:191], v[230:233], v[80:83]
	v_mfma_f32_16x16x32_bf16 v[72:75], v[162:165], v[238:241], v[72:75]
	v_mfma_f32_16x16x32_bf16 v[64:67], v[188:191], v[238:241], v[64:67]
	s_barrier
	s_add_i32 s24, s24, s27
	v_lshl_add_u64 v[166:167], s[0:1], 0, v[168:169]
	s_mov_b32 m0, s24
	ds_read_b128 v[192:195], v145 offset:16384
	ds_read_b128 v[196:199], v145 offset:17408
	ds_read_b128 v[200:203], v145 offset:18432
	ds_read_b128 v[204:207], v145 offset:19456
	ds_read_b128 v[208:211], v145 offset:20480
	ds_read_b128 v[230:233], v145 offset:21504
	ds_read_b128 v[234:237], v145 offset:22528
	ds_read_b128 v[238:241], v145 offset:23552
	global_load_lds_dwordx4 v[166:167], off
	s_add_i32 m0, s24, 0x2000
	s_add_u32 s68, s0, 0x80000
	v_lshl_add_u64 v[212:213], s[0:1], 0, v[132:133]
	s_addc_u32 s69, s1, 0
	s_add_i32 s24, s25, s27
	global_load_lds_dwordx4 v[212:213], off
	v_lshl_add_u64 v[242:243], s[68:69], 0, v[168:169]
	s_mov_b32 m0, s24
	v_lshl_add_u64 v[244:245], s[38:39], 0, v[130:131]
	global_load_lds_dwordx4 v[242:243], off
	v_lshl_add_u64 v[242:243], s[68:69], 0, v[132:133]
	s_add_i32 m0, s24, 0x2000
	s_nop 0
	global_load_lds_dwordx4 v[242:243], off
	v_lshl_add_u64 v[242:243], s[38:39], 0, v[128:129]
	s_mov_b32 m0, s42
	s_nop 0
	global_load_lds_dwordx4 v[242:243], off
	s_mov_b32 m0, s43
	s_nop 0
	global_load_lds_dwordx4 v[244:245], off
	s_waitcnt vmcnt(8)
	s_waitcnt lgkmcnt(0)
	s_barrier
	v_mfma_f32_16x16x32_bf16 v[60:63], v[138:141], v[192:195], v[60:63]
	v_mfma_f32_16x16x32_bf16 v[52:55], v[150:153], v[192:195], v[52:55]
	v_mfma_f32_16x16x32_bf16 v[44:47], v[138:141], v[200:203], v[44:47]
	v_mfma_f32_16x16x32_bf16 v[36:39], v[150:153], v[200:203], v[36:39]
	v_mfma_f32_16x16x32_bf16 v[28:31], v[138:141], v[208:211], v[28:31]
	v_mfma_f32_16x16x32_bf16 v[20:23], v[150:153], v[208:211], v[20:23]
	v_mfma_f32_16x16x32_bf16 v[12:15], v[138:141], v[234:237], v[12:15]
	v_mfma_f32_16x16x32_bf16 v[4:7], v[150:153], v[234:237], v[4:7]
	v_mfma_f32_16x16x32_bf16 v[60:63], v[146:149], v[196:199], v[60:63]
	v_mfma_f32_16x16x32_bf16 v[52:55], v[154:157], v[196:199], v[52:55]
	v_mfma_f32_16x16x32_bf16 v[44:47], v[146:149], v[204:207], v[44:47]
	v_mfma_f32_16x16x32_bf16 v[36:39], v[154:157], v[204:207], v[36:39]
	v_mfma_f32_16x16x32_bf16 v[28:31], v[146:149], v[230:233], v[28:31]
	v_mfma_f32_16x16x32_bf16 v[20:23], v[154:157], v[230:233], v[20:23]
	v_mfma_f32_16x16x32_bf16 v[12:15], v[146:149], v[238:241], v[12:15]
	v_mfma_f32_16x16x32_bf16 v[4:7], v[154:157], v[238:241], v[4:7]
	v_mfma_f32_16x16x32_bf16 v[56:59], v[158:161], v[192:195], v[56:59]
	v_mfma_f32_16x16x32_bf16 v[48:51], v[184:187], v[192:195], v[48:51]
	v_mfma_f32_16x16x32_bf16 v[40:43], v[158:161], v[200:203], v[40:43]
	v_mfma_f32_16x16x32_bf16 v[32:35], v[184:187], v[200:203], v[32:35]
	v_mfma_f32_16x16x32_bf16 v[24:27], v[158:161], v[208:211], v[24:27]
	v_mfma_f32_16x16x32_bf16 v[16:19], v[184:187], v[208:211], v[16:19]
	v_mfma_f32_16x16x32_bf16 v[8:11], v[158:161], v[234:237], v[8:11]
	v_mfma_f32_16x16x32_bf16 v[0:3], v[184:187], v[234:237], v[0:3]
	v_mfma_f32_16x16x32_bf16 v[56:59], v[162:165], v[196:199], v[56:59]
	v_mfma_f32_16x16x32_bf16 v[48:51], v[188:191], v[196:199], v[48:51]
	v_mfma_f32_16x16x32_bf16 v[40:43], v[162:165], v[204:207], v[40:43]
	v_mfma_f32_16x16x32_bf16 v[32:35], v[188:191], v[204:207], v[32:35]
	v_mfma_f32_16x16x32_bf16 v[24:27], v[162:165], v[230:233], v[24:27]
	v_mfma_f32_16x16x32_bf16 v[16:19], v[188:191], v[230:233], v[16:19]
	v_mfma_f32_16x16x32_bf16 v[8:11], v[162:165], v[238:241], v[8:11]
	v_mfma_f32_16x16x32_bf16 v[0:3], v[188:191], v[238:241], v[0:3]
	s_barrier
; #define PG8_STAGE(bufoff, gbase, voff) do { _Pragma("unroll") for (int _i = 0; _i < 2; ++_i) \
;         __builtin_amdgcn_global_load_lds((const unsigned*)((const char*)(gbase) + (voff)[_i]), (LAS unsigned*)(lds + (bufoff) + ldsw + _i * 8192), 16, 0, 0); } while (0)
; #define PG8_LDA(dst, b, h) do { _Pragma("unroll") for (int m = 0; m < 4; ++m) _Pragma("unroll") for (int k = 0; k < 2; ++k) dst[m][k] = *(const LAS bf16x8*)(lds + PG8_SA(b, h) + aoff + m * 2048 + k * 1024); } while (0)
; #define PG8_LDB(dst, b, h) do { _Pragma("unroll") for (int n = 0; n < 2; ++n) _Pragma("unroll") for (int k = 0; k < 2; ++k) dst[n][k] = *(const LAS bf16x8*)(lds + PG8_SB(b, h) + boff + n * 2048 + k * 1024); } while (0)
; #define PG8_MMA(ai, bj, At, Bt) do { __builtin_amdgcn_s_setprio(1); _Pragma("unroll") for (int m = 0; m < 4; ++m) _Pragma("unroll") for (int n = 0; n < 2; ++n) _Pragma("unroll") for (int k = 0; k < 2; ++k) \
;         acc[ai][bj][m][n] = __builtin_amdgcn_mfma_f32_16x16x32_bf16(Bt[n][k], At[m][k], acc[ai][bj][m][n], 0, 0, 0); __builtin_amdgcn_s_setprio(0); } while (0)
; #define PG8_WAIT_V(n) asm volatile("s_waitcnt vmcnt(" #n ")" ::: "memory")
; #define PG8_WAIT_L(n) asm volatile("s_waitcnt lgkmcnt(" #n ")" ::: "memory")
; #define PG8_BAR __builtin_amdgcn_s_barrier()
; #define PG8_SCHED __builtin_amdgcn_sched_barrier(0)
; template <class Epi>
; __device__ __forceinline__ void gemm_phase(LAS unsigned char* lds, const Gemm g, const StaticOrder& S, const Epi& E, const int tid) {
;     ...
;             PG8_LDB(B0, 1, 0); PG8_LDB(B1, 1, 1); PG8_SCHED; PG8_LDA(At, 1, 0); PG8_STAGE(PG8_SA(0, 1), a2 + hsA, voffA);
;             PG8_WAIT_V(8); PG8_WAIT_L(0); PG8_BAR; PG8_MMA(0, 0, At, B0); PG8_MMA(0, 1, At, B1); PG8_BAR; PG8_SCHED;
	s_add_i32 s24, 0, 0x18000
	s_add_i32 s25, 0, 0x1c000
	v_add_u32_e32 v154, s24, v143
	v_add_u32_e32 v170, s25, v143
	ds_read_b128 v[138:141], v154
	ds_read_b128 v[146:149], v154 offset:1024
	ds_read_b128 v[150:153], v154 offset:2048
	ds_read_b128 v[154:157], v154 offset:3072
	ds_read_b128 v[158:161], v170
	ds_read_b128 v[162:165], v170 offset:1024
	ds_read_b128 v[184:187], v170 offset:2048
	ds_read_b128 v[188:191], v170 offset:3072
	s_add_u32 s38, s38, 0x80000
	s_addc_u32 s39, s39, 0
	s_mov_b32 m0, s44
	v_lshl_add_u64 v[246:247], s[38:39], 0, v[128:129]
	ds_read_b128 v[192:195], v145 offset:32768
	ds_read_b128 v[196:199], v145 offset:33792
	ds_read_b128 v[200:203], v145 offset:34816
	ds_read_b128 v[204:207], v145 offset:35840
	ds_read_b128 v[208:211], v145 offset:36864
	ds_read_b128 v[230:233], v145 offset:37888
	ds_read_b128 v[234:237], v145 offset:38912
	ds_read_b128 v[238:241], v145 offset:39936
	global_load_lds_dwordx4 v[246:247], off
	v_lshl_add_u64 v[246:247], s[38:39], 0, v[130:131]
	s_mov_b32 m0, s45
	s_nop 0
	global_load_lds_dwordx4 v[246:247], off
	s_waitcnt vmcnt(8)
	s_waitcnt lgkmcnt(0)
	s_barrier
	v_mfma_f32_16x16x32_bf16 v[124:127], v[138:141], v[192:195], v[124:127]
	v_mfma_f32_16x16x32_bf16 v[116:119], v[150:153], v[192:195], v[116:119]
	v_mfma_f32_16x16x32_bf16 v[108:111], v[138:141], v[200:203], v[108:111]
	v_mfma_f32_16x16x32_bf16 v[100:103], v[150:153], v[200:203], v[100:103]
	v_mfma_f32_16x16x32_bf16 v[92:95], v[138:141], v[208:211], v[92:95]
	v_mfma_f32_16x16x32_bf16 v[84:87], v[150:153], v[208:211], v[84:87]
	v_mfma_f32_16x16x32_bf16 v[76:79], v[138:141], v[234:237], v[76:79]
	v_mfma_f32_16x16x32_bf16 v[68:71], v[150:153], v[234:237], v[68:71]
	v_mfma_f32_16x16x32_bf16 v[124:127], v[146:149], v[196:199], v[124:127]
	v_mfma_f32_16x16x32_bf16 v[116:119], v[154:157], v[196:199], v[116:119]
	v_mfma_f32_16x16x32_bf16 v[108:111], v[146:149], v[204:207], v[108:111]
	v_mfma_f32_16x16x32_bf16 v[100:103], v[154:157], v[204:207], v[100:103]
	v_mfma_f32_16x16x32_bf16 v[92:95], v[146:149], v[230:233], v[92:95]
	v_mfma_f32_16x16x32_bf16 v[84:87], v[154:157], v[230:233], v[84:87]
	v_mfma_f32_16x16x32_bf16 v[76:79], v[146:149], v[238:241], v[76:79]
	v_mfma_f32_16x16x32_bf16 v[68:71], v[154:157], v[238:241], v[68:71]
	v_mfma_f32_16x16x32_bf16 v[120:123], v[158:161], v[192:195], v[120:123]
	v_mfma_f32_16x16x32_bf16 v[112:115], v[184:187], v[192:195], v[112:115]
	v_mfma_f32_16x16x32_bf16 v[104:107], v[158:161], v[200:203], v[104:107]
	v_mfma_f32_16x16x32_bf16 v[96:99], v[184:187], v[200:203], v[96:99]
	v_mfma_f32_16x16x32_bf16 v[88:91], v[158:161], v[208:211], v[88:91]
	v_mfma_f32_16x16x32_bf16 v[80:83], v[184:187], v[208:211], v[80:83]
	v_mfma_f32_16x16x32_bf16 v[72:75], v[158:161], v[234:237], v[72:75]
	v_mfma_f32_16x16x32_bf16 v[64:67], v[184:187], v[234:237], v[64:67]
	v_mfma_f32_16x16x32_bf16 v[120:123], v[162:165], v[196:199], v[120:123]
	v_mfma_f32_16x16x32_bf16 v[112:115], v[188:191], v[196:199], v[112:115]
	v_mfma_f32_16x16x32_bf16 v[104:107], v[162:165], v[204:207], v[104:107]
	v_mfma_f32_16x16x32_bf16 v[96:99], v[188:191], v[204:207], v[96:99]
	v_mfma_f32_16x16x32_bf16 v[88:91], v[162:165], v[230:233], v[88:91]
	v_mfma_f32_16x16x32_bf16 v[80:83], v[188:191], v[230:233], v[80:83]
	v_mfma_f32_16x16x32_bf16 v[72:75], v[162:165], v[238:241], v[72:75]
	v_mfma_f32_16x16x32_bf16 v[64:67], v[188:191], v[238:241], v[64:67]
	s_barrier
; #define PG8_STAGE(bufoff, gbase, voff) do { _Pragma("unroll") for (int _i = 0; _i < 2; ++_i) \
;         __builtin_amdgcn_global_load_lds((const unsigned*)((const char*)(gbase) + (voff)[_i]), (LAS unsigned*)(lds + (bufoff) + ldsw + _i * 8192), 16, 0, 0); } while (0)
; #define PG8_LDA(dst, b, h) do { _Pragma("unroll") for (int m = 0; m < 4; ++m) _Pragma("unroll") for (int k = 0; k < 2; ++k) dst[m][k] = *(const LAS bf16x8*)(lds + PG8_SA(b, h) + aoff + m * 2048 + k * 1024); } while (0)
; #define PG8_MMA(ai, bj, At, Bt) do { __builtin_amdgcn_s_setprio(1); _Pragma("unroll") for (int m = 0; m < 4; ++m) _Pragma("unroll") for (int n = 0; n < 2; ++n) _Pragma("unroll") for (int k = 0; k < 2; ++k) \
;         acc[ai][bj][m][n] = __builtin_amdgcn_mfma_f32_16x16x32_bf16(Bt[n][k], At[m][k], acc[ai][bj][m][n], 0, 0, 0); __builtin_amdgcn_s_setprio(0); } while (0)
; #define PG8_WAIT_V(n) asm volatile("s_waitcnt vmcnt(" #n ")" ::: "memory")
; #define PG8_WAIT_L(n) asm volatile("s_waitcnt lgkmcnt(" #n ")" ::: "memory")
; #define PG8_BAR __builtin_amdgcn_s_barrier()
; #define PG8_SCHED __builtin_amdgcn_sched_barrier(0)
; template <class Epi>
; __device__ __forceinline__ void gemm_phase(LAS unsigned char* lds, const Gemm g, const StaticOrder& S, const Epi& E, const int tid) {
;     ...
;         for (int t = 0; t < nt; t += 2) {
;             const bool last = (t == nt - 2);
;             const char* a1 = cA + (size_t)(t + 1) * kstep;
;             const char* a2 = last ? nA : cA + (size_t)(t + 2) * kstep; const char* b2 = last ? nB : cB + (size_t)(t + 2) * kstep;
;             const char* a3 = a2 + kstep; const char* b3 = b2 + kstep;
;     ...
;             PG8_LDA(At, 1, 1); PG8_STAGE(PG8_SB(1, 0), b3, voffB); PG8_STAGE(PG8_SB(1, 1), b3 + hsB, voffB); PG8_STAGE(PG8_SA(1, 0), a3, voffA);
;             PG8_WAIT_V(8); PG8_WAIT_L(0); PG8_BAR; PG8_MMA(1, 0, At, B0); PG8_MMA(1, 1, At, B1); PG8_BAR; PG8_SCHED;
	s_add_i32 s24, s24, s27
	v_lshl_add_u64 v[166:167], v[166:167], 0, s[28:29]
	s_mov_b32 m0, s24
	ds_read_b128 v[192:195], v145 offset:49152
	ds_read_b128 v[196:199], v145 offset:50176
	ds_read_b128 v[200:203], v145 offset:51200
	ds_read_b128 v[204:207], v145 offset:52224
	ds_read_b128 v[208:211], v145 offset:53248
	ds_read_b128 v[230:233], v145 offset:54272
	ds_read_b128 v[234:237], v145 offset:55296
	ds_read_b128 v[238:241], v145 offset:56320
	global_load_lds_dwordx4 v[166:167], off
	s_add_i32 m0, s24, 0x2000
	s_add_u32 s0, s0, 0x80080
	v_lshl_add_u64 v[166:167], v[212:213], 0, s[28:29]
	s_addc_u32 s1, s1, 0
	s_add_i32 s24, s25, s27
	global_load_lds_dwordx4 v[166:167], off
	v_lshl_add_u64 v[166:167], s[0:1], 0, v[168:169]
	s_mov_b32 m0, s24
	s_nop 0
	global_load_lds_dwordx4 v[166:167], off
	v_lshl_add_u64 v[166:167], s[0:1], 0, v[132:133]
	s_add_i32 m0, s24, 0x2000
	s_nop 0
	global_load_lds_dwordx4 v[166:167], off
	v_lshl_add_u64 v[166:167], v[242:243], 0, s[28:29]
	s_mov_b32 m0, s46
	s_nop 0
	global_load_lds_dwordx4 v[166:167], off
	v_lshl_add_u64 v[166:167], v[244:245], 0, s[28:29]
	s_mov_b32 m0, s47
	s_nop 0
	global_load_lds_dwordx4 v[166:167], off
	s_waitcnt vmcnt(8)
	s_waitcnt lgkmcnt(0)
	s_barrier
	v_mfma_f32_16x16x32_bf16 v[60:63], v[138:141], v[192:195], v[60:63]
	s_add_i32 s59, s59, 2
	s_add_u32 s34, s34, 0x100
	s_addc_u32 s35, s35, 0
	s_add_u32 s57, s57, 0x100
	v_mfma_f32_16x16x32_bf16 v[52:55], v[150:153], v[192:195], v[52:55]
	s_addc_u32 s58, s58, 0
	s_add_u32 s0, s34, 0xfff80080
	s_addc_u32 s1, s35, -1
	s_add_i32 s24, 0, 0x10000
	v_mfma_f32_16x16x32_bf16 v[44:47], v[138:141], v[200:203], v[44:47]
	s_cmp_eq_u32 s59, 28
	s_cselect_b32 s39, s15, s1
	s_cselect_b32 s38, s53, s0
	s_cselect_b32 s1, s13, s58
	v_mfma_f32_16x16x32_bf16 v[36:39], v[150:153], v[200:203], v[36:39]
	s_cselect_b32 s0, s56, s57
	s_add_i32 s25, 0, 0x14000
	s_cmp_gt_u32 s59, 29
	v_mfma_f32_16x16x32_bf16 v[28:31], v[138:141], v[208:211], v[28:31]
	v_mfma_f32_16x16x32_bf16 v[20:23], v[150:153], v[208:211], v[20:23]
	v_mfma_f32_16x16x32_bf16 v[12:15], v[138:141], v[234:237], v[12:15]
	v_mfma_f32_16x16x32_bf16 v[4:7], v[150:153], v[234:237], v[4:7]
	v_mfma_f32_16x16x32_bf16 v[60:63], v[146:149], v[196:199], v[60:63]
	v_mfma_f32_16x16x32_bf16 v[52:55], v[154:157], v[196:199], v[52:55]
	v_mfma_f32_16x16x32_bf16 v[44:47], v[146:149], v[204:207], v[44:47]
	v_mfma_f32_16x16x32_bf16 v[36:39], v[154:157], v[204:207], v[36:39]
	v_mfma_f32_16x16x32_bf16 v[28:31], v[146:149], v[230:233], v[28:31]
	v_mfma_f32_16x16x32_bf16 v[20:23], v[154:157], v[230:233], v[20:23]
	v_mfma_f32_16x16x32_bf16 v[12:15], v[146:149], v[238:241], v[12:15]
	v_mfma_f32_16x16x32_bf16 v[4:7], v[154:157], v[238:241], v[4:7]
	v_mfma_f32_16x16x32_bf16 v[56:59], v[158:161], v[192:195], v[56:59]
	v_mfma_f32_16x16x32_bf16 v[48:51], v[184:187], v[192:195], v[48:51]
	v_mfma_f32_16x16x32_bf16 v[40:43], v[158:161], v[200:203], v[40:43]
	v_mfma_f32_16x16x32_bf16 v[32:35], v[184:187], v[200:203], v[32:35]
	v_mfma_f32_16x16x32_bf16 v[24:27], v[158:161], v[208:211], v[24:27]
	v_mfma_f32_16x16x32_bf16 v[16:19], v[184:187], v[208:211], v[16:19]
	v_mfma_f32_16x16x32_bf16 v[8:11], v[158:161], v[234:237], v[8:11]
	v_mfma_f32_16x16x32_bf16 v[0:3], v[184:187], v[234:237], v[0:3]
	v_mfma_f32_16x16x32_bf16 v[56:59], v[162:165], v[196:199], v[56:59]
	v_mfma_f32_16x16x32_bf16 v[48:51], v[188:191], v[196:199], v[48:51]
	v_mfma_f32_16x16x32_bf16 v[40:43], v[162:165], v[204:207], v[40:43]
	v_mfma_f32_16x16x32_bf16 v[32:35], v[188:191], v[204:207], v[32:35]
	v_mfma_f32_16x16x32_bf16 v[24:27], v[162:165], v[230:233], v[24:27]
	v_mfma_f32_16x16x32_bf16 v[16:19], v[188:191], v[230:233], v[16:19]
	v_mfma_f32_16x16x32_bf16 v[8:11], v[162:165], v[238:241], v[8:11]
	v_mfma_f32_16x16x32_bf16 v[0:3], v[188:191], v[238:241], v[0:3]
	s_barrier
	s_cbranch_scc0 .Lkrot_a
	s_and_b64 vcc, exec, s[10:11]
	s_cbranch_vccz .LBB0_164
	s_barrier

; #define PG8_STAGE(bufoff, gbase, voff) do { _Pragma("unroll") for (int _i = 0; _i < 2; ++_i) \
;         __builtin_amdgcn_global_load_lds((const unsigned*)((const char*)(gbase) + (voff)[_i]), (LAS unsigned*)(lds + (bufoff) + ldsw + _i * 8192), 16, 0, 0); } while (0)
; #define PG8_LDA(dst, b, h) do { _Pragma("unroll") for (int m = 0; m < 4; ++m) _Pragma("unroll") for (int k = 0; k < 2; ++k) dst[m][k] = *(const LAS bf16x8*)(lds + PG8_SA(b, h) + aoff + m * 2048 + k * 1024); } while (0)
; #define PG8_LDB(dst, b, h) do { _Pragma("unroll") for (int n = 0; n < 2; ++n) _Pragma("unroll") for (int k = 0; k < 2; ++k) dst[n][k] = *(const LAS bf16x8*)(lds + PG8_SB(b, h) + boff + n * 2048 + k * 1024); } while (0)
; #define PG8_MMA(ai, bj, At, Bt) do { __builtin_amdgcn_s_setprio(1); _Pragma("unroll") for (int m = 0; m < 4; ++m) _Pragma("unroll") for (int n = 0; n < 2; ++n) _Pragma("unroll") for (int k = 0; k < 2; ++k) \
;         acc[ai][bj][m][n] = __builtin_amdgcn_mfma_f32_16x16x32_bf16(Bt[n][k], At[m][k], acc[ai][bj][m][n], 0, 0, 0); __builtin_amdgcn_s_setprio(0); } while (0)
; #define PG8_WAIT_V(n) asm volatile("s_waitcnt vmcnt(" #n ")" ::: "memory")
; #define PG8_WAIT_L(n) asm volatile("s_waitcnt lgkmcnt(" #n ")" ::: "memory")
; #define PG8_BAR __builtin_amdgcn_s_barrier()
; #define PG8_SCHED __builtin_amdgcn_sched_barrier(0)
; template <class Epi>
; __device__ __forceinline__ void gemm_phase(LAS unsigned char* lds, const Gemm g, const StaticOrder& S, const Epi& E, const int tid) {
;     ...
;             PG8_LDB(B0, 0, 0); PG8_LDB(B1, 0, 1); PG8_SCHED; PG8_LDA(At, 0, 0); PG8_STAGE(PG8_SA(1, 1), a1 + hsA, voffA);
;             PG8_WAIT_V(8); PG8_WAIT_L(0); PG8_BAR; PG8_MMA(0, 0, At, B0); PG8_MMA(0, 1, At, B1); PG8_BAR; PG8_SCHED;
;             PG8_LDA(At, 0, 1); PG8_STAGE(PG8_SB(0, 0), b2, voffB); PG8_STAGE(PG8_SB(0, 1), b2 + hsB, voffB); PG8_STAGE(PG8_SA(0, 0), a2, voffA);
;             PG8_WAIT_V(8); PG8_WAIT_L(0); PG8_BAR; PG8_MMA(1, 0, At, B0); PG8_MMA(1, 1, At, B1); PG8_BAR; PG8_SCHED;
.Lkrot_b:
	v_add_u32_e32 v152, s24, v193
	v_add_u32_e32 v170, s25, v193
	ds_read_b128 v[128:131], v152
	ds_read_b128 v[132:135], v152 offset:1024
	ds_read_b128 v[136:139], v152 offset:2048
	ds_read_b128 v[152:155], v152 offset:3072
	ds_read_b128 v[156:159], v170
	ds_read_b128 v[160:163], v170 offset:1024
	ds_read_b128 v[164:167], v170 offset:2048
	ds_read_b128 v[184:187], v170 offset:3072
	v_lshl_add_u64 v[212:213], s[18:19], 0, v[148:149]
	s_add_i32 m0, s44, 0xc000
	ds_read_b128 v[188:191], v198
	ds_read_b128 v[200:203], v198 offset:1024
	ds_read_b128 v[204:207], v198 offset:2048
	ds_read_b128 v[208:211], v198 offset:3072
	ds_read_b128 v[230:233], v198 offset:4096
	ds_read_b128 v[234:237], v198 offset:5120
	ds_read_b128 v[238:241], v198 offset:6144
	ds_read_b128 v[242:245], v198 offset:7168
	global_load_lds_dwordx4 v[212:213], off
	v_lshl_add_u64 v[212:213], s[18:19], 0, v[150:151]
	s_add_i32 m0, s44, 0xe000
	s_nop 0
	global_load_lds_dwordx4 v[212:213], off
	s_waitcnt vmcnt(8)
	s_waitcnt lgkmcnt(0)
	s_barrier
	v_mfma_f32_16x16x32_bf16 v[124:127], v[128:131], v[188:191], v[124:127]
	v_mfma_f32_16x16x32_bf16 v[120:123], v[136:139], v[188:191], v[120:123]
	v_mfma_f32_16x16x32_bf16 v[116:119], v[128:131], v[204:207], v[116:119]
	v_mfma_f32_16x16x32_bf16 v[108:111], v[136:139], v[204:207], v[108:111]
	v_mfma_f32_16x16x32_bf16 v[92:95], v[128:131], v[230:233], v[92:95]
	v_mfma_f32_16x16x32_bf16 v[88:91], v[136:139], v[230:233], v[88:91]
	v_mfma_f32_16x16x32_bf16 v[80:83], v[128:131], v[238:241], v[80:83]
	v_mfma_f32_16x16x32_bf16 v[72:75], v[136:139], v[238:241], v[72:75]
	v_mfma_f32_16x16x32_bf16 v[124:127], v[132:135], v[200:203], v[124:127]
	v_mfma_f32_16x16x32_bf16 v[120:123], v[152:155], v[200:203], v[120:123]
	v_mfma_f32_16x16x32_bf16 v[116:119], v[132:135], v[208:211], v[116:119]
	v_mfma_f32_16x16x32_bf16 v[108:111], v[152:155], v[208:211], v[108:111]
	v_mfma_f32_16x16x32_bf16 v[92:95], v[132:135], v[234:237], v[92:95]
	v_mfma_f32_16x16x32_bf16 v[88:91], v[152:155], v[234:237], v[88:91]
	v_mfma_f32_16x16x32_bf16 v[80:83], v[132:135], v[242:245], v[80:83]
	v_mfma_f32_16x16x32_bf16 v[72:75], v[152:155], v[242:245], v[72:75]
	v_mfma_f32_16x16x32_bf16 v[112:115], v[156:159], v[188:191], v[112:115]
	v_mfma_f32_16x16x32_bf16 v[104:107], v[164:167], v[188:191], v[104:107]
	v_mfma_f32_16x16x32_bf16 v[100:103], v[156:159], v[204:207], v[100:103]
	v_mfma_f32_16x16x32_bf16 v[96:99], v[164:167], v[204:207], v[96:99]
	v_mfma_f32_16x16x32_bf16 v[84:87], v[156:159], v[230:233], v[84:87]
	v_mfma_f32_16x16x32_bf16 v[76:79], v[164:167], v[230:233], v[76:79]
	v_mfma_f32_16x16x32_bf16 v[68:71], v[156:159], v[238:241], v[68:71]
	v_mfma_f32_16x16x32_bf16 v[64:67], v[164:167], v[238:241], v[64:67]
	v_mfma_f32_16x16x32_bf16 v[112:115], v[160:163], v[200:203], v[112:115]
	v_mfma_f32_16x16x32_bf16 v[104:107], v[184:187], v[200:203], v[104:107]
	v_mfma_f32_16x16x32_bf16 v[100:103], v[160:163], v[208:211], v[100:103]
	v_mfma_f32_16x16x32_bf16 v[96:99], v[184:187], v[208:211], v[96:99]
	v_mfma_f32_16x16x32_bf16 v[84:87], v[160:163], v[234:237], v[84:87]
	v_mfma_f32_16x16x32_bf16 v[76:79], v[184:187], v[234:237], v[76:79]
	v_mfma_f32_16x16x32_bf16 v[68:71], v[160:163], v[242:245], v[68:71]
	v_mfma_f32_16x16x32_bf16 v[64:67], v[184:187], v[242:245], v[64:67]
	s_barrier
	s_add_i32 s18, s24, s39
	v_lshl_add_u64 v[212:213], s[34:35], 0, v[144:145]
	s_mov_b32 m0, s18
	ds_read_b128 v[188:191], v198 offset:16384
	ds_read_b128 v[200:203], v198 offset:17408
	ds_read_b128 v[204:207], v198 offset:18432
	ds_read_b128 v[208:211], v198 offset:19456
	ds_read_b128 v[230:233], v198 offset:20480
	ds_read_b128 v[234:237], v198 offset:21504
	ds_read_b128 v[238:241], v198 offset:22528
	ds_read_b128 v[242:245], v198 offset:23552
	global_load_lds_dwordx4 v[212:213], off
	s_add_i32 m0, s18, 0x2000
	s_add_u32 s18, s34, 0x160000
	v_lshl_add_u64 v[246:247], s[34:35], 0, v[140:141]
	s_addc_u32 s19, s35, 0
	s_add_i32 s24, s25, s39
	global_load_lds_dwordx4 v[246:247], off
	v_lshl_add_u64 v[248:249], s[18:19], 0, v[144:145]
	s_mov_b32 m0, s24
	v_lshl_add_u64 v[250:251], s[36:37], 0, v[142:143]
	global_load_lds_dwordx4 v[248:249], off
	v_lshl_add_u64 v[248:249], s[18:19], 0, v[140:141]
	s_add_i32 m0, s24, 0x2000
	s_nop 0
	global_load_lds_dwordx4 v[248:249], off
	v_lshl_add_u64 v[248:249], s[36:37], 0, v[146:147]
	s_mov_b32 m0, s44
	s_nop 0
	global_load_lds_dwordx4 v[248:249], off
	s_mov_b32 m0, s45
	s_nop 0
	global_load_lds_dwordx4 v[250:251], off
	s_waitcnt vmcnt(8)
	s_waitcnt lgkmcnt(0)
	s_barrier
	v_mfma_f32_16x16x32_bf16 v[60:63], v[128:131], v[188:191], v[60:63]
	v_mfma_f32_16x16x32_bf16 v[56:59], v[136:139], v[188:191], v[56:59]
	v_mfma_f32_16x16x32_bf16 v[44:47], v[128:131], v[204:207], v[44:47]
	v_mfma_f32_16x16x32_bf16 v[40:43], v[136:139], v[204:207], v[40:43]
	v_mfma_f32_16x16x32_bf16 v[28:31], v[128:131], v[230:233], v[28:31]
	v_mfma_f32_16x16x32_bf16 v[24:27], v[136:139], v[230:233], v[24:27]
	v_mfma_f32_16x16x32_bf16 v[12:15], v[128:131], v[238:241], v[12:15]
	v_mfma_f32_16x16x32_bf16 v[8:11], v[136:139], v[238:241], v[8:11]
	v_mfma_f32_16x16x32_bf16 v[60:63], v[132:135], v[200:203], v[60:63]
	v_mfma_f32_16x16x32_bf16 v[56:59], v[152:155], v[200:203], v[56:59]
	v_mfma_f32_16x16x32_bf16 v[44:47], v[132:135], v[208:211], v[44:47]
	v_mfma_f32_16x16x32_bf16 v[40:43], v[152:155], v[208:211], v[40:43]
	v_mfma_f32_16x16x32_bf16 v[28:31], v[132:135], v[234:237], v[28:31]
	v_mfma_f32_16x16x32_bf16 v[24:27], v[152:155], v[234:237], v[24:27]
	v_mfma_f32_16x16x32_bf16 v[12:15], v[132:135], v[242:245], v[12:15]
	v_mfma_f32_16x16x32_bf16 v[8:11], v[152:155], v[242:245], v[8:11]
	v_mfma_f32_16x16x32_bf16 v[52:55], v[156:159], v[188:191], v[52:55]
	v_mfma_f32_16x16x32_bf16 v[48:51], v[164:167], v[188:191], v[48:51]
	v_mfma_f32_16x16x32_bf16 v[36:39], v[156:159], v[204:207], v[36:39]
	v_mfma_f32_16x16x32_bf16 v[32:35], v[164:167], v[204:207], v[32:35]
	v_mfma_f32_16x16x32_bf16 v[20:23], v[156:159], v[230:233], v[20:23]
	v_mfma_f32_16x16x32_bf16 v[16:19], v[164:167], v[230:233], v[16:19]
	v_mfma_f32_16x16x32_bf16 v[4:7], v[156:159], v[238:241], v[4:7]
	v_mfma_f32_16x16x32_bf16 v[0:3], v[164:167], v[238:241], v[0:3]
	v_mfma_f32_16x16x32_bf16 v[52:55], v[160:163], v[200:203], v[52:55]
	v_mfma_f32_16x16x32_bf16 v[48:51], v[184:187], v[200:203], v[48:51]
	v_mfma_f32_16x16x32_bf16 v[36:39], v[160:163], v[208:211], v[36:39]
	v_mfma_f32_16x16x32_bf16 v[32:35], v[184:187], v[208:211], v[32:35]
	v_mfma_f32_16x16x32_bf16 v[20:23], v[160:163], v[234:237], v[20:23]
	v_mfma_f32_16x16x32_bf16 v[16:19], v[184:187], v[234:237], v[16:19]
	v_mfma_f32_16x16x32_bf16 v[4:7], v[160:163], v[242:245], v[4:7]
	v_mfma_f32_16x16x32_bf16 v[0:3], v[184:187], v[242:245], v[0:3]
	s_barrier
; #define PG8_STAGE(bufoff, gbase, voff) do { _Pragma("unroll") for (int _i = 0; _i < 2; ++_i) \
;         __builtin_amdgcn_global_load_lds((const unsigned*)((const char*)(gbase) + (voff)[_i]), (LAS unsigned*)(lds + (bufoff) + ldsw + _i * 8192), 16, 0, 0); } while (0)
; #define PG8_LDA(dst, b, h) do { _Pragma("unroll") for (int m = 0; m < 4; ++m) _Pragma("unroll") for (int k = 0; k < 2; ++k) dst[m][k] = *(const LAS bf16x8*)(lds + PG8_SA(b, h) + aoff + m * 2048 + k * 1024); } while (0)
; #define PG8_LDB(dst, b, h) do { _Pragma("unroll") for (int n = 0; n < 2; ++n) _Pragma("unroll") for (int k = 0; k < 2; ++k) dst[n][k] = *(const LAS bf16x8*)(lds + PG8_SB(b, h) + boff + n * 2048 + k * 1024); } while (0)
; #define PG8_MMA(ai, bj, At, Bt) do { __builtin_amdgcn_s_setprio(1); _Pragma("unroll") for (int m = 0; m < 4; ++m) _Pragma("unroll") for (int n = 0; n < 2; ++n) _Pragma("unroll") for (int k = 0; k < 2; ++k) \
;         acc[ai][bj][m][n] = __builtin_amdgcn_mfma_f32_16x16x32_bf16(Bt[n][k], At[m][k], acc[ai][bj][m][n], 0, 0, 0); __builtin_amdgcn_s_setprio(0); } while (0)
; #define PG8_WAIT_V(n) asm volatile("s_waitcnt vmcnt(" #n ")" ::: "memory")
; #define PG8_WAIT_L(n) asm volatile("s_waitcnt lgkmcnt(" #n ")" ::: "memory")
; #define PG8_BAR __builtin_amdgcn_s_barrier()
; #define PG8_SCHED __builtin_amdgcn_sched_barrier(0)
; template <class Epi>
; __device__ __forceinline__ void gemm_phase(LAS unsigned char* lds, const Gemm g, const StaticOrder& S, const Epi& E, const int tid) {
;     ...
;             PG8_LDB(B0, 1, 0); PG8_LDB(B1, 1, 1); PG8_SCHED; PG8_LDA(At, 1, 0); PG8_STAGE(PG8_SA(0, 1), a2 + hsA, voffA);
;             PG8_WAIT_V(8); PG8_WAIT_L(0); PG8_BAR; PG8_MMA(0, 0, At, B0); PG8_MMA(0, 1, At, B1); PG8_BAR; PG8_SCHED;
	s_add_i32 s24, 0, 0x18000
	s_add_i32 s25, 0, 0x1c000
	v_add_u32_e32 v152, s24, v193
	v_add_u32_e32 v170, s25, v193
	ds_read_b128 v[128:131], v152
	ds_read_b128 v[132:135], v152 offset:1024
	ds_read_b128 v[136:139], v152 offset:2048
	ds_read_b128 v[152:155], v152 offset:3072
	ds_read_b128 v[156:159], v170
	ds_read_b128 v[160:163], v170 offset:1024
	ds_read_b128 v[164:167], v170 offset:2048
	ds_read_b128 v[184:187], v170 offset:3072
	s_add_u32 s18, s36, 0x160000
	s_addc_u32 s19, s37, 0
	s_mov_b32 m0, s46
	v_lshl_add_u64 v[170:171], s[18:19], 0, v[146:147]
	ds_read_b128 v[188:191], v198 offset:32768
	ds_read_b128 v[200:203], v198 offset:33792
	ds_read_b128 v[204:207], v198 offset:34816
	ds_read_b128 v[208:211], v198 offset:35840
	ds_read_b128 v[230:233], v198 offset:36864
	ds_read_b128 v[234:237], v198 offset:37888
	ds_read_b128 v[238:241], v198 offset:38912
	ds_read_b128 v[242:245], v198 offset:39936
	global_load_lds_dwordx4 v[170:171], off
	v_lshl_add_u64 v[170:171], s[18:19], 0, v[142:143]
	s_mov_b32 m0, s47
	s_nop 0
	global_load_lds_dwordx4 v[170:171], off
	s_waitcnt vmcnt(8)
	s_waitcnt lgkmcnt(0)
	s_barrier
	v_mfma_f32_16x16x32_bf16 v[124:127], v[128:131], v[188:191], v[124:127]
	v_mfma_f32_16x16x32_bf16 v[120:123], v[136:139], v[188:191], v[120:123]
	v_mfma_f32_16x16x32_bf16 v[116:119], v[128:131], v[204:207], v[116:119]
	v_mfma_f32_16x16x32_bf16 v[108:111], v[136:139], v[204:207], v[108:111]
	v_mfma_f32_16x16x32_bf16 v[92:95], v[128:131], v[230:233], v[92:95]
	v_mfma_f32_16x16x32_bf16 v[88:91], v[136:139], v[230:233], v[88:91]
	v_mfma_f32_16x16x32_bf16 v[80:83], v[128:131], v[238:241], v[80:83]
	v_mfma_f32_16x16x32_bf16 v[72:75], v[136:139], v[238:241], v[72:75]
	v_mfma_f32_16x16x32_bf16 v[124:127], v[132:135], v[200:203], v[124:127]
	v_mfma_f32_16x16x32_bf16 v[120:123], v[152:155], v[200:203], v[120:123]
	v_mfma_f32_16x16x32_bf16 v[116:119], v[132:135], v[208:211], v[116:119]
	v_mfma_f32_16x16x32_bf16 v[108:111], v[152:155], v[208:211], v[108:111]
	v_mfma_f32_16x16x32_bf16 v[92:95], v[132:135], v[234:237], v[92:95]
	v_mfma_f32_16x16x32_bf16 v[88:91], v[152:155], v[234:237], v[88:91]
	v_mfma_f32_16x16x32_bf16 v[80:83], v[132:135], v[242:245], v[80:83]
	v_mfma_f32_16x16x32_bf16 v[72:75], v[152:155], v[242:245], v[72:75]
	v_mfma_f32_16x16x32_bf16 v[112:115], v[156:159], v[188:191], v[112:115]
	v_mfma_f32_16x16x32_bf16 v[104:107], v[164:167], v[188:191], v[104:107]
	v_mfma_f32_16x16x32_bf16 v[100:103], v[156:159], v[204:207], v[100:103]
	v_mfma_f32_16x16x32_bf16 v[96:99], v[164:167], v[204:207], v[96:99]
	v_mfma_f32_16x16x32_bf16 v[84:87], v[156:159], v[230:233], v[84:87]
	v_mfma_f32_16x16x32_bf16 v[76:79], v[164:167], v[230:233], v[76:79]
	v_mfma_f32_16x16x32_bf16 v[68:71], v[156:159], v[238:241], v[68:71]
	v_mfma_f32_16x16x32_bf16 v[64:67], v[164:167], v[238:241], v[64:67]
	v_mfma_f32_16x16x32_bf16 v[112:115], v[160:163], v[200:203], v[112:115]
	v_mfma_f32_16x16x32_bf16 v[104:107], v[184:187], v[200:203], v[104:107]
	v_mfma_f32_16x16x32_bf16 v[100:103], v[160:163], v[208:211], v[100:103]
	v_mfma_f32_16x16x32_bf16 v[96:99], v[184:187], v[208:211], v[96:99]
	v_mfma_f32_16x16x32_bf16 v[84:87], v[160:163], v[234:237], v[84:87]
	v_mfma_f32_16x16x32_bf16 v[76:79], v[184:187], v[234:237], v[76:79]
	v_mfma_f32_16x16x32_bf16 v[68:71], v[160:163], v[242:245], v[68:71]
	v_mfma_f32_16x16x32_bf16 v[64:67], v[184:187], v[242:245], v[64:67]
	s_barrier
; #define PG8_STAGE(bufoff, gbase, voff) do { _Pragma("unroll") for (int _i = 0; _i < 2; ++_i) \
;         __builtin_amdgcn_global_load_lds((const unsigned*)((const char*)(gbase) + (voff)[_i]), (LAS unsigned*)(lds + (bufoff) + ldsw + _i * 8192), 16, 0, 0); } while (0)
; #define PG8_LDA(dst, b, h) do { _Pragma("unroll") for (int m = 0; m < 4; ++m) _Pragma("unroll") for (int k = 0; k < 2; ++k) dst[m][k] = *(const LAS bf16x8*)(lds + PG8_SA(b, h) + aoff + m * 2048 + k * 1024); } while (0)
; #define PG8_LDB(dst, b, h) do { _Pragma("unroll") for (int n = 0; n < 2; ++n) _Pragma("unroll") for (int k = 0; k < 2; ++k) dst[n][k] = *(const LAS bf16x8*)(lds + PG8_SB(b, h) + boff + n * 2048 + k * 1024); } while (0)
; #define PG8_WAIT_V(n) asm volatile("s_waitcnt vmcnt(" #n ")" ::: "memory")
; #define PG8_WAIT_L(n) asm volatile("s_waitcnt lgkmcnt(" #n ")" ::: "memory")
; template <class Epi>
; __device__ __forceinline__ void gemm_phase(LAS unsigned char* lds, const Gemm g, const StaticOrder& S, const Epi& E, const int tid) {
;     ...
;         for (int t = 0; t < nt; t += 2) {
;             const bool last = (t == nt - 2);
;             const char* a1 = cA + (size_t)(t + 1) * kstep;
;             const char* a2 = last ? nA : cA + (size_t)(t + 2) * kstep; const char* b2 = last ? nB : cB + (size_t)(t + 2) * kstep;
;             const char* a3 = a2 + kstep; const char* b3 = b2 + kstep;
;             PG8_LDB(B0, 0, 0); PG8_LDB(B1, 0, 1); PG8_SCHED; PG8_LDA(At, 0, 0); PG8_STAGE(PG8_SA(1, 1), a1 + hsA, voffA);
;             PG8_WAIT_V(8); PG8_WAIT_L(0); PG8_BAR; PG8_MMA(0, 0, At, B0); PG8_MMA(0, 1, At, B1); PG8_BAR; PG8_SCHED;
;             PG8_LDA(At, 0, 1); PG8_STAGE(PG8_SB(0, 0), b2, voffB); PG8_STAGE(PG8_SB(0, 1), b2 + hsB, voffB); PG8_STAGE(PG8_SA(0, 0), a2, voffA);
;             PG8_WAIT_V(8); PG8_WAIT_L(0); PG8_BAR; PG8_MMA(1, 0, At, B0); PG8_MMA(1, 1, At, B1); PG8_BAR; PG8_SCHED;
;             PG8_LDB(B0, 1, 0); PG8_LDB(B1, 1, 1); PG8_SCHED; PG8_LDA(At, 1, 0); PG8_STAGE(PG8_SA(0, 1), a2 + hsA, voffA);
;             PG8_WAIT_V(8); PG8_WAIT_L(0); PG8_BAR; PG8_MMA(0, 0, At, B0); PG8_MMA(0, 1, At, B1); PG8_BAR; PG8_SCHED;
;             PG8_LDA(At, 1, 1); PG8_STAGE(PG8_SB(1, 0), b3, voffB); PG8_STAGE(PG8_SB(1, 1), b3 + hsB, voffB); PG8_STAGE(PG8_SA(1, 0), a3, voffA);
;             PG8_WAIT_V(8); PG8_WAIT_L(0); PG8_BAR; PG8_MMA(1, 0, At, B0); PG8_MMA(1, 1, At, B1); PG8_BAR; PG8_SCHED;
	s_add_i32 s18, s24, s39
	v_lshl_add_u64 v[170:171], v[212:213], 0, s[28:29]
	s_mov_b32 m0, s18
	ds_read_b128 v[188:191], v198 offset:49152
	ds_read_b128 v[200:203], v198 offset:50176
	ds_read_b128 v[204:207], v198 offset:51200
	ds_read_b128 v[208:211], v198 offset:52224
	ds_read_b128 v[230:233], v198 offset:53248
	ds_read_b128 v[234:237], v198 offset:54272
	ds_read_b128 v[238:241], v198 offset:55296
	ds_read_b128 v[242:245], v198 offset:56320
	global_load_lds_dwordx4 v[170:171], off
	s_add_i32 m0, s18, 0x2000
	s_add_u32 s18, s34, 0x160080
	v_lshl_add_u64 v[170:171], v[246:247], 0, s[28:29]
	s_addc_u32 s19, s35, 0
	s_add_i32 s24, s25, s39
	global_load_lds_dwordx4 v[170:171], off
	v_lshl_add_u64 v[170:171], s[18:19], 0, v[144:145]
	s_mov_b32 m0, s24
	s_nop 0
	global_load_lds_dwordx4 v[170:171], off
	v_lshl_add_u64 v[170:171], s[18:19], 0, v[140:141]
	s_add_i32 m0, s24, 0x2000
	s_nop 0
	global_load_lds_dwordx4 v[170:171], off
	v_lshl_add_u64 v[170:171], v[248:249], 0, s[28:29]
	s_mov_b32 m0, s56
	s_nop 0
	global_load_lds_dwordx4 v[170:171], off
	v_lshl_add_u64 v[170:171], v[250:251], 0, s[28:29]
	s_mov_b32 m0, s57
	s_nop 0
	global_load_lds_dwordx4 v[170:171], off
	s_waitcnt vmcnt(8)
	s_waitcnt lgkmcnt(0)
	s_barrier
	v_mfma_f32_16x16x32_bf16 v[60:63], v[128:131], v[188:191], v[60:63]
	s_add_i32 s69, s69, 2
	s_add_u32 s42, s42, 0x100
	s_addc_u32 s43, s43, 0
	s_mov_b64 s[18:19], s[0:1]
	v_mfma_f32_16x16x32_bf16 v[56:59], v[136:139], v[188:191], v[56:59]
	s_add_u32 s0, s18, 0x100
	s_addc_u32 s1, s19, 0
	s_add_i32 s24, 0, 0x10000
	s_cmpk_eq_i32 s69, 0x54
	v_mfma_f32_16x16x32_bf16 v[44:47], v[128:131], v[204:207], v[44:47]
	s_cselect_b32 s37, s15, s1
	s_cselect_b32 s36, s14, s0
	s_cselect_b32 s35, s17, s43
	s_cselect_b32 s34, s16, s42
	v_mfma_f32_16x16x32_bf16 v[40:43], v[136:139], v[204:207], v[40:43]
	s_add_i32 s25, 0, 0x14000
	s_cmpk_gt_u32 s69, 0x55
	v_mfma_f32_16x16x32_bf16 v[28:31], v[128:131], v[230:233], v[28:31]
	v_mfma_f32_16x16x32_bf16 v[24:27], v[136:139], v[230:233], v[24:27]
	v_mfma_f32_16x16x32_bf16 v[12:15], v[128:131], v[238:241], v[12:15]
	v_mfma_f32_16x16x32_bf16 v[8:11], v[136:139], v[238:241], v[8:11]
	v_mfma_f32_16x16x32_bf16 v[60:63], v[132:135], v[200:203], v[60:63]
	v_mfma_f32_16x16x32_bf16 v[56:59], v[152:155], v[200:203], v[56:59]
	v_mfma_f32_16x16x32_bf16 v[44:47], v[132:135], v[208:211], v[44:47]
	v_mfma_f32_16x16x32_bf16 v[40:43], v[152:155], v[208:211], v[40:43]
	v_mfma_f32_16x16x32_bf16 v[28:31], v[132:135], v[234:237], v[28:31]
	v_mfma_f32_16x16x32_bf16 v[24:27], v[152:155], v[234:237], v[24:27]
	v_mfma_f32_16x16x32_bf16 v[12:15], v[132:135], v[242:245], v[12:15]
	v_mfma_f32_16x16x32_bf16 v[8:11], v[152:155], v[242:245], v[8:11]
	v_mfma_f32_16x16x32_bf16 v[52:55], v[156:159], v[188:191], v[52:55]
	v_mfma_f32_16x16x32_bf16 v[48:51], v[164:167], v[188:191], v[48:51]
	v_mfma_f32_16x16x32_bf16 v[36:39], v[156:159], v[204:207], v[36:39]
	v_mfma_f32_16x16x32_bf16 v[32:35], v[164:167], v[204:207], v[32:35]
	v_mfma_f32_16x16x32_bf16 v[20:23], v[156:159], v[230:233], v[20:23]
	v_mfma_f32_16x16x32_bf16 v[16:19], v[164:167], v[230:233], v[16:19]
	v_mfma_f32_16x16x32_bf16 v[4:7], v[156:159], v[238:241], v[4:7]
	v_mfma_f32_16x16x32_bf16 v[0:3], v[164:167], v[238:241], v[0:3]
	v_mfma_f32_16x16x32_bf16 v[52:55], v[160:163], v[200:203], v[52:55]
	v_mfma_f32_16x16x32_bf16 v[48:51], v[184:187], v[200:203], v[48:51]
	v_mfma_f32_16x16x32_bf16 v[36:39], v[160:163], v[208:211], v[36:39]
	v_mfma_f32_16x16x32_bf16 v[32:35], v[184:187], v[208:211], v[32:35]
	v_mfma_f32_16x16x32_bf16 v[20:23], v[160:163], v[234:237], v[20:23]
	v_mfma_f32_16x16x32_bf16 v[16:19], v[184:187], v[234:237], v[16:19]
	v_mfma_f32_16x16x32_bf16 v[4:7], v[160:163], v[242:245], v[4:7]
	v_mfma_f32_16x16x32_bf16 v[0:3], v[184:187], v[242:245], v[0:3]
	s_barrier
	s_cbranch_scc0 .Lkrot_b
	s_and_b64 vcc, exec, s[10:11]
	s_cbranch_vccz .LBB0_236
	s_barrier

; #define PG8_STAGE(bufoff, gbase, voff) do { _Pragma("unroll") for (int _i = 0; _i < 2; ++_i) \
;         __builtin_amdgcn_global_load_lds((const unsigned*)((const char*)(gbase) + (voff)[_i]), (LAS unsigned*)(lds + (bufoff) + ldsw + _i * 8192), 16, 0, 0); } while (0)
; #define PG8_LDA(dst, b, h) do { _Pragma("unroll") for (int m = 0; m < 4; ++m) _Pragma("unroll") for (int k = 0; k < 2; ++k) dst[m][k] = *(const LAS bf16x8*)(lds + PG8_SA(b, h) + aoff + m * 2048 + k * 1024); } while (0)
; #define PG8_LDB(dst, b, h) do { _Pragma("unroll") for (int n = 0; n < 2; ++n) _Pragma("unroll") for (int k = 0; k < 2; ++k) dst[n][k] = *(const LAS bf16x8*)(lds + PG8_SB(b, h) + boff + n * 2048 + k * 1024); } while (0)
; #define PG8_MMA(ai, bj, At, Bt) do { __builtin_amdgcn_s_setprio(1); _Pragma("unroll") for (int m = 0; m < 4; ++m) _Pragma("unroll") for (int n = 0; n < 2; ++n) _Pragma("unroll") for (int k = 0; k < 2; ++k) \
;         acc[ai][bj][m][n] = __builtin_amdgcn_mfma_f32_16x16x32_bf16(Bt[n][k], At[m][k], acc[ai][bj][m][n], 0, 0, 0); __builtin_amdgcn_s_setprio(0); } while (0)
; #define PG8_WAIT_V(n) asm volatile("s_waitcnt vmcnt(" #n ")" ::: "memory")
; #define PG8_WAIT_L(n) asm volatile("s_waitcnt lgkmcnt(" #n ")" ::: "memory")
; #define PG8_BAR __builtin_amdgcn_s_barrier()
; #define PG8_SCHED __builtin_amdgcn_sched_barrier(0)
; template <class Epi>
; __device__ __forceinline__ void gemm_phase(LAS unsigned char* lds, const Gemm g, const StaticOrder& S, const Epi& E, const int tid) {
;     ...
;             const char* a1 = cA + (size_t)(t + 1) * kstep;
;             const char* a2 = last ? nA : cA + (size_t)(t + 2) * kstep; const char* b2 = last ? nB : cB + (size_t)(t + 2) * kstep;
;             const char* a3 = a2 + kstep; const char* b3 = b2 + kstep;
;             PG8_LDB(B0, 0, 0); PG8_LDB(B1, 0, 1); PG8_SCHED; PG8_LDA(At, 0, 0); PG8_STAGE(PG8_SA(1, 1), a1 + hsA, voffA);
;             PG8_WAIT_V(8); PG8_WAIT_L(0); PG8_BAR; PG8_MMA(0, 0, At, B0); PG8_MMA(0, 1, At, B1); PG8_BAR; PG8_SCHED;
;             PG8_LDA(At, 0, 1); PG8_STAGE(PG8_SB(0, 0), b2, voffB); PG8_STAGE(PG8_SB(0, 1), b2 + hsB, voffB); PG8_STAGE(PG8_SA(0, 0), a2, voffA);
;             PG8_WAIT_V(8); PG8_WAIT_L(0); PG8_BAR; PG8_MMA(1, 0, At, B0); PG8_MMA(1, 1, At, B1); PG8_BAR; PG8_SCHED;
.Lgprio_c:
.LBB0_354:
	s_add_u32 s0, s36, 0xfff80080
	s_addc_u32 s1, s37, -1
	s_add_i32 s24, 0, 0x10000
	s_cmp_eq_u32 vcc_hi, 28
	s_cselect_b32 s43, s10, s1
	s_cselect_b32 s42, s11, s0
	s_cselect_b32 s1, s47, vcc_lo
	s_cselect_b32 s0, s49, s69
	s_add_i32 s55, 0, 0x14000
.Lkrot_c:
	v_add_u32_e32 v143, s24, v163
	ds_read_b128 v[144:147], v143
	ds_read_b128 v[148:151], v143 offset:1024
	ds_read_b128 v[152:155], v143 offset:2048
	ds_read_b128 v[156:159], v143 offset:3072
	v_add_u32_e32 v143, s55, v163
	ds_read_b128 v[184:187], v143
	ds_read_b128 v[188:191], v143 offset:1024
	ds_read_b128 v[192:195], v143 offset:2048
	ds_read_b128 v[196:199], v143 offset:3072
	v_lshl_add_u64 v[160:161], s[36:37], 0, v[138:139]
	s_add_i32 m0, s58, 0xc000
	ds_read_b128 v[200:203], v165
	ds_read_b128 v[204:207], v165 offset:1024
	ds_read_b128 v[208:211], v165 offset:2048
	ds_read_b128 v[232:235], v165 offset:3072
	ds_read_b128 v[236:239], v165 offset:4096
	ds_read_b128 v[240:243], v165 offset:5120
	ds_read_b128 v[244:247], v165 offset:6144
	ds_read_b128 v[248:251], v165 offset:7168
	global_load_lds_dwordx4 v[160:161], off
	v_lshl_add_u64 v[160:161], s[36:37], 0, v[140:141]
	s_add_i32 m0, s58, 0xe000
	s_nop 0
	global_load_lds_dwordx4 v[160:161], off
	s_waitcnt vmcnt(8)
	s_waitcnt lgkmcnt(0)
	s_barrier
	v_mfma_f32_16x16x32_bf16 v[124:127], v[144:147], v[200:203], v[124:127]
	v_mfma_f32_16x16x32_bf16 v[120:123], v[152:155], v[200:203], v[120:123]
	v_mfma_f32_16x16x32_bf16 v[108:111], v[144:147], v[208:211], v[108:111]
	v_mfma_f32_16x16x32_bf16 v[104:107], v[152:155], v[208:211], v[104:107]
	v_mfma_f32_16x16x32_bf16 v[92:95], v[144:147], v[236:239], v[92:95]
	v_mfma_f32_16x16x32_bf16 v[88:91], v[152:155], v[236:239], v[88:91]
	v_mfma_f32_16x16x32_bf16 v[76:79], v[144:147], v[244:247], v[76:79]
	v_mfma_f32_16x16x32_bf16 v[72:75], v[152:155], v[244:247], v[72:75]
	v_mfma_f32_16x16x32_bf16 v[124:127], v[148:151], v[204:207], v[124:127]
	v_mfma_f32_16x16x32_bf16 v[120:123], v[156:159], v[204:207], v[120:123]
	v_mfma_f32_16x16x32_bf16 v[108:111], v[148:151], v[232:235], v[108:111]
	v_mfma_f32_16x16x32_bf16 v[104:107], v[156:159], v[232:235], v[104:107]
	v_mfma_f32_16x16x32_bf16 v[92:95], v[148:151], v[240:243], v[92:95]
	v_mfma_f32_16x16x32_bf16 v[88:91], v[156:159], v[240:243], v[88:91]
	v_mfma_f32_16x16x32_bf16 v[76:79], v[148:151], v[248:251], v[76:79]
	v_mfma_f32_16x16x32_bf16 v[72:75], v[156:159], v[248:251], v[72:75]
	v_mfma_f32_16x16x32_bf16 v[116:119], v[184:187], v[200:203], v[116:119]
	v_mfma_f32_16x16x32_bf16 v[112:115], v[192:195], v[200:203], v[112:115]
	v_mfma_f32_16x16x32_bf16 v[100:103], v[184:187], v[208:211], v[100:103]
	v_mfma_f32_16x16x32_bf16 v[96:99], v[192:195], v[208:211], v[96:99]
	v_mfma_f32_16x16x32_bf16 v[84:87], v[184:187], v[236:239], v[84:87]
	v_mfma_f32_16x16x32_bf16 v[80:83], v[192:195], v[236:239], v[80:83]
	v_mfma_f32_16x16x32_bf16 v[68:71], v[184:187], v[244:247], v[68:71]
	v_mfma_f32_16x16x32_bf16 v[64:67], v[192:195], v[244:247], v[64:67]
	v_mfma_f32_16x16x32_bf16 v[116:119], v[188:191], v[204:207], v[116:119]
	v_mfma_f32_16x16x32_bf16 v[112:115], v[196:199], v[204:207], v[112:115]
	v_mfma_f32_16x16x32_bf16 v[100:103], v[188:191], v[232:235], v[100:103]
	v_mfma_f32_16x16x32_bf16 v[96:99], v[196:199], v[232:235], v[96:99]
	v_mfma_f32_16x16x32_bf16 v[84:87], v[188:191], v[240:243], v[84:87]
	v_mfma_f32_16x16x32_bf16 v[80:83], v[196:199], v[240:243], v[80:83]
	v_mfma_f32_16x16x32_bf16 v[68:71], v[188:191], v[248:251], v[68:71]
	v_mfma_f32_16x16x32_bf16 v[64:67], v[196:199], v[248:251], v[64:67]
	s_barrier
	s_add_i32 s24, s24, s57
	v_lshl_add_u64 v[160:161], s[0:1], 0, v[132:133]
	s_mov_b32 m0, s24
	ds_read_b128 v[200:203], v165 offset:16384
	ds_read_b128 v[204:207], v165 offset:17408
	ds_read_b128 v[208:211], v165 offset:18432
	ds_read_b128 v[232:235], v165 offset:19456
	ds_read_b128 v[236:239], v165 offset:20480
	ds_read_b128 v[240:243], v165 offset:21504
	ds_read_b128 v[244:247], v165 offset:22528
	ds_read_b128 v[248:251], v165 offset:23552
	global_load_lds_dwordx4 v[160:161], off
	s_add_i32 m0, s24, 0x2000
	s_add_u32 s24, s0, 0x80000
	v_lshl_add_u64 v[166:167], s[0:1], 0, v[128:129]
	s_addc_u32 s25, s1, 0
	s_add_i32 s55, s55, s57
	global_load_lds_dwordx4 v[166:167], off
	v_lshl_add_u64 v[170:171], s[24:25], 0, v[132:133]
	s_mov_b32 m0, s55
	v_lshl_add_u64 v[212:213], s[42:43], 0, v[130:131]
	global_load_lds_dwordx4 v[170:171], off
	v_lshl_add_u64 v[170:171], s[24:25], 0, v[128:129]
	s_add_i32 m0, s55, 0x2000
	s_nop 0
	global_load_lds_dwordx4 v[170:171], off
	v_lshl_add_u64 v[170:171], s[42:43], 0, v[134:135]
	s_mov_b32 m0, s58
	s_nop 0
	global_load_lds_dwordx4 v[170:171], off
	s_mov_b32 m0, s59
	s_nop 0
	global_load_lds_dwordx4 v[212:213], off
	s_waitcnt vmcnt(8)
	s_waitcnt lgkmcnt(0)
	s_barrier
; #define PG8_STAGE(bufoff, gbase, voff) do { _Pragma("unroll") for (int _i = 0; _i < 2; ++_i) \
;         __builtin_amdgcn_global_load_lds((const unsigned*)((const char*)(gbase) + (voff)[_i]), (LAS unsigned*)(lds + (bufoff) + ldsw + _i * 8192), 16, 0, 0); } while (0)
; #define PG8_LDA(dst, b, h) do { _Pragma("unroll") for (int m = 0; m < 4; ++m) _Pragma("unroll") for (int k = 0; k < 2; ++k) dst[m][k] = *(const LAS bf16x8*)(lds + PG8_SA(b, h) + aoff + m * 2048 + k * 1024); } while (0)
; #define PG8_LDB(dst, b, h) do { _Pragma("unroll") for (int n = 0; n < 2; ++n) _Pragma("unroll") for (int k = 0; k < 2; ++k) dst[n][k] = *(const LAS bf16x8*)(lds + PG8_SB(b, h) + boff + n * 2048 + k * 1024); } while (0)
; #define PG8_MMA(ai, bj, At, Bt) do { __builtin_amdgcn_s_setprio(1); _Pragma("unroll") for (int m = 0; m < 4; ++m) _Pragma("unroll") for (int n = 0; n < 2; ++n) _Pragma("unroll") for (int k = 0; k < 2; ++k) \
;         acc[ai][bj][m][n] = __builtin_amdgcn_mfma_f32_16x16x32_bf16(Bt[n][k], At[m][k], acc[ai][bj][m][n], 0, 0, 0); __builtin_amdgcn_s_setprio(0); } while (0)
; #define PG8_WAIT_V(n) asm volatile("s_waitcnt vmcnt(" #n ")" ::: "memory")
; #define PG8_WAIT_L(n) asm volatile("s_waitcnt lgkmcnt(" #n ")" ::: "memory")
; #define PG8_BAR __builtin_amdgcn_s_barrier()
; #define PG8_SCHED __builtin_amdgcn_sched_barrier(0)
; template <class Epi>
; __device__ __forceinline__ void gemm_phase(LAS unsigned char* lds, const Gemm g, const StaticOrder& S, const Epi& E, const int tid) {
;     ...
;             PG8_WAIT_V(8); PG8_WAIT_L(0); PG8_BAR; PG8_MMA(1, 0, At, B0); PG8_MMA(1, 1, At, B1); PG8_BAR; PG8_SCHED;
;             PG8_LDB(B0, 1, 0); PG8_LDB(B1, 1, 1); PG8_SCHED; PG8_LDA(At, 1, 0); PG8_STAGE(PG8_SA(0, 1), a2 + hsA, voffA);
;             PG8_WAIT_V(8); PG8_WAIT_L(0); PG8_BAR; PG8_MMA(0, 0, At, B0); PG8_MMA(0, 1, At, B1); PG8_BAR; PG8_SCHED;
	v_mfma_f32_16x16x32_bf16 v[60:63], v[144:147], v[200:203], v[60:63]
	v_mfma_f32_16x16x32_bf16 v[56:59], v[152:155], v[200:203], v[56:59]
	v_mfma_f32_16x16x32_bf16 v[44:47], v[144:147], v[208:211], v[44:47]
	v_mfma_f32_16x16x32_bf16 v[40:43], v[152:155], v[208:211], v[40:43]
	v_mfma_f32_16x16x32_bf16 v[28:31], v[144:147], v[236:239], v[28:31]
	v_mfma_f32_16x16x32_bf16 v[24:27], v[152:155], v[236:239], v[24:27]
	v_mfma_f32_16x16x32_bf16 v[12:15], v[144:147], v[244:247], v[12:15]
	v_mfma_f32_16x16x32_bf16 v[8:11], v[152:155], v[244:247], v[8:11]
	v_mfma_f32_16x16x32_bf16 v[60:63], v[148:151], v[204:207], v[60:63]
	v_mfma_f32_16x16x32_bf16 v[56:59], v[156:159], v[204:207], v[56:59]
	v_mfma_f32_16x16x32_bf16 v[44:47], v[148:151], v[232:235], v[44:47]
	v_mfma_f32_16x16x32_bf16 v[40:43], v[156:159], v[232:235], v[40:43]
	v_mfma_f32_16x16x32_bf16 v[28:31], v[148:151], v[240:243], v[28:31]
	v_mfma_f32_16x16x32_bf16 v[24:27], v[156:159], v[240:243], v[24:27]
	v_mfma_f32_16x16x32_bf16 v[12:15], v[148:151], v[248:251], v[12:15]
	v_mfma_f32_16x16x32_bf16 v[8:11], v[156:159], v[248:251], v[8:11]
	v_mfma_f32_16x16x32_bf16 v[52:55], v[184:187], v[200:203], v[52:55]
	v_mfma_f32_16x16x32_bf16 v[48:51], v[192:195], v[200:203], v[48:51]
	v_mfma_f32_16x16x32_bf16 v[36:39], v[184:187], v[208:211], v[36:39]
	v_mfma_f32_16x16x32_bf16 v[32:35], v[192:195], v[208:211], v[32:35]
	v_mfma_f32_16x16x32_bf16 v[20:23], v[184:187], v[236:239], v[20:23]
	v_mfma_f32_16x16x32_bf16 v[16:19], v[192:195], v[236:239], v[16:19]
	v_mfma_f32_16x16x32_bf16 v[4:7], v[184:187], v[244:247], v[4:7]
	v_mfma_f32_16x16x32_bf16 v[0:3], v[192:195], v[244:247], v[0:3]
	v_mfma_f32_16x16x32_bf16 v[52:55], v[188:191], v[204:207], v[52:55]
	v_mfma_f32_16x16x32_bf16 v[48:51], v[196:199], v[204:207], v[48:51]
	v_mfma_f32_16x16x32_bf16 v[36:39], v[188:191], v[232:235], v[36:39]
	v_mfma_f32_16x16x32_bf16 v[32:35], v[196:199], v[232:235], v[32:35]
	v_mfma_f32_16x16x32_bf16 v[20:23], v[188:191], v[240:243], v[20:23]
	v_mfma_f32_16x16x32_bf16 v[16:19], v[196:199], v[240:243], v[16:19]
	v_mfma_f32_16x16x32_bf16 v[4:7], v[188:191], v[248:251], v[4:7]
	v_mfma_f32_16x16x32_bf16 v[0:3], v[196:199], v[248:251], v[0:3]
	s_barrier
	s_add_i32 s55, 0, 0x18000
	v_add_u32_e32 v143, s55, v163
	s_add_i32 s67, 0, 0x1c000
	ds_read_b128 v[144:147], v143
	ds_read_b128 v[148:151], v143 offset:1024
	ds_read_b128 v[152:155], v143 offset:2048
	ds_read_b128 v[156:159], v143 offset:3072
	v_add_u32_e32 v143, s67, v163
	ds_read_b128 v[184:187], v143
	ds_read_b128 v[188:191], v143 offset:1024
	ds_read_b128 v[192:195], v143 offset:2048
	ds_read_b128 v[196:199], v143 offset:3072
	s_add_u32 s24, s42, 0x80000
	s_addc_u32 s25, s43, 0
	s_mov_b32 m0, s27
	v_lshl_add_u64 v[172:173], s[24:25], 0, v[134:135]
	ds_read_b128 v[200:203], v165 offset:32768
	ds_read_b128 v[204:207], v165 offset:33792
	ds_read_b128 v[208:211], v165 offset:34816
	ds_read_b128 v[232:235], v165 offset:35840
	ds_read_b128 v[236:239], v165 offset:36864
	ds_read_b128 v[240:243], v165 offset:37888
	ds_read_b128 v[244:247], v165 offset:38912
	ds_read_b128 v[248:251], v165 offset:39936
	global_load_lds_dwordx4 v[172:173], off
	v_lshl_add_u64 v[172:173], s[24:25], 0, v[130:131]
	s_mov_b32 m0, s96
	s_nop 0
	global_load_lds_dwordx4 v[172:173], off
	s_waitcnt vmcnt(8)
	s_waitcnt lgkmcnt(0)
	s_barrier
	v_mfma_f32_16x16x32_bf16 v[124:127], v[144:147], v[200:203], v[124:127]
	v_mfma_f32_16x16x32_bf16 v[120:123], v[152:155], v[200:203], v[120:123]
	v_mfma_f32_16x16x32_bf16 v[108:111], v[144:147], v[208:211], v[108:111]
	v_mfma_f32_16x16x32_bf16 v[104:107], v[152:155], v[208:211], v[104:107]
	v_mfma_f32_16x16x32_bf16 v[92:95], v[144:147], v[236:239], v[92:95]
	v_mfma_f32_16x16x32_bf16 v[88:91], v[152:155], v[236:239], v[88:91]
	v_mfma_f32_16x16x32_bf16 v[76:79], v[144:147], v[244:247], v[76:79]
	v_mfma_f32_16x16x32_bf16 v[72:75], v[152:155], v[244:247], v[72:75]
	v_mfma_f32_16x16x32_bf16 v[124:127], v[148:151], v[204:207], v[124:127]
	v_mfma_f32_16x16x32_bf16 v[120:123], v[156:159], v[204:207], v[120:123]
	v_mfma_f32_16x16x32_bf16 v[108:111], v[148:151], v[232:235], v[108:111]
	v_mfma_f32_16x16x32_bf16 v[104:107], v[156:159], v[232:235], v[104:107]
	v_mfma_f32_16x16x32_bf16 v[92:95], v[148:151], v[240:243], v[92:95]
	v_mfma_f32_16x16x32_bf16 v[88:91], v[156:159], v[240:243], v[88:91]
	v_mfma_f32_16x16x32_bf16 v[76:79], v[148:151], v[248:251], v[76:79]
	v_mfma_f32_16x16x32_bf16 v[72:75], v[156:159], v[248:251], v[72:75]
	v_mfma_f32_16x16x32_bf16 v[116:119], v[184:187], v[200:203], v[116:119]
	v_mfma_f32_16x16x32_bf16 v[112:115], v[192:195], v[200:203], v[112:115]
	v_mfma_f32_16x16x32_bf16 v[100:103], v[184:187], v[208:211], v[100:103]
	v_mfma_f32_16x16x32_bf16 v[96:99], v[192:195], v[208:211], v[96:99]
	v_mfma_f32_16x16x32_bf16 v[84:87], v[184:187], v[236:239], v[84:87]
	v_mfma_f32_16x16x32_bf16 v[80:83], v[192:195], v[236:239], v[80:83]
	v_mfma_f32_16x16x32_bf16 v[68:71], v[184:187], v[244:247], v[68:71]
	v_mfma_f32_16x16x32_bf16 v[64:67], v[192:195], v[244:247], v[64:67]
	v_mfma_f32_16x16x32_bf16 v[116:119], v[188:191], v[204:207], v[116:119]
	v_mfma_f32_16x16x32_bf16 v[112:115], v[196:199], v[204:207], v[112:115]
	v_mfma_f32_16x16x32_bf16 v[100:103], v[188:191], v[232:235], v[100:103]
	v_mfma_f32_16x16x32_bf16 v[96:99], v[196:199], v[232:235], v[96:99]
	v_mfma_f32_16x16x32_bf16 v[84:87], v[188:191], v[240:243], v[84:87]
	v_mfma_f32_16x16x32_bf16 v[80:83], v[196:199], v[240:243], v[80:83]
	v_mfma_f32_16x16x32_bf16 v[68:71], v[188:191], v[248:251], v[68:71]
	v_mfma_f32_16x16x32_bf16 v[64:67], v[196:199], v[248:251], v[64:67]
	s_barrier
; #define PG8_STAGE(bufoff, gbase, voff) do { _Pragma("unroll") for (int _i = 0; _i < 2; ++_i) \
;         __builtin_amdgcn_global_load_lds((const unsigned*)((const char*)(gbase) + (voff)[_i]), (LAS unsigned*)(lds + (bufoff) + ldsw + _i * 8192), 16, 0, 0); } while (0)
; #define PG8_LDA(dst, b, h) do { _Pragma("unroll") for (int m = 0; m < 4; ++m) _Pragma("unroll") for (int k = 0; k < 2; ++k) dst[m][k] = *(const LAS bf16x8*)(lds + PG8_SA(b, h) + aoff + m * 2048 + k * 1024); } while (0)
; #define PG8_LDB(dst, b, h) do { _Pragma("unroll") for (int n = 0; n < 2; ++n) _Pragma("unroll") for (int k = 0; k < 2; ++k) dst[n][k] = *(const LAS bf16x8*)(lds + PG8_SB(b, h) + boff + n * 2048 + k * 1024); } while (0)
; #define PG8_WAIT_V(n) asm volatile("s_waitcnt vmcnt(" #n ")" ::: "memory")
; #define PG8_WAIT_L(n) asm volatile("s_waitcnt lgkmcnt(" #n ")" ::: "memory")
; template <class Epi>
; __device__ __forceinline__ void gemm_phase(LAS unsigned char* lds, const Gemm g, const StaticOrder& S, const Epi& E, const int tid) {
;     ...
;         for (int t = 0; t < nt; t += 2) {
;             const bool last = (t == nt - 2);
;             const char* a1 = cA + (size_t)(t + 1) * kstep;
;             const char* a2 = last ? nA : cA + (size_t)(t + 2) * kstep; const char* b2 = last ? nB : cB + (size_t)(t + 2) * kstep;
;             const char* a3 = a2 + kstep; const char* b3 = b2 + kstep;
;             PG8_LDB(B0, 0, 0); PG8_LDB(B1, 0, 1); PG8_SCHED; PG8_LDA(At, 0, 0); PG8_STAGE(PG8_SA(1, 1), a1 + hsA, voffA);
;             PG8_WAIT_V(8); PG8_WAIT_L(0); PG8_BAR; PG8_MMA(0, 0, At, B0); PG8_MMA(0, 1, At, B1); PG8_BAR; PG8_SCHED;
;             PG8_LDA(At, 0, 1); PG8_STAGE(PG8_SB(0, 0), b2, voffB); PG8_STAGE(PG8_SB(0, 1), b2 + hsB, voffB); PG8_STAGE(PG8_SA(0, 0), a2, voffA);
;             PG8_WAIT_V(8); PG8_WAIT_L(0); PG8_BAR; PG8_MMA(1, 0, At, B0); PG8_MMA(1, 1, At, B1); PG8_BAR; PG8_SCHED;
;             PG8_LDB(B0, 1, 0); PG8_LDB(B1, 1, 1); PG8_SCHED; PG8_LDA(At, 1, 0); PG8_STAGE(PG8_SA(0, 1), a2 + hsA, voffA);
;             PG8_WAIT_V(8); PG8_WAIT_L(0); PG8_BAR; PG8_MMA(0, 0, At, B0); PG8_MMA(0, 1, At, B1); PG8_BAR; PG8_SCHED;
;             PG8_LDA(At, 1, 1); PG8_STAGE(PG8_SB(1, 0), b3, voffB); PG8_STAGE(PG8_SB(1, 1), b3 + hsB, voffB); PG8_STAGE(PG8_SA(1, 0), a3, voffA);
;             PG8_WAIT_V(8); PG8_WAIT_L(0); PG8_BAR; PG8_MMA(1, 0, At, B0); PG8_MMA(1, 1, At, B1); PG8_BAR; PG8_SCHED;
	s_add_i32 s24, s55, s57
	v_lshl_add_u64 v[160:161], v[160:161], 0, s[28:29]
	s_mov_b32 m0, s24
	ds_read_b128 v[200:203], v165 offset:49152
	ds_read_b128 v[204:207], v165 offset:50176
	ds_read_b128 v[208:211], v165 offset:51200
	ds_read_b128 v[232:235], v165 offset:52224
	ds_read_b128 v[236:239], v165 offset:53248
	ds_read_b128 v[240:243], v165 offset:54272
	ds_read_b128 v[244:247], v165 offset:55296
	ds_read_b128 v[248:251], v165 offset:56320
	global_load_lds_dwordx4 v[160:161], off
	s_add_i32 m0, s24, 0x2000
	s_add_u32 s0, s0, 0x80080
	v_lshl_add_u64 v[160:161], v[166:167], 0, s[28:29]
	s_addc_u32 s1, s1, 0
	s_add_i32 s24, s67, s57
	global_load_lds_dwordx4 v[160:161], off
	v_lshl_add_u64 v[160:161], s[0:1], 0, v[132:133]
	s_mov_b32 m0, s24
	s_nop 0
	global_load_lds_dwordx4 v[160:161], off
	v_lshl_add_u64 v[160:161], s[0:1], 0, v[128:129]
	s_add_i32 m0, s24, 0x2000
	s_nop 0
	global_load_lds_dwordx4 v[160:161], off
	v_lshl_add_u64 v[160:161], v[170:171], 0, s[28:29]
	s_mov_b32 m0, s6
	s_nop 0
	global_load_lds_dwordx4 v[160:161], off
	v_lshl_add_u64 v[160:161], v[212:213], 0, s[28:29]
	s_mov_b32 m0, s7
	s_nop 0
	global_load_lds_dwordx4 v[160:161], off
	s_waitcnt vmcnt(8)
	s_waitcnt lgkmcnt(0)
	s_barrier
	v_mfma_f32_16x16x32_bf16 v[60:63], v[144:147], v[200:203], v[60:63]
	s_add_i32 vcc_hi, vcc_hi, 2
	s_add_u32 s36, s36, 0x100
	s_addc_u32 s37, s37, 0
	s_add_u32 s69, s69, 0x100
	v_mfma_f32_16x16x32_bf16 v[56:59], v[152:155], v[200:203], v[56:59]
	s_addc_u32 vcc_lo, vcc_lo, 0
	s_add_u32 s0, s36, 0xfff80080
	s_addc_u32 s1, s37, -1
	s_add_i32 s24, 0, 0x10000
	v_mfma_f32_16x16x32_bf16 v[44:47], v[144:147], v[208:211], v[44:47]
	s_cmp_eq_u32 vcc_hi, 28
	s_cselect_b32 s43, s10, s1
	s_cselect_b32 s42, s11, s0
	s_cselect_b32 s1, s47, vcc_lo
	v_mfma_f32_16x16x32_bf16 v[40:43], v[152:155], v[208:211], v[40:43]
	s_cselect_b32 s0, s49, s69
	s_add_i32 s55, 0, 0x14000
	s_cmp_gt_u32 vcc_hi, 29
	v_mfma_f32_16x16x32_bf16 v[28:31], v[144:147], v[236:239], v[28:31]
	v_mfma_f32_16x16x32_bf16 v[24:27], v[152:155], v[236:239], v[24:27]
	v_mfma_f32_16x16x32_bf16 v[12:15], v[144:147], v[244:247], v[12:15]
	v_mfma_f32_16x16x32_bf16 v[8:11], v[152:155], v[244:247], v[8:11]
	v_mfma_f32_16x16x32_bf16 v[60:63], v[148:151], v[204:207], v[60:63]
	v_mfma_f32_16x16x32_bf16 v[56:59], v[156:159], v[204:207], v[56:59]
	v_mfma_f32_16x16x32_bf16 v[44:47], v[148:151], v[232:235], v[44:47]
	v_mfma_f32_16x16x32_bf16 v[40:43], v[156:159], v[232:235], v[40:43]
	v_mfma_f32_16x16x32_bf16 v[28:31], v[148:151], v[240:243], v[28:31]
	v_mfma_f32_16x16x32_bf16 v[24:27], v[156:159], v[240:243], v[24:27]
	v_mfma_f32_16x16x32_bf16 v[12:15], v[148:151], v[248:251], v[12:15]
	v_mfma_f32_16x16x32_bf16 v[8:11], v[156:159], v[248:251], v[8:11]
	v_mfma_f32_16x16x32_bf16 v[52:55], v[184:187], v[200:203], v[52:55]
	v_mfma_f32_16x16x32_bf16 v[48:51], v[192:195], v[200:203], v[48:51]
	v_mfma_f32_16x16x32_bf16 v[36:39], v[184:187], v[208:211], v[36:39]
	v_mfma_f32_16x16x32_bf16 v[32:35], v[192:195], v[208:211], v[32:35]
	v_mfma_f32_16x16x32_bf16 v[20:23], v[184:187], v[236:239], v[20:23]
	v_mfma_f32_16x16x32_bf16 v[16:19], v[192:195], v[236:239], v[16:19]
	v_mfma_f32_16x16x32_bf16 v[4:7], v[184:187], v[244:247], v[4:7]
	v_mfma_f32_16x16x32_bf16 v[0:3], v[192:195], v[244:247], v[0:3]
	v_mfma_f32_16x16x32_bf16 v[52:55], v[188:191], v[204:207], v[52:55]
	v_mfma_f32_16x16x32_bf16 v[48:51], v[196:199], v[204:207], v[48:51]
	v_mfma_f32_16x16x32_bf16 v[36:39], v[188:191], v[232:235], v[36:39]
	v_mfma_f32_16x16x32_bf16 v[32:35], v[196:199], v[232:235], v[32:35]
	v_mfma_f32_16x16x32_bf16 v[20:23], v[188:191], v[240:243], v[20:23]
	v_mfma_f32_16x16x32_bf16 v[16:19], v[196:199], v[240:243], v[16:19]
	v_mfma_f32_16x16x32_bf16 v[4:7], v[188:191], v[248:251], v[4:7]
	v_mfma_f32_16x16x32_bf16 v[0:3], v[196:199], v[248:251], v[0:3]
	s_barrier
	s_cbranch_scc0 .Lkrot_c
	s_and_b64 vcc, exec, s[34:35]
	s_cbranch_vccz .LBB0_357
	s_barrier

; #define PG8_STAGE(bufoff, gbase, voff) do { _Pragma("unroll") for (int _i = 0; _i < 2; ++_i) \
;         __builtin_amdgcn_global_load_lds((const unsigned*)((const char*)(gbase) + (voff)[_i]), (LAS unsigned*)(lds + (bufoff) + ldsw + _i * 8192), 16, 0, 0); } while (0)
; #define PG8_LDA(dst, b, h) do { _Pragma("unroll") for (int m = 0; m < 4; ++m) _Pragma("unroll") for (int k = 0; k < 2; ++k) dst[m][k] = *(const LAS bf16x8*)(lds + PG8_SA(b, h) + aoff + m * 2048 + k * 1024); } while (0)
; #define PG8_LDB(dst, b, h) do { _Pragma("unroll") for (int n = 0; n < 2; ++n) _Pragma("unroll") for (int k = 0; k < 2; ++k) dst[n][k] = *(const LAS bf16x8*)(lds + PG8_SB(b, h) + boff + n * 2048 + k * 1024); } while (0)
; #define PG8_MMA(ai, bj, At, Bt) do { __builtin_amdgcn_s_setprio(1); _Pragma("unroll") for (int m = 0; m < 4; ++m) _Pragma("unroll") for (int n = 0; n < 2; ++n) _Pragma("unroll") for (int k = 0; k < 2; ++k) \
;         acc[ai][bj][m][n] = __builtin_amdgcn_mfma_f32_16x16x32_bf16(Bt[n][k], At[m][k], acc[ai][bj][m][n], 0, 0, 0); __builtin_amdgcn_s_setprio(0); } while (0)
; #define PG8_WAIT_V(n) asm volatile("s_waitcnt vmcnt(" #n ")" ::: "memory")
; #define PG8_WAIT_L(n) asm volatile("s_waitcnt lgkmcnt(" #n ")" ::: "memory")
; #define PG8_BAR __builtin_amdgcn_s_barrier()
; #define PG8_SCHED __builtin_amdgcn_sched_barrier(0)
; template <class Epi>
; __device__ __forceinline__ void gemm_phase(LAS unsigned char* lds, const Gemm g, const StaticOrder& S, const Epi& E, const int tid) {
;     ...
;             PG8_LDB(B0, 0, 0); PG8_LDB(B1, 0, 1); PG8_SCHED; PG8_LDA(At, 0, 0); PG8_STAGE(PG8_SA(1, 1), a1 + hsA, voffA);
;             PG8_WAIT_V(8); PG8_WAIT_L(0); PG8_BAR; PG8_MMA(0, 0, At, B0); PG8_MMA(0, 1, At, B1); PG8_BAR; PG8_SCHED;
;             PG8_LDA(At, 0, 1); PG8_STAGE(PG8_SB(0, 0), b2, voffB); PG8_STAGE(PG8_SB(0, 1), b2 + hsB, voffB); PG8_STAGE(PG8_SA(0, 0), a2, voffA);
;             PG8_WAIT_V(8); PG8_WAIT_L(0); PG8_BAR; PG8_MMA(1, 0, At, B0); PG8_MMA(1, 1, At, B1); PG8_BAR; PG8_SCHED;
.Lkrot_d:
	v_add_u32_e32 v150, s24, v232
	v_add_u32_e32 v166, s55, v232
	ds_read_b128 v[138:141], v150
	ds_read_b128 v[142:145], v150 offset:1024
	ds_read_b128 v[146:149], v150 offset:2048
	ds_read_b128 v[150:153], v150 offset:3072
	ds_read_b128 v[154:157], v166
	ds_read_b128 v[158:161], v166 offset:1024
	ds_read_b128 v[162:165], v166 offset:2048
	ds_read_b128 v[184:187], v166 offset:3072
	v_lshl_add_u64 v[166:167], s[36:37], 0, v[134:135]
	s_add_i32 m0, s7, 0xc000
	ds_read_b128 v[188:191], v234
	ds_read_b128 v[192:195], v234 offset:1024
	ds_read_b128 v[196:199], v234 offset:2048
	ds_read_b128 v[200:203], v234 offset:3072
	ds_read_b128 v[204:207], v234 offset:4096
	ds_read_b128 v[208:211], v234 offset:5120
	ds_read_b128 v[236:239], v234 offset:6144
	ds_read_b128 v[240:243], v234 offset:7168
	global_load_lds_dwordx4 v[166:167], off
	v_lshl_add_u64 v[166:167], s[36:37], 0, v[136:137]
	s_add_i32 m0, s7, 0xe000
	s_nop 0
	global_load_lds_dwordx4 v[166:167], off
	s_waitcnt vmcnt(8)
	s_waitcnt lgkmcnt(0)
	s_barrier
	v_mfma_f32_16x16x32_bf16 v[124:127], v[138:141], v[188:191], v[124:127]
	v_mfma_f32_16x16x32_bf16 v[120:123], v[146:149], v[188:191], v[120:123]
	v_mfma_f32_16x16x32_bf16 v[116:119], v[138:141], v[196:199], v[116:119]
	v_mfma_f32_16x16x32_bf16 v[112:115], v[146:149], v[196:199], v[112:115]
	v_mfma_f32_16x16x32_bf16 v[108:111], v[138:141], v[204:207], v[108:111]
	v_mfma_f32_16x16x32_bf16 v[104:107], v[146:149], v[204:207], v[104:107]
	v_mfma_f32_16x16x32_bf16 v[100:103], v[138:141], v[236:239], v[100:103]
	v_mfma_f32_16x16x32_bf16 v[96:99], v[146:149], v[236:239], v[96:99]
	v_mfma_f32_16x16x32_bf16 v[124:127], v[142:145], v[192:195], v[124:127]
	v_mfma_f32_16x16x32_bf16 v[120:123], v[150:153], v[192:195], v[120:123]
	v_mfma_f32_16x16x32_bf16 v[116:119], v[142:145], v[200:203], v[116:119]
	v_mfma_f32_16x16x32_bf16 v[112:115], v[150:153], v[200:203], v[112:115]
	v_mfma_f32_16x16x32_bf16 v[108:111], v[142:145], v[208:211], v[108:111]
	v_mfma_f32_16x16x32_bf16 v[104:107], v[150:153], v[208:211], v[104:107]
	v_mfma_f32_16x16x32_bf16 v[100:103], v[142:145], v[240:243], v[100:103]
	v_mfma_f32_16x16x32_bf16 v[96:99], v[150:153], v[240:243], v[96:99]
	v_mfma_f32_16x16x32_bf16 v[92:95], v[154:157], v[188:191], v[92:95]
	v_mfma_f32_16x16x32_bf16 v[88:91], v[162:165], v[188:191], v[88:91]
	v_mfma_f32_16x16x32_bf16 v[84:87], v[154:157], v[196:199], v[84:87]
	v_mfma_f32_16x16x32_bf16 v[80:83], v[162:165], v[196:199], v[80:83]
	v_mfma_f32_16x16x32_bf16 v[76:79], v[154:157], v[204:207], v[76:79]
	v_mfma_f32_16x16x32_bf16 v[72:75], v[162:165], v[204:207], v[72:75]
	v_mfma_f32_16x16x32_bf16 v[68:71], v[154:157], v[236:239], v[68:71]
	v_mfma_f32_16x16x32_bf16 v[64:67], v[162:165], v[236:239], v[64:67]
	v_mfma_f32_16x16x32_bf16 v[92:95], v[158:161], v[192:195], v[92:95]
	v_mfma_f32_16x16x32_bf16 v[88:91], v[184:187], v[192:195], v[88:91]
	v_mfma_f32_16x16x32_bf16 v[84:87], v[158:161], v[200:203], v[84:87]
	v_mfma_f32_16x16x32_bf16 v[80:83], v[184:187], v[200:203], v[80:83]
	v_mfma_f32_16x16x32_bf16 v[76:79], v[158:161], v[208:211], v[76:79]
	v_mfma_f32_16x16x32_bf16 v[72:75], v[184:187], v[208:211], v[72:75]
	v_mfma_f32_16x16x32_bf16 v[68:71], v[158:161], v[240:243], v[68:71]
	v_mfma_f32_16x16x32_bf16 v[64:67], v[184:187], v[240:243], v[64:67]
	s_barrier
	s_add_i32 s24, s24, s6
	v_lshl_add_u64 v[166:167], s[48:49], 0, v[168:169]
	s_mov_b32 m0, s24
	ds_read_b128 v[188:191], v234 offset:16384
	ds_read_b128 v[192:195], v234 offset:17408
	ds_read_b128 v[196:199], v234 offset:18432
	ds_read_b128 v[200:203], v234 offset:19456
	ds_read_b128 v[204:207], v234 offset:20480
	ds_read_b128 v[208:211], v234 offset:21504
	ds_read_b128 v[236:239], v234 offset:22528
	ds_read_b128 v[240:243], v234 offset:23552
	global_load_lds_dwordx4 v[166:167], off
	s_add_i32 m0, s24, 0x2000
	s_add_u32 s24, s48, 0x40000
	v_lshl_add_u64 v[170:171], s[48:49], 0, v[128:129]
	s_addc_u32 s25, s49, 0
	s_add_i32 s36, s55, s6
	global_load_lds_dwordx4 v[170:171], off
	v_lshl_add_u64 v[172:173], s[24:25], 0, v[168:169]
	s_mov_b32 m0, s36
	v_lshl_add_u64 v[212:213], vcc, 0, v[130:131]
	global_load_lds_dwordx4 v[172:173], off
	v_lshl_add_u64 v[172:173], s[24:25], 0, v[128:129]
	s_add_i32 m0, s36, 0x2000
	s_nop 0
	global_load_lds_dwordx4 v[172:173], off
	v_lshl_add_u64 v[172:173], vcc, 0, v[132:133]
	s_mov_b32 m0, s7
	s_nop 0
	global_load_lds_dwordx4 v[172:173], off
	s_mov_b32 m0, s10
	s_nop 0
	global_load_lds_dwordx4 v[212:213], off
	s_waitcnt vmcnt(8)
	s_waitcnt lgkmcnt(0)
	s_barrier
	v_mfma_f32_16x16x32_bf16 v[60:63], v[138:141], v[188:191], v[60:63]
	v_mfma_f32_16x16x32_bf16 v[56:59], v[146:149], v[188:191], v[56:59]
	v_mfma_f32_16x16x32_bf16 v[52:55], v[138:141], v[196:199], v[52:55]
	v_mfma_f32_16x16x32_bf16 v[48:51], v[146:149], v[196:199], v[48:51]
	v_mfma_f32_16x16x32_bf16 v[44:47], v[138:141], v[204:207], v[44:47]
	v_mfma_f32_16x16x32_bf16 v[40:43], v[146:149], v[204:207], v[40:43]
	v_mfma_f32_16x16x32_bf16 v[36:39], v[138:141], v[236:239], v[36:39]
	v_mfma_f32_16x16x32_bf16 v[32:35], v[146:149], v[236:239], v[32:35]
	v_mfma_f32_16x16x32_bf16 v[60:63], v[142:145], v[192:195], v[60:63]
	v_mfma_f32_16x16x32_bf16 v[56:59], v[150:153], v[192:195], v[56:59]
	v_mfma_f32_16x16x32_bf16 v[52:55], v[142:145], v[200:203], v[52:55]
	v_mfma_f32_16x16x32_bf16 v[48:51], v[150:153], v[200:203], v[48:51]
	v_mfma_f32_16x16x32_bf16 v[44:47], v[142:145], v[208:211], v[44:47]
	v_mfma_f32_16x16x32_bf16 v[40:43], v[150:153], v[208:211], v[40:43]
	v_mfma_f32_16x16x32_bf16 v[36:39], v[142:145], v[240:243], v[36:39]
	v_mfma_f32_16x16x32_bf16 v[32:35], v[150:153], v[240:243], v[32:35]
	v_mfma_f32_16x16x32_bf16 v[28:31], v[154:157], v[188:191], v[28:31]
	v_mfma_f32_16x16x32_bf16 v[24:27], v[162:165], v[188:191], v[24:27]
	v_mfma_f32_16x16x32_bf16 v[20:23], v[154:157], v[196:199], v[20:23]
	v_mfma_f32_16x16x32_bf16 v[16:19], v[162:165], v[196:199], v[16:19]
	v_mfma_f32_16x16x32_bf16 v[12:15], v[154:157], v[204:207], v[12:15]
	v_mfma_f32_16x16x32_bf16 v[8:11], v[162:165], v[204:207], v[8:11]
	v_mfma_f32_16x16x32_bf16 v[4:7], v[154:157], v[236:239], v[4:7]
	v_mfma_f32_16x16x32_bf16 v[0:3], v[162:165], v[236:239], v[0:3]
	v_mfma_f32_16x16x32_bf16 v[28:31], v[158:161], v[192:195], v[28:31]
	v_mfma_f32_16x16x32_bf16 v[24:27], v[184:187], v[192:195], v[24:27]
	v_mfma_f32_16x16x32_bf16 v[20:23], v[158:161], v[200:203], v[20:23]
	v_mfma_f32_16x16x32_bf16 v[16:19], v[184:187], v[200:203], v[16:19]
	v_mfma_f32_16x16x32_bf16 v[12:15], v[158:161], v[208:211], v[12:15]
	v_mfma_f32_16x16x32_bf16 v[8:11], v[184:187], v[208:211], v[8:11]
	v_mfma_f32_16x16x32_bf16 v[4:7], v[158:161], v[240:243], v[4:7]
	v_mfma_f32_16x16x32_bf16 v[0:3], v[184:187], v[240:243], v[0:3]
	s_barrier
; #define PG8_STAGE(bufoff, gbase, voff) do { _Pragma("unroll") for (int _i = 0; _i < 2; ++_i) \
;         __builtin_amdgcn_global_load_lds((const unsigned*)((const char*)(gbase) + (voff)[_i]), (LAS unsigned*)(lds + (bufoff) + ldsw + _i * 8192), 16, 0, 0); } while (0)
; #define PG8_LDA(dst, b, h) do { _Pragma("unroll") for (int m = 0; m < 4; ++m) _Pragma("unroll") for (int k = 0; k < 2; ++k) dst[m][k] = *(const LAS bf16x8*)(lds + PG8_SA(b, h) + aoff + m * 2048 + k * 1024); } while (0)
; #define PG8_LDB(dst, b, h) do { _Pragma("unroll") for (int n = 0; n < 2; ++n) _Pragma("unroll") for (int k = 0; k < 2; ++k) dst[n][k] = *(const LAS bf16x8*)(lds + PG8_SB(b, h) + boff + n * 2048 + k * 1024); } while (0)
; #define PG8_MMA(ai, bj, At, Bt) do { __builtin_amdgcn_s_setprio(1); _Pragma("unroll") for (int m = 0; m < 4; ++m) _Pragma("unroll") for (int n = 0; n < 2; ++n) _Pragma("unroll") for (int k = 0; k < 2; ++k) \
;         acc[ai][bj][m][n] = __builtin_amdgcn_mfma_f32_16x16x32_bf16(Bt[n][k], At[m][k], acc[ai][bj][m][n], 0, 0, 0); __builtin_amdgcn_s_setprio(0); } while (0)
; #define PG8_WAIT_V(n) asm volatile("s_waitcnt vmcnt(" #n ")" ::: "memory")
; #define PG8_WAIT_L(n) asm volatile("s_waitcnt lgkmcnt(" #n ")" ::: "memory")
; #define PG8_BAR __builtin_amdgcn_s_barrier()
; #define PG8_SCHED __builtin_amdgcn_sched_barrier(0)
; template <class Epi>
; __device__ __forceinline__ void gemm_phase(LAS unsigned char* lds, const Gemm g, const StaticOrder& S, const Epi& E, const int tid) {
;     ...
;             PG8_LDB(B0, 1, 0); PG8_LDB(B1, 1, 1); PG8_SCHED; PG8_LDA(At, 1, 0); PG8_STAGE(PG8_SA(0, 1), a2 + hsA, voffA);
;             PG8_WAIT_V(8); PG8_WAIT_L(0); PG8_BAR; PG8_MMA(0, 0, At, B0); PG8_MMA(0, 1, At, B1); PG8_BAR; PG8_SCHED;
	s_add_i32 s36, 0, 0x18000
	s_add_i32 s37, 0, 0x1c000
	v_add_u32_e32 v150, s36, v232
	v_add_u32_e32 v184, s37, v232
	ds_read_b128 v[138:141], v150
	ds_read_b128 v[142:145], v150 offset:1024
	ds_read_b128 v[146:149], v150 offset:2048
	ds_read_b128 v[150:153], v150 offset:3072
	ds_read_b128 v[154:157], v184
	ds_read_b128 v[158:161], v184 offset:1024
	ds_read_b128 v[162:165], v184 offset:2048
	ds_read_b128 v[184:187], v184 offset:3072
	s_add_u32 s24, vcc_lo, 0xc0000
	s_addc_u32 s25, vcc_hi, 0
	s_mov_b32 m0, s11
	v_lshl_add_u64 v[244:245], s[24:25], 0, v[132:133]
	ds_read_b128 v[188:191], v234 offset:32768
	ds_read_b128 v[192:195], v234 offset:33792
	ds_read_b128 v[196:199], v234 offset:34816
	ds_read_b128 v[200:203], v234 offset:35840
	ds_read_b128 v[204:207], v234 offset:36864
	ds_read_b128 v[208:211], v234 offset:37888
	ds_read_b128 v[236:239], v234 offset:38912
	ds_read_b128 v[240:243], v234 offset:39936
	global_load_lds_dwordx4 v[244:245], off
	v_lshl_add_u64 v[244:245], s[24:25], 0, v[130:131]
	s_mov_b32 m0, s27
	s_nop 0
	global_load_lds_dwordx4 v[244:245], off
	s_waitcnt vmcnt(8)
	s_waitcnt lgkmcnt(0)
	s_barrier
	v_mfma_f32_16x16x32_bf16 v[124:127], v[138:141], v[188:191], v[124:127]
	v_mfma_f32_16x16x32_bf16 v[120:123], v[146:149], v[188:191], v[120:123]
	v_mfma_f32_16x16x32_bf16 v[116:119], v[138:141], v[196:199], v[116:119]
	v_mfma_f32_16x16x32_bf16 v[112:115], v[146:149], v[196:199], v[112:115]
	v_mfma_f32_16x16x32_bf16 v[108:111], v[138:141], v[204:207], v[108:111]
	v_mfma_f32_16x16x32_bf16 v[104:107], v[146:149], v[204:207], v[104:107]
	v_mfma_f32_16x16x32_bf16 v[100:103], v[138:141], v[236:239], v[100:103]
	v_mfma_f32_16x16x32_bf16 v[96:99], v[146:149], v[236:239], v[96:99]
	v_mfma_f32_16x16x32_bf16 v[124:127], v[142:145], v[192:195], v[124:127]
	v_mfma_f32_16x16x32_bf16 v[120:123], v[150:153], v[192:195], v[120:123]
	v_mfma_f32_16x16x32_bf16 v[116:119], v[142:145], v[200:203], v[116:119]
	v_mfma_f32_16x16x32_bf16 v[112:115], v[150:153], v[200:203], v[112:115]
	v_mfma_f32_16x16x32_bf16 v[108:111], v[142:145], v[208:211], v[108:111]
	v_mfma_f32_16x16x32_bf16 v[104:107], v[150:153], v[208:211], v[104:107]
	v_mfma_f32_16x16x32_bf16 v[100:103], v[142:145], v[240:243], v[100:103]
	v_mfma_f32_16x16x32_bf16 v[96:99], v[150:153], v[240:243], v[96:99]
	v_mfma_f32_16x16x32_bf16 v[92:95], v[154:157], v[188:191], v[92:95]
	v_mfma_f32_16x16x32_bf16 v[88:91], v[162:165], v[188:191], v[88:91]
	v_mfma_f32_16x16x32_bf16 v[84:87], v[154:157], v[196:199], v[84:87]
	v_mfma_f32_16x16x32_bf16 v[80:83], v[162:165], v[196:199], v[80:83]
	v_mfma_f32_16x16x32_bf16 v[76:79], v[154:157], v[204:207], v[76:79]
	v_mfma_f32_16x16x32_bf16 v[72:75], v[162:165], v[204:207], v[72:75]
	v_mfma_f32_16x16x32_bf16 v[68:71], v[154:157], v[236:239], v[68:71]
	v_mfma_f32_16x16x32_bf16 v[64:67], v[162:165], v[236:239], v[64:67]
	v_mfma_f32_16x16x32_bf16 v[92:95], v[158:161], v[192:195], v[92:95]
	v_mfma_f32_16x16x32_bf16 v[88:91], v[184:187], v[192:195], v[88:91]
	v_mfma_f32_16x16x32_bf16 v[84:87], v[158:161], v[200:203], v[84:87]
	v_mfma_f32_16x16x32_bf16 v[80:83], v[184:187], v[200:203], v[80:83]
	v_mfma_f32_16x16x32_bf16 v[76:79], v[158:161], v[208:211], v[76:79]
	v_mfma_f32_16x16x32_bf16 v[72:75], v[184:187], v[208:211], v[72:75]
	v_mfma_f32_16x16x32_bf16 v[68:71], v[158:161], v[240:243], v[68:71]
	v_mfma_f32_16x16x32_bf16 v[64:67], v[184:187], v[240:243], v[64:67]
	s_barrier
; #define PG8_STAGE(bufoff, gbase, voff) do { _Pragma("unroll") for (int _i = 0; _i < 2; ++_i) \
;         __builtin_amdgcn_global_load_lds((const unsigned*)((const char*)(gbase) + (voff)[_i]), (LAS unsigned*)(lds + (bufoff) + ldsw + _i * 8192), 16, 0, 0); } while (0)
; #define PG8_LDA(dst, b, h) do { _Pragma("unroll") for (int m = 0; m < 4; ++m) _Pragma("unroll") for (int k = 0; k < 2; ++k) dst[m][k] = *(const LAS bf16x8*)(lds + PG8_SA(b, h) + aoff + m * 2048 + k * 1024); } while (0)
; #define PG8_LDB(dst, b, h) do { _Pragma("unroll") for (int n = 0; n < 2; ++n) _Pragma("unroll") for (int k = 0; k < 2; ++k) dst[n][k] = *(const LAS bf16x8*)(lds + PG8_SB(b, h) + boff + n * 2048 + k * 1024); } while (0)
; #define PG8_WAIT_V(n) asm volatile("s_waitcnt vmcnt(" #n ")" ::: "memory")
; #define PG8_WAIT_L(n) asm volatile("s_waitcnt lgkmcnt(" #n ")" ::: "memory")
; template <class Epi>
; __device__ __forceinline__ void gemm_phase(LAS unsigned char* lds, const Gemm g, const StaticOrder& S, const Epi& E, const int tid) {
;     ...
;         for (int t = 0; t < nt; t += 2) {
;             const bool last = (t == nt - 2);
;             const char* a1 = cA + (size_t)(t + 1) * kstep;
;             const char* a2 = last ? nA : cA + (size_t)(t + 2) * kstep; const char* b2 = last ? nB : cB + (size_t)(t + 2) * kstep;
;             const char* a3 = a2 + kstep; const char* b3 = b2 + kstep;
;             PG8_LDB(B0, 0, 0); PG8_LDB(B1, 0, 1); PG8_SCHED; PG8_LDA(At, 0, 0); PG8_STAGE(PG8_SA(1, 1), a1 + hsA, voffA);
;             PG8_WAIT_V(8); PG8_WAIT_L(0); PG8_BAR; PG8_MMA(0, 0, At, B0); PG8_MMA(0, 1, At, B1); PG8_BAR; PG8_SCHED;
;             PG8_LDA(At, 0, 1); PG8_STAGE(PG8_SB(0, 0), b2, voffB); PG8_STAGE(PG8_SB(0, 1), b2 + hsB, voffB); PG8_STAGE(PG8_SA(0, 0), a2, voffA);
;             PG8_WAIT_V(8); PG8_WAIT_L(0); PG8_BAR; PG8_MMA(1, 0, At, B0); PG8_MMA(1, 1, At, B1); PG8_BAR; PG8_SCHED;
;             PG8_LDB(B0, 1, 0); PG8_LDB(B1, 1, 1); PG8_SCHED; PG8_LDA(At, 1, 0); PG8_STAGE(PG8_SA(0, 1), a2 + hsA, voffA);
;             PG8_WAIT_V(8); PG8_WAIT_L(0); PG8_BAR; PG8_MMA(0, 0, At, B0); PG8_MMA(0, 1, At, B1); PG8_BAR; PG8_SCHED;
;             PG8_LDA(At, 1, 1); PG8_STAGE(PG8_SB(1, 0), b3, voffB); PG8_STAGE(PG8_SB(1, 1), b3 + hsB, voffB); PG8_STAGE(PG8_SA(1, 0), a3, voffA);
;             PG8_WAIT_V(8); PG8_WAIT_L(0); PG8_BAR; PG8_MMA(1, 0, At, B0); PG8_MMA(1, 1, At, B1); PG8_BAR; PG8_SCHED;
	s_add_i32 s24, s36, s6
	v_lshl_add_u64 v[166:167], v[166:167], 0, s[28:29]
	s_mov_b32 m0, s24
	ds_read_b128 v[188:191], v234 offset:49152
	ds_read_b128 v[192:195], v234 offset:50176
	ds_read_b128 v[196:199], v234 offset:51200
	ds_read_b128 v[200:203], v234 offset:52224
	ds_read_b128 v[204:207], v234 offset:53248
	ds_read_b128 v[208:211], v234 offset:54272
	ds_read_b128 v[236:239], v234 offset:55296
	ds_read_b128 v[240:243], v234 offset:56320
	global_load_lds_dwordx4 v[166:167], off
	s_add_i32 m0, s24, 0x2000
	s_add_u32 s24, s48, 0x40080
	v_lshl_add_u64 v[166:167], v[170:171], 0, s[28:29]
	s_addc_u32 s25, s49, 0
	s_add_i32 s36, s37, s6
	global_load_lds_dwordx4 v[166:167], off
	v_lshl_add_u64 v[166:167], s[24:25], 0, v[168:169]
	s_mov_b32 m0, s36
	s_nop 0
	global_load_lds_dwordx4 v[166:167], off
	v_lshl_add_u64 v[166:167], s[24:25], 0, v[128:129]
	s_add_i32 m0, s36, 0x2000
	s_nop 0
	global_load_lds_dwordx4 v[166:167], off
	v_lshl_add_u64 v[166:167], v[172:173], 0, s[28:29]
	s_mov_b32 m0, s56
	s_nop 0
	global_load_lds_dwordx4 v[166:167], off
	v_lshl_add_u64 v[166:167], v[212:213], 0, s[28:29]
	s_mov_b32 m0, s57
	s_nop 0
	global_load_lds_dwordx4 v[166:167], off
	s_waitcnt vmcnt(8)
	s_waitcnt lgkmcnt(0)
	s_barrier
	v_mfma_f32_16x16x32_bf16 v[60:63], v[138:141], v[188:191], v[60:63]
	s_add_i32 s96, s96, 2
	s_add_u32 s68, s68, 0x100
	s_addc_u32 s69, s69, 0
	s_mov_b64 s[36:37], s[42:43]
	v_mfma_f32_16x16x32_bf16 v[56:59], v[146:149], v[188:191], v[56:59]
	s_add_u32 s42, s36, 0x100
	s_addc_u32 s43, s37, 0
	s_add_i32 s24, 0, 0x10000
	s_cmp_eq_u32 s96, 12
	v_mfma_f32_16x16x32_bf16 v[52:55], v[138:141], v[196:199], v[52:55]
	s_cselect_b32 vcc_hi, s47, s43
	s_cselect_b32 vcc_lo, s46, s42
	s_cselect_b32 s49, s35, s69
	s_cselect_b32 s48, s45, s68
	v_mfma_f32_16x16x32_bf16 v[48:51], v[146:149], v[196:199], v[48:51]
	s_add_i32 s55, 0, 0x14000
	s_cmp_gt_u32 s96, 13
	v_mfma_f32_16x16x32_bf16 v[44:47], v[138:141], v[204:207], v[44:47]
	v_mfma_f32_16x16x32_bf16 v[40:43], v[146:149], v[204:207], v[40:43]
	v_mfma_f32_16x16x32_bf16 v[36:39], v[138:141], v[236:239], v[36:39]
	v_mfma_f32_16x16x32_bf16 v[32:35], v[146:149], v[236:239], v[32:35]
	v_mfma_f32_16x16x32_bf16 v[60:63], v[142:145], v[192:195], v[60:63]
	v_mfma_f32_16x16x32_bf16 v[56:59], v[150:153], v[192:195], v[56:59]
	v_mfma_f32_16x16x32_bf16 v[52:55], v[142:145], v[200:203], v[52:55]
	v_mfma_f32_16x16x32_bf16 v[48:51], v[150:153], v[200:203], v[48:51]
	v_mfma_f32_16x16x32_bf16 v[44:47], v[142:145], v[208:211], v[44:47]
	v_mfma_f32_16x16x32_bf16 v[40:43], v[150:153], v[208:211], v[40:43]
	v_mfma_f32_16x16x32_bf16 v[36:39], v[142:145], v[240:243], v[36:39]
	v_mfma_f32_16x16x32_bf16 v[32:35], v[150:153], v[240:243], v[32:35]
	v_mfma_f32_16x16x32_bf16 v[28:31], v[154:157], v[188:191], v[28:31]
	v_mfma_f32_16x16x32_bf16 v[24:27], v[162:165], v[188:191], v[24:27]
	v_mfma_f32_16x16x32_bf16 v[20:23], v[154:157], v[196:199], v[20:23]
	v_mfma_f32_16x16x32_bf16 v[16:19], v[162:165], v[196:199], v[16:19]
	v_mfma_f32_16x16x32_bf16 v[12:15], v[154:157], v[204:207], v[12:15]
	v_mfma_f32_16x16x32_bf16 v[8:11], v[162:165], v[204:207], v[8:11]
	v_mfma_f32_16x16x32_bf16 v[4:7], v[154:157], v[236:239], v[4:7]
	v_mfma_f32_16x16x32_bf16 v[0:3], v[162:165], v[236:239], v[0:3]
	v_mfma_f32_16x16x32_bf16 v[28:31], v[158:161], v[192:195], v[28:31]
	v_mfma_f32_16x16x32_bf16 v[24:27], v[184:187], v[192:195], v[24:27]
	v_mfma_f32_16x16x32_bf16 v[20:23], v[158:161], v[200:203], v[20:23]
	v_mfma_f32_16x16x32_bf16 v[16:19], v[184:187], v[200:203], v[16:19]
	v_mfma_f32_16x16x32_bf16 v[12:15], v[158:161], v[208:211], v[12:15]
	v_mfma_f32_16x16x32_bf16 v[8:11], v[184:187], v[208:211], v[8:11]
	v_mfma_f32_16x16x32_bf16 v[4:7], v[158:161], v[240:243], v[4:7]
	v_mfma_f32_16x16x32_bf16 v[0:3], v[184:187], v[240:243], v[0:3]
	s_barrier
	s_cbranch_scc0 .Lkrot_d
	s_and_b64 vcc, exec, s[12:13]
	s_cbranch_vccz .LBB0_826
	s_barrier

; #define PG8_STAGE(bufoff, gbase, voff) do { _Pragma("unroll") for (int _i = 0; _i < 2; ++_i) \
;         __builtin_amdgcn_global_load_lds((const unsigned*)((const char*)(gbase) + (voff)[_i]), (LAS unsigned*)(lds + (bufoff) + ldsw + _i * 8192), 16, 0, 0); } while (0)
; #define PG8_LDA(dst, b, h) do { _Pragma("unroll") for (int m = 0; m < 4; ++m) _Pragma("unroll") for (int k = 0; k < 2; ++k) dst[m][k] = *(const LAS bf16x8*)(lds + PG8_SA(b, h) + aoff + m * 2048 + k * 1024); } while (0)
; #define PG8_LDB(dst, b, h) do { _Pragma("unroll") for (int n = 0; n < 2; ++n) _Pragma("unroll") for (int k = 0; k < 2; ++k) dst[n][k] = *(const LAS bf16x8*)(lds + PG8_SB(b, h) + boff + n * 2048 + k * 1024); } while (0)
; #define PG8_MMA(ai, bj, At, Bt) do { __builtin_amdgcn_s_setprio(1); _Pragma("unroll") for (int m = 0; m < 4; ++m) _Pragma("unroll") for (int n = 0; n < 2; ++n) _Pragma("unroll") for (int k = 0; k < 2; ++k) \
;         acc[ai][bj][m][n] = __builtin_amdgcn_mfma_f32_16x16x32_bf16(Bt[n][k], At[m][k], acc[ai][bj][m][n], 0, 0, 0); __builtin_amdgcn_s_setprio(0); } while (0)
; #define PG8_WAIT_V(n) asm volatile("s_waitcnt vmcnt(" #n ")" ::: "memory")
; #define PG8_WAIT_L(n) asm volatile("s_waitcnt lgkmcnt(" #n ")" ::: "memory")
; #define PG8_BAR __builtin_amdgcn_s_barrier()
; #define PG8_SCHED __builtin_amdgcn_sched_barrier(0)
; template <class Epi>
; __device__ __forceinline__ void gemm_phase(LAS unsigned char* lds, const Gemm g, const StaticOrder& S, const Epi& E, const int tid) {
;     ...
;             PG8_LDB(B0, 0, 0); PG8_LDB(B1, 0, 1); PG8_SCHED; PG8_LDA(At, 0, 0); PG8_STAGE(PG8_SA(1, 1), a1 + hsA, voffA);
;             PG8_WAIT_V(8); PG8_WAIT_L(0); PG8_BAR; PG8_MMA(0, 0, At, B0); PG8_MMA(0, 1, At, B1); PG8_BAR; PG8_SCHED;
;             PG8_LDA(At, 0, 1); PG8_STAGE(PG8_SB(0, 0), b2, voffB); PG8_STAGE(PG8_SB(0, 1), b2 + hsB, voffB); PG8_STAGE(PG8_SA(0, 0), a2, voffA);
;             PG8_WAIT_V(8); PG8_WAIT_L(0); PG8_BAR; PG8_MMA(1, 0, At, B0); PG8_MMA(1, 1, At, B1); PG8_BAR; PG8_SCHED;
.Lkrot_e:
	v_add_u32_e32 v76, s2, v204
	v_add_u32_e32 v156, s55, v204
	ds_read_b128 v[64:67], v76
	ds_read_b128 v[68:71], v76 offset:1024
	ds_read_b128 v[72:75], v76 offset:2048
	ds_read_b128 v[76:79], v76 offset:3072
	ds_read_b128 v[144:147], v156
	ds_read_b128 v[148:151], v156 offset:1024
	ds_read_b128 v[152:155], v156 offset:2048
	ds_read_b128 v[156:159], v156 offset:3072
	v_lshl_add_u64 v[170:171], s[16:17], 0, v[192:193]
	s_add_i32 m0, s36, 0xc000
	ds_read_b128 v[160:163], v209
	ds_read_b128 v[164:167], v209 offset:1024
	ds_read_b128 v[196:199], v209 offset:2048
	ds_read_b128 v[200:203], v209 offset:3072
	ds_read_b128 v[210:213], v209 offset:4096
	ds_read_b128 v[230:233], v209 offset:5120
	ds_read_b128 v[234:237], v209 offset:6144
	ds_read_b128 v[238:241], v209 offset:7168
	global_load_lds_dwordx4 v[170:171], off
	v_lshl_add_u64 v[170:171], s[16:17], 0, v[194:195]
	s_add_i32 m0, s36, 0xe000
	s_nop 0
	global_load_lds_dwordx4 v[170:171], off
	s_waitcnt vmcnt(8)
	s_waitcnt lgkmcnt(0)
	s_barrier
	v_mfma_f32_16x16x32_bf16 v[140:143], v[64:67], v[160:163], v[140:143]
	v_mfma_f32_16x16x32_bf16 v[136:139], v[72:75], v[160:163], v[136:139]
	v_mfma_f32_16x16x32_bf16 v[124:127], v[64:67], v[196:199], v[124:127]
	v_mfma_f32_16x16x32_bf16 v[120:123], v[72:75], v[196:199], v[120:123]
	v_mfma_f32_16x16x32_bf16 v[108:111], v[64:67], v[210:213], v[108:111]
	v_mfma_f32_16x16x32_bf16 v[104:107], v[72:75], v[210:213], v[104:107]
	v_mfma_f32_16x16x32_bf16 v[96:99], v[64:67], v[234:237], v[96:99]
	v_mfma_f32_16x16x32_bf16 v[88:91], v[72:75], v[234:237], v[88:91]
	v_mfma_f32_16x16x32_bf16 v[140:143], v[68:71], v[164:167], v[140:143]
	v_mfma_f32_16x16x32_bf16 v[136:139], v[76:79], v[164:167], v[136:139]
	v_mfma_f32_16x16x32_bf16 v[124:127], v[68:71], v[200:203], v[124:127]
	v_mfma_f32_16x16x32_bf16 v[120:123], v[76:79], v[200:203], v[120:123]
	v_mfma_f32_16x16x32_bf16 v[108:111], v[68:71], v[230:233], v[108:111]
	v_mfma_f32_16x16x32_bf16 v[104:107], v[76:79], v[230:233], v[104:107]
	v_mfma_f32_16x16x32_bf16 v[96:99], v[68:71], v[238:241], v[96:99]
	v_mfma_f32_16x16x32_bf16 v[88:91], v[76:79], v[238:241], v[88:91]
	v_mfma_f32_16x16x32_bf16 v[132:135], v[144:147], v[160:163], v[132:135]
	v_mfma_f32_16x16x32_bf16 v[128:131], v[152:155], v[160:163], v[128:131]
	v_mfma_f32_16x16x32_bf16 v[116:119], v[144:147], v[196:199], v[116:119]
	v_mfma_f32_16x16x32_bf16 v[112:115], v[152:155], v[196:199], v[112:115]
	v_mfma_f32_16x16x32_bf16 v[100:103], v[144:147], v[210:213], v[100:103]
	v_mfma_f32_16x16x32_bf16 v[92:95], v[152:155], v[210:213], v[92:95]
	v_mfma_f32_16x16x32_bf16 v[84:87], v[144:147], v[234:237], v[84:87]
	v_mfma_f32_16x16x32_bf16 v[80:83], v[152:155], v[234:237], v[80:83]
	v_mfma_f32_16x16x32_bf16 v[132:135], v[148:151], v[164:167], v[132:135]
	v_mfma_f32_16x16x32_bf16 v[128:131], v[156:159], v[164:167], v[128:131]
	v_mfma_f32_16x16x32_bf16 v[116:119], v[148:151], v[200:203], v[116:119]
	v_mfma_f32_16x16x32_bf16 v[112:115], v[156:159], v[200:203], v[112:115]
	v_mfma_f32_16x16x32_bf16 v[100:103], v[148:151], v[230:233], v[100:103]
	v_mfma_f32_16x16x32_bf16 v[92:95], v[156:159], v[230:233], v[92:95]
	v_mfma_f32_16x16x32_bf16 v[84:87], v[148:151], v[238:241], v[84:87]
	v_mfma_f32_16x16x32_bf16 v[80:83], v[156:159], v[238:241], v[80:83]
	s_barrier
	s_add_i32 s2, s2, s35
	v_lshl_add_u64 v[170:171], s[0:1], 0, v[188:189]
	s_mov_b32 m0, s2
	ds_read_b128 v[160:163], v209 offset:16384
	ds_read_b128 v[164:167], v209 offset:17408
	ds_read_b128 v[196:199], v209 offset:18432
	ds_read_b128 v[200:203], v209 offset:19456
	ds_read_b128 v[210:213], v209 offset:20480
	ds_read_b128 v[230:233], v209 offset:21504
	ds_read_b128 v[234:237], v209 offset:22528
	ds_read_b128 v[238:241], v209 offset:23552
	global_load_lds_dwordx4 v[170:171], off
	s_add_i32 m0, s2, 0x2000
	s_add_u32 s24, s0, 0x80000
	v_lshl_add_u64 v[172:173], s[0:1], 0, v[184:185]
	s_addc_u32 s25, s1, 0
	s_add_i32 s2, s55, s35
	global_load_lds_dwordx4 v[172:173], off
	v_lshl_add_u64 v[242:243], s[24:25], 0, v[188:189]
	s_mov_b32 m0, s2
	v_lshl_add_u64 v[244:245], s[18:19], 0, v[186:187]
	global_load_lds_dwordx4 v[242:243], off
	v_lshl_add_u64 v[242:243], s[24:25], 0, v[184:185]
	s_add_i32 m0, s2, 0x2000
	s_nop 0
	global_load_lds_dwordx4 v[242:243], off
	v_lshl_add_u64 v[242:243], s[18:19], 0, v[190:191]
	s_mov_b32 m0, s36
	s_nop 0
	global_load_lds_dwordx4 v[242:243], off
	s_mov_b32 m0, s37
	s_nop 0
	global_load_lds_dwordx4 v[244:245], off
	s_waitcnt vmcnt(8)
	s_waitcnt lgkmcnt(0)
	s_barrier
	v_mfma_f32_16x16x32_bf16 v[60:63], v[64:67], v[160:163], v[60:63]
	v_mfma_f32_16x16x32_bf16 v[56:59], v[72:75], v[160:163], v[56:59]
	v_mfma_f32_16x16x32_bf16 v[44:47], v[64:67], v[196:199], v[44:47]
	v_mfma_f32_16x16x32_bf16 v[40:43], v[72:75], v[196:199], v[40:43]
	v_mfma_f32_16x16x32_bf16 v[28:31], v[64:67], v[210:213], v[28:31]
	v_mfma_f32_16x16x32_bf16 v[24:27], v[72:75], v[210:213], v[24:27]
	v_mfma_f32_16x16x32_bf16 v[12:15], v[64:67], v[234:237], v[12:15]
	v_mfma_f32_16x16x32_bf16 v[8:11], v[72:75], v[234:237], v[8:11]
	v_mfma_f32_16x16x32_bf16 v[60:63], v[68:71], v[164:167], v[60:63]
	v_mfma_f32_16x16x32_bf16 v[56:59], v[76:79], v[164:167], v[56:59]
	v_mfma_f32_16x16x32_bf16 v[44:47], v[68:71], v[200:203], v[44:47]
	v_mfma_f32_16x16x32_bf16 v[40:43], v[76:79], v[200:203], v[40:43]
	v_mfma_f32_16x16x32_bf16 v[28:31], v[68:71], v[230:233], v[28:31]
	v_mfma_f32_16x16x32_bf16 v[24:27], v[76:79], v[230:233], v[24:27]
	v_mfma_f32_16x16x32_bf16 v[12:15], v[68:71], v[238:241], v[12:15]
	v_mfma_f32_16x16x32_bf16 v[8:11], v[76:79], v[238:241], v[8:11]
	v_mfma_f32_16x16x32_bf16 v[52:55], v[144:147], v[160:163], v[52:55]
	v_mfma_f32_16x16x32_bf16 v[48:51], v[152:155], v[160:163], v[48:51]
	v_mfma_f32_16x16x32_bf16 v[36:39], v[144:147], v[196:199], v[36:39]
	v_mfma_f32_16x16x32_bf16 v[32:35], v[152:155], v[196:199], v[32:35]
	v_mfma_f32_16x16x32_bf16 v[20:23], v[144:147], v[210:213], v[20:23]
	v_mfma_f32_16x16x32_bf16 v[16:19], v[152:155], v[210:213], v[16:19]
	v_mfma_f32_16x16x32_bf16 v[4:7], v[144:147], v[234:237], v[4:7]
	v_mfma_f32_16x16x32_bf16 v[0:3], v[152:155], v[234:237], v[0:3]
	v_mfma_f32_16x16x32_bf16 v[52:55], v[148:151], v[164:167], v[52:55]
	v_mfma_f32_16x16x32_bf16 v[48:51], v[156:159], v[164:167], v[48:51]
	v_mfma_f32_16x16x32_bf16 v[36:39], v[148:151], v[200:203], v[36:39]
	v_mfma_f32_16x16x32_bf16 v[32:35], v[156:159], v[200:203], v[32:35]
	v_mfma_f32_16x16x32_bf16 v[20:23], v[148:151], v[230:233], v[20:23]
	v_mfma_f32_16x16x32_bf16 v[16:19], v[156:159], v[230:233], v[16:19]
	v_mfma_f32_16x16x32_bf16 v[4:7], v[148:151], v[238:241], v[4:7]
	v_mfma_f32_16x16x32_bf16 v[0:3], v[156:159], v[238:241], v[0:3]
	s_barrier
; #define PG8_STAGE(bufoff, gbase, voff) do { _Pragma("unroll") for (int _i = 0; _i < 2; ++_i) \
;         __builtin_amdgcn_global_load_lds((const unsigned*)((const char*)(gbase) + (voff)[_i]), (LAS unsigned*)(lds + (bufoff) + ldsw + _i * 8192), 16, 0, 0); } while (0)
; #define PG8_LDA(dst, b, h) do { _Pragma("unroll") for (int m = 0; m < 4; ++m) _Pragma("unroll") for (int k = 0; k < 2; ++k) dst[m][k] = *(const LAS bf16x8*)(lds + PG8_SA(b, h) + aoff + m * 2048 + k * 1024); } while (0)
; #define PG8_LDB(dst, b, h) do { _Pragma("unroll") for (int n = 0; n < 2; ++n) _Pragma("unroll") for (int k = 0; k < 2; ++k) dst[n][k] = *(const LAS bf16x8*)(lds + PG8_SB(b, h) + boff + n * 2048 + k * 1024); } while (0)
; #define PG8_MMA(ai, bj, At, Bt) do { __builtin_amdgcn_s_setprio(1); _Pragma("unroll") for (int m = 0; m < 4; ++m) _Pragma("unroll") for (int n = 0; n < 2; ++n) _Pragma("unroll") for (int k = 0; k < 2; ++k) \
;         acc[ai][bj][m][n] = __builtin_amdgcn_mfma_f32_16x16x32_bf16(Bt[n][k], At[m][k], acc[ai][bj][m][n], 0, 0, 0); __builtin_amdgcn_s_setprio(0); } while (0)
; #define PG8_WAIT_V(n) asm volatile("s_waitcnt vmcnt(" #n ")" ::: "memory")
; #define PG8_WAIT_L(n) asm volatile("s_waitcnt lgkmcnt(" #n ")" ::: "memory")
; #define PG8_BAR __builtin_amdgcn_s_barrier()
; #define PG8_SCHED __builtin_amdgcn_sched_barrier(0)
; template <class Epi>
; __device__ __forceinline__ void gemm_phase(LAS unsigned char* lds, const Gemm g, const StaticOrder& S, const Epi& E, const int tid) {
;     ...
;             PG8_LDB(B0, 1, 0); PG8_LDB(B1, 1, 1); PG8_SCHED; PG8_LDA(At, 1, 0); PG8_STAGE(PG8_SA(0, 1), a2 + hsA, voffA);
;             PG8_WAIT_V(8); PG8_WAIT_L(0); PG8_BAR; PG8_MMA(0, 0, At, B0); PG8_MMA(0, 1, At, B1); PG8_BAR; PG8_SCHED;
	s_add_i32 s2, 0, 0x18000
	s_add_i32 s24, 0, 0x1c000
	v_add_u32_e32 v76, s2, v204
	v_add_u32_e32 v156, s24, v204
	ds_read_b128 v[64:67], v76
	ds_read_b128 v[68:71], v76 offset:1024
	ds_read_b128 v[72:75], v76 offset:2048
	ds_read_b128 v[76:79], v76 offset:3072
	ds_read_b128 v[144:147], v156
	ds_read_b128 v[148:151], v156 offset:1024
	ds_read_b128 v[152:155], v156 offset:2048
	ds_read_b128 v[156:159], v156 offset:3072
	s_add_u32 s18, s18, 0x80000
	s_addc_u32 s19, s19, 0
	s_mov_b32 m0, s38
	v_lshl_add_u64 v[246:247], s[18:19], 0, v[190:191]
	ds_read_b128 v[160:163], v209 offset:32768
	ds_read_b128 v[164:167], v209 offset:33792
	ds_read_b128 v[196:199], v209 offset:34816
	ds_read_b128 v[200:203], v209 offset:35840
	ds_read_b128 v[210:213], v209 offset:36864
	ds_read_b128 v[230:233], v209 offset:37888
	ds_read_b128 v[234:237], v209 offset:38912
	ds_read_b128 v[238:241], v209 offset:39936
	global_load_lds_dwordx4 v[246:247], off
	v_lshl_add_u64 v[246:247], s[18:19], 0, v[186:187]
	s_mov_b32 m0, s39
	s_nop 0
	global_load_lds_dwordx4 v[246:247], off
	s_waitcnt vmcnt(8)
	s_waitcnt lgkmcnt(0)
	s_barrier
	v_mfma_f32_16x16x32_bf16 v[140:143], v[64:67], v[160:163], v[140:143]
	v_mfma_f32_16x16x32_bf16 v[136:139], v[72:75], v[160:163], v[136:139]
	v_mfma_f32_16x16x32_bf16 v[124:127], v[64:67], v[196:199], v[124:127]
	v_mfma_f32_16x16x32_bf16 v[120:123], v[72:75], v[196:199], v[120:123]
	v_mfma_f32_16x16x32_bf16 v[108:111], v[64:67], v[210:213], v[108:111]
	v_mfma_f32_16x16x32_bf16 v[104:107], v[72:75], v[210:213], v[104:107]
	v_mfma_f32_16x16x32_bf16 v[96:99], v[64:67], v[234:237], v[96:99]
	v_mfma_f32_16x16x32_bf16 v[88:91], v[72:75], v[234:237], v[88:91]
	v_mfma_f32_16x16x32_bf16 v[140:143], v[68:71], v[164:167], v[140:143]
	v_mfma_f32_16x16x32_bf16 v[136:139], v[76:79], v[164:167], v[136:139]
	v_mfma_f32_16x16x32_bf16 v[124:127], v[68:71], v[200:203], v[124:127]
	v_mfma_f32_16x16x32_bf16 v[120:123], v[76:79], v[200:203], v[120:123]
	v_mfma_f32_16x16x32_bf16 v[108:111], v[68:71], v[230:233], v[108:111]
	v_mfma_f32_16x16x32_bf16 v[104:107], v[76:79], v[230:233], v[104:107]
	v_mfma_f32_16x16x32_bf16 v[96:99], v[68:71], v[238:241], v[96:99]
	v_mfma_f32_16x16x32_bf16 v[88:91], v[76:79], v[238:241], v[88:91]
	v_mfma_f32_16x16x32_bf16 v[132:135], v[144:147], v[160:163], v[132:135]
	v_mfma_f32_16x16x32_bf16 v[128:131], v[152:155], v[160:163], v[128:131]
	v_mfma_f32_16x16x32_bf16 v[116:119], v[144:147], v[196:199], v[116:119]
	v_mfma_f32_16x16x32_bf16 v[112:115], v[152:155], v[196:199], v[112:115]
	v_mfma_f32_16x16x32_bf16 v[100:103], v[144:147], v[210:213], v[100:103]
	v_mfma_f32_16x16x32_bf16 v[92:95], v[152:155], v[210:213], v[92:95]
	v_mfma_f32_16x16x32_bf16 v[84:87], v[144:147], v[234:237], v[84:87]
	v_mfma_f32_16x16x32_bf16 v[80:83], v[152:155], v[234:237], v[80:83]
	v_mfma_f32_16x16x32_bf16 v[132:135], v[148:151], v[164:167], v[132:135]
	v_mfma_f32_16x16x32_bf16 v[128:131], v[156:159], v[164:167], v[128:131]
	v_mfma_f32_16x16x32_bf16 v[116:119], v[148:151], v[200:203], v[116:119]
	v_mfma_f32_16x16x32_bf16 v[112:115], v[156:159], v[200:203], v[112:115]
	v_mfma_f32_16x16x32_bf16 v[100:103], v[148:151], v[230:233], v[100:103]
	v_mfma_f32_16x16x32_bf16 v[92:95], v[156:159], v[230:233], v[92:95]
	v_mfma_f32_16x16x32_bf16 v[84:87], v[148:151], v[238:241], v[84:87]
	v_mfma_f32_16x16x32_bf16 v[80:83], v[156:159], v[238:241], v[80:83]
	s_barrier
; #define PG8_STAGE(bufoff, gbase, voff) do { _Pragma("unroll") for (int _i = 0; _i < 2; ++_i) \
;         __builtin_amdgcn_global_load_lds((const unsigned*)((const char*)(gbase) + (voff)[_i]), (LAS unsigned*)(lds + (bufoff) + ldsw + _i * 8192), 16, 0, 0); } while (0)
; #define PG8_LDA(dst, b, h) do { _Pragma("unroll") for (int m = 0; m < 4; ++m) _Pragma("unroll") for (int k = 0; k < 2; ++k) dst[m][k] = *(const LAS bf16x8*)(lds + PG8_SA(b, h) + aoff + m * 2048 + k * 1024); } while (0)
; #define PG8_LDB(dst, b, h) do { _Pragma("unroll") for (int n = 0; n < 2; ++n) _Pragma("unroll") for (int k = 0; k < 2; ++k) dst[n][k] = *(const LAS bf16x8*)(lds + PG8_SB(b, h) + boff + n * 2048 + k * 1024); } while (0)
; #define PG8_WAIT_V(n) asm volatile("s_waitcnt vmcnt(" #n ")" ::: "memory")
; #define PG8_WAIT_L(n) asm volatile("s_waitcnt lgkmcnt(" #n ")" ::: "memory")
; template <class Epi>
; __device__ __forceinline__ void gemm_phase(LAS unsigned char* lds, const Gemm g, const StaticOrder& S, const Epi& E, const int tid) {
;     ...
;         for (int t = 0; t < nt; t += 2) {
;             const bool last = (t == nt - 2);
;             const char* a1 = cA + (size_t)(t + 1) * kstep;
;             const char* a2 = last ? nA : cA + (size_t)(t + 2) * kstep; const char* b2 = last ? nB : cB + (size_t)(t + 2) * kstep;
;             const char* a3 = a2 + kstep; const char* b3 = b2 + kstep;
;             PG8_LDB(B0, 0, 0); PG8_LDB(B1, 0, 1); PG8_SCHED; PG8_LDA(At, 0, 0); PG8_STAGE(PG8_SA(1, 1), a1 + hsA, voffA);
;             PG8_WAIT_V(8); PG8_WAIT_L(0); PG8_BAR; PG8_MMA(0, 0, At, B0); PG8_MMA(0, 1, At, B1); PG8_BAR; PG8_SCHED;
;             PG8_LDA(At, 0, 1); PG8_STAGE(PG8_SB(0, 0), b2, voffB); PG8_STAGE(PG8_SB(0, 1), b2 + hsB, voffB); PG8_STAGE(PG8_SA(0, 0), a2, voffA);
;             PG8_WAIT_V(8); PG8_WAIT_L(0); PG8_BAR; PG8_MMA(1, 0, At, B0); PG8_MMA(1, 1, At, B1); PG8_BAR; PG8_SCHED;
;             PG8_LDB(B0, 1, 0); PG8_LDB(B1, 1, 1); PG8_SCHED; PG8_LDA(At, 1, 0); PG8_STAGE(PG8_SA(0, 1), a2 + hsA, voffA);
;             PG8_WAIT_V(8); PG8_WAIT_L(0); PG8_BAR; PG8_MMA(0, 0, At, B0); PG8_MMA(0, 1, At, B1); PG8_BAR; PG8_SCHED;
;             PG8_LDA(At, 1, 1); PG8_STAGE(PG8_SB(1, 0), b3, voffB); PG8_STAGE(PG8_SB(1, 1), b3 + hsB, voffB); PG8_STAGE(PG8_SA(1, 0), a3, voffA);
;             PG8_WAIT_V(8); PG8_WAIT_L(0); PG8_BAR; PG8_MMA(1, 0, At, B0); PG8_MMA(1, 1, At, B1); PG8_BAR; PG8_SCHED;
	s_add_i32 s2, s2, s35
	v_lshl_add_u64 v[170:171], v[170:171], 0, s[28:29]
	s_mov_b32 m0, s2
	ds_read_b128 v[160:163], v209 offset:49152
	ds_read_b128 v[164:167], v209 offset:50176
	ds_read_b128 v[196:199], v209 offset:51200
	ds_read_b128 v[200:203], v209 offset:52224
	ds_read_b128 v[210:213], v209 offset:53248
	ds_read_b128 v[230:233], v209 offset:54272
	ds_read_b128 v[234:237], v209 offset:55296
	ds_read_b128 v[238:241], v209 offset:56320
	global_load_lds_dwordx4 v[170:171], off
	s_add_i32 m0, s2, 0x2000
	s_add_u32 s0, s0, 0x80080
	v_lshl_add_u64 v[170:171], v[172:173], 0, s[28:29]
	s_addc_u32 s1, s1, 0
	s_add_i32 s2, s24, s35
	global_load_lds_dwordx4 v[170:171], off
	v_lshl_add_u64 v[170:171], s[0:1], 0, v[188:189]
	s_mov_b32 m0, s2
	s_nop 0
	global_load_lds_dwordx4 v[170:171], off
	v_lshl_add_u64 v[170:171], s[0:1], 0, v[184:185]
	s_add_i32 m0, s2, 0x2000
	s_nop 0
	global_load_lds_dwordx4 v[170:171], off
	v_lshl_add_u64 v[170:171], v[242:243], 0, s[28:29]
	s_mov_b32 m0, s44
	s_nop 0
	global_load_lds_dwordx4 v[170:171], off
	v_lshl_add_u64 v[170:171], v[244:245], 0, s[28:29]
	s_mov_b32 m0, s45
	s_nop 0
	global_load_lds_dwordx4 v[170:171], off
	s_waitcnt vmcnt(8)
	s_waitcnt lgkmcnt(0)
	s_barrier
	v_mfma_f32_16x16x32_bf16 v[60:63], v[64:67], v[160:163], v[60:63]
	s_add_i32 s57, s57, 2
	s_add_u32 s16, s16, 0x100
	s_addc_u32 s17, s17, 0
	s_add_u32 s53, s53, 0x100
	v_mfma_f32_16x16x32_bf16 v[56:59], v[72:75], v[160:163], v[56:59]
	s_addc_u32 s56, s56, 0
	s_add_u32 s0, s16, 0xfff80080
	s_addc_u32 s1, s17, -1
	s_add_i32 s2, 0, 0x10000
	v_mfma_f32_16x16x32_bf16 v[44:47], v[64:67], v[196:199], v[44:47]
	s_cmp_eq_u32 s57, 28
	s_cselect_b32 s19, s11, s1
	s_cselect_b32 s18, s49, s0
	s_cselect_b32 s1, s9, s56
	v_mfma_f32_16x16x32_bf16 v[40:43], v[72:75], v[196:199], v[40:43]
	s_cselect_b32 s0, s52, s53
	s_add_i32 s55, 0, 0x14000
	s_cmp_gt_u32 s57, 29
	v_mfma_f32_16x16x32_bf16 v[28:31], v[64:67], v[210:213], v[28:31]
	v_mfma_f32_16x16x32_bf16 v[24:27], v[72:75], v[210:213], v[24:27]
	v_mfma_f32_16x16x32_bf16 v[12:15], v[64:67], v[234:237], v[12:15]
	v_mfma_f32_16x16x32_bf16 v[8:11], v[72:75], v[234:237], v[8:11]
	v_mfma_f32_16x16x32_bf16 v[60:63], v[68:71], v[164:167], v[60:63]
	v_mfma_f32_16x16x32_bf16 v[56:59], v[76:79], v[164:167], v[56:59]
	v_mfma_f32_16x16x32_bf16 v[44:47], v[68:71], v[200:203], v[44:47]
	v_mfma_f32_16x16x32_bf16 v[40:43], v[76:79], v[200:203], v[40:43]
	v_mfma_f32_16x16x32_bf16 v[28:31], v[68:71], v[230:233], v[28:31]
	v_mfma_f32_16x16x32_bf16 v[24:27], v[76:79], v[230:233], v[24:27]
	v_mfma_f32_16x16x32_bf16 v[12:15], v[68:71], v[238:241], v[12:15]
	v_mfma_f32_16x16x32_bf16 v[8:11], v[76:79], v[238:241], v[8:11]
	v_mfma_f32_16x16x32_bf16 v[52:55], v[144:147], v[160:163], v[52:55]
	v_mfma_f32_16x16x32_bf16 v[48:51], v[152:155], v[160:163], v[48:51]
	v_mfma_f32_16x16x32_bf16 v[36:39], v[144:147], v[196:199], v[36:39]
	v_mfma_f32_16x16x32_bf16 v[32:35], v[152:155], v[196:199], v[32:35]
	v_mfma_f32_16x16x32_bf16 v[20:23], v[144:147], v[210:213], v[20:23]
	v_mfma_f32_16x16x32_bf16 v[16:19], v[152:155], v[210:213], v[16:19]
	v_mfma_f32_16x16x32_bf16 v[4:7], v[144:147], v[234:237], v[4:7]
	v_mfma_f32_16x16x32_bf16 v[0:3], v[152:155], v[234:237], v[0:3]
	v_mfma_f32_16x16x32_bf16 v[52:55], v[148:151], v[164:167], v[52:55]
	v_mfma_f32_16x16x32_bf16 v[48:51], v[156:159], v[164:167], v[48:51]
	v_mfma_f32_16x16x32_bf16 v[36:39], v[148:151], v[200:203], v[36:39]
	v_mfma_f32_16x16x32_bf16 v[32:35], v[156:159], v[200:203], v[32:35]
	v_mfma_f32_16x16x32_bf16 v[20:23], v[148:151], v[230:233], v[20:23]
	v_mfma_f32_16x16x32_bf16 v[16:19], v[156:159], v[230:233], v[16:19]
	v_mfma_f32_16x16x32_bf16 v[4:7], v[148:151], v[238:241], v[4:7]
	v_mfma_f32_16x16x32_bf16 v[0:3], v[156:159], v[238:241], v[0:3]
	s_barrier
	s_cbranch_scc0 .Lkrot_e
	s_and_b64 vcc, exec, s[6:7]
	s_movk_i32 s49, 0x300
	s_mov_b64 s[52:53], 0x60000
	s_cbranch_vccz .LBB0_896
	s_barrier

; #define PG8_STAGE(bufoff, gbase, voff) do { _Pragma("unroll") for (int _i = 0; _i < 2; ++_i) \
;         __builtin_amdgcn_global_load_lds((const unsigned*)((const char*)(gbase) + (voff)[_i]), (LAS unsigned*)(lds + (bufoff) + ldsw + _i * 8192), 16, 0, 0); } while (0)
; #define PG8_LDA(dst, b, h) do { _Pragma("unroll") for (int m = 0; m < 4; ++m) _Pragma("unroll") for (int k = 0; k < 2; ++k) dst[m][k] = *(const LAS bf16x8*)(lds + PG8_SA(b, h) + aoff + m * 2048 + k * 1024); } while (0)
; #define PG8_LDB(dst, b, h) do { _Pragma("unroll") for (int n = 0; n < 2; ++n) _Pragma("unroll") for (int k = 0; k < 2; ++k) dst[n][k] = *(const LAS bf16x8*)(lds + PG8_SB(b, h) + boff + n * 2048 + k * 1024); } while (0)
; #define PG8_MMA(ai, bj, At, Bt) do { __builtin_amdgcn_s_setprio(1); _Pragma("unroll") for (int m = 0; m < 4; ++m) _Pragma("unroll") for (int n = 0; n < 2; ++n) _Pragma("unroll") for (int k = 0; k < 2; ++k) \
;         acc[ai][bj][m][n] = __builtin_amdgcn_mfma_f32_16x16x32_bf16(Bt[n][k], At[m][k], acc[ai][bj][m][n], 0, 0, 0); __builtin_amdgcn_s_setprio(0); } while (0)
; #define PG8_WAIT_V(n) asm volatile("s_waitcnt vmcnt(" #n ")" ::: "memory")
; #define PG8_WAIT_L(n) asm volatile("s_waitcnt lgkmcnt(" #n ")" ::: "memory")
; #define PG8_BAR __builtin_amdgcn_s_barrier()
; #define PG8_SCHED __builtin_amdgcn_sched_barrier(0)
; template <class Epi>
; __device__ __forceinline__ void gemm_phase(LAS unsigned char* lds, const Gemm g, const StaticOrder& S, const Epi& E, const int tid) {
;     ...
;             PG8_LDB(B0, 0, 0); PG8_LDB(B1, 0, 1); PG8_SCHED; PG8_LDA(At, 0, 0); PG8_STAGE(PG8_SA(1, 1), a1 + hsA, voffA);
;             PG8_WAIT_V(8); PG8_WAIT_L(0); PG8_BAR; PG8_MMA(0, 0, At, B0); PG8_MMA(0, 1, At, B1); PG8_BAR; PG8_SCHED;
;             PG8_LDA(At, 0, 1); PG8_STAGE(PG8_SB(0, 0), b2, voffB); PG8_STAGE(PG8_SB(0, 1), b2 + hsB, voffB); PG8_STAGE(PG8_SA(0, 0), a2, voffA);
;             PG8_WAIT_V(8); PG8_WAIT_L(0); PG8_BAR; PG8_MMA(1, 0, At, B0); PG8_MMA(1, 1, At, B1); PG8_BAR; PG8_SCHED;
.Lkrot_f:
	v_add_u32_e32 v154, s2, v143
	v_add_u32_e32 v166, s55, v143
	ds_read_b128 v[138:141], v154
	ds_read_b128 v[146:149], v154 offset:1024
	ds_read_b128 v[150:153], v154 offset:2048
	ds_read_b128 v[154:157], v154 offset:3072
	ds_read_b128 v[158:161], v166
	ds_read_b128 v[162:165], v166 offset:1024
	ds_read_b128 v[184:187], v166 offset:2048
	ds_read_b128 v[188:191], v166 offset:3072
	v_lshl_add_u64 v[166:167], s[18:19], 0, v[134:135]
	s_add_i32 m0, s40, 0xc000
	ds_read_b128 v[192:195], v145
	ds_read_b128 v[196:199], v145 offset:1024
	ds_read_b128 v[200:203], v145 offset:2048
	ds_read_b128 v[204:207], v145 offset:3072
	ds_read_b128 v[208:211], v145 offset:4096
	ds_read_b128 v[230:233], v145 offset:5120
	ds_read_b128 v[234:237], v145 offset:6144
	ds_read_b128 v[238:241], v145 offset:7168
	global_load_lds_dwordx4 v[166:167], off
	v_lshl_add_u64 v[166:167], s[18:19], 0, v[136:137]
	s_add_i32 m0, s40, 0xe000
	s_nop 0
	global_load_lds_dwordx4 v[166:167], off
	s_waitcnt vmcnt(8)
	s_waitcnt lgkmcnt(0)
	s_barrier
	v_mfma_f32_16x16x32_bf16 v[124:127], v[138:141], v[192:195], v[124:127]
	v_mfma_f32_16x16x32_bf16 v[116:119], v[150:153], v[192:195], v[116:119]
	v_mfma_f32_16x16x32_bf16 v[108:111], v[138:141], v[200:203], v[108:111]
	v_mfma_f32_16x16x32_bf16 v[100:103], v[150:153], v[200:203], v[100:103]
	v_mfma_f32_16x16x32_bf16 v[92:95], v[138:141], v[208:211], v[92:95]
	v_mfma_f32_16x16x32_bf16 v[84:87], v[150:153], v[208:211], v[84:87]
	v_mfma_f32_16x16x32_bf16 v[76:79], v[138:141], v[234:237], v[76:79]
	v_mfma_f32_16x16x32_bf16 v[68:71], v[150:153], v[234:237], v[68:71]
	v_mfma_f32_16x16x32_bf16 v[124:127], v[146:149], v[196:199], v[124:127]
	v_mfma_f32_16x16x32_bf16 v[116:119], v[154:157], v[196:199], v[116:119]
	v_mfma_f32_16x16x32_bf16 v[108:111], v[146:149], v[204:207], v[108:111]
	v_mfma_f32_16x16x32_bf16 v[100:103], v[154:157], v[204:207], v[100:103]
	v_mfma_f32_16x16x32_bf16 v[92:95], v[146:149], v[230:233], v[92:95]
	v_mfma_f32_16x16x32_bf16 v[84:87], v[154:157], v[230:233], v[84:87]
	v_mfma_f32_16x16x32_bf16 v[76:79], v[146:149], v[238:241], v[76:79]
	v_mfma_f32_16x16x32_bf16 v[68:71], v[154:157], v[238:241], v[68:71]
	v_mfma_f32_16x16x32_bf16 v[120:123], v[158:161], v[192:195], v[120:123]
	v_mfma_f32_16x16x32_bf16 v[112:115], v[184:187], v[192:195], v[112:115]
	v_mfma_f32_16x16x32_bf16 v[104:107], v[158:161], v[200:203], v[104:107]
	v_mfma_f32_16x16x32_bf16 v[96:99], v[184:187], v[200:203], v[96:99]
	v_mfma_f32_16x16x32_bf16 v[88:91], v[158:161], v[208:211], v[88:91]
	v_mfma_f32_16x16x32_bf16 v[80:83], v[184:187], v[208:211], v[80:83]
	v_mfma_f32_16x16x32_bf16 v[72:75], v[158:161], v[234:237], v[72:75]
	v_mfma_f32_16x16x32_bf16 v[64:67], v[184:187], v[234:237], v[64:67]
	v_mfma_f32_16x16x32_bf16 v[120:123], v[162:165], v[196:199], v[120:123]
	v_mfma_f32_16x16x32_bf16 v[112:115], v[188:191], v[196:199], v[112:115]
	v_mfma_f32_16x16x32_bf16 v[104:107], v[162:165], v[204:207], v[104:107]
	v_mfma_f32_16x16x32_bf16 v[96:99], v[188:191], v[204:207], v[96:99]
	v_mfma_f32_16x16x32_bf16 v[88:91], v[162:165], v[230:233], v[88:91]
	v_mfma_f32_16x16x32_bf16 v[80:83], v[188:191], v[230:233], v[80:83]
	v_mfma_f32_16x16x32_bf16 v[72:75], v[162:165], v[238:241], v[72:75]
	v_mfma_f32_16x16x32_bf16 v[64:67], v[188:191], v[238:241], v[64:67]
	s_barrier
	s_add_i32 s2, s2, s27
	v_lshl_add_u64 v[166:167], s[0:1], 0, v[168:169]
	s_mov_b32 m0, s2
	ds_read_b128 v[192:195], v145 offset:16384
	ds_read_b128 v[196:199], v145 offset:17408
	ds_read_b128 v[200:203], v145 offset:18432
	ds_read_b128 v[204:207], v145 offset:19456
	ds_read_b128 v[208:211], v145 offset:20480
	ds_read_b128 v[230:233], v145 offset:21504
	ds_read_b128 v[234:237], v145 offset:22528
	ds_read_b128 v[238:241], v145 offset:23552
	global_load_lds_dwordx4 v[166:167], off
	s_add_i32 m0, s2, 0x2000
	s_add_u32 s24, s0, 0x80000
	v_lshl_add_u64 v[170:171], s[0:1], 0, v[132:133]
	s_addc_u32 s25, s1, 0
	s_add_i32 s2, s55, s27
	global_load_lds_dwordx4 v[170:171], off
	v_lshl_add_u64 v[172:173], s[24:25], 0, v[168:169]
	s_mov_b32 m0, s2
	v_lshl_add_u64 v[212:213], s[34:35], 0, v[130:131]
	global_load_lds_dwordx4 v[172:173], off
	v_lshl_add_u64 v[172:173], s[24:25], 0, v[132:133]
	s_add_i32 m0, s2, 0x2000
	s_nop 0
	global_load_lds_dwordx4 v[172:173], off
	v_lshl_add_u64 v[172:173], s[34:35], 0, v[128:129]
	s_mov_b32 m0, s40
	s_nop 0
	global_load_lds_dwordx4 v[172:173], off
	s_mov_b32 m0, s41
	s_nop 0
	global_load_lds_dwordx4 v[212:213], off
	s_waitcnt vmcnt(8)
	s_waitcnt lgkmcnt(0)
	s_barrier
	v_mfma_f32_16x16x32_bf16 v[60:63], v[138:141], v[192:195], v[60:63]
	v_mfma_f32_16x16x32_bf16 v[52:55], v[150:153], v[192:195], v[52:55]
	v_mfma_f32_16x16x32_bf16 v[44:47], v[138:141], v[200:203], v[44:47]
	v_mfma_f32_16x16x32_bf16 v[36:39], v[150:153], v[200:203], v[36:39]
	v_mfma_f32_16x16x32_bf16 v[28:31], v[138:141], v[208:211], v[28:31]
	v_mfma_f32_16x16x32_bf16 v[20:23], v[150:153], v[208:211], v[20:23]
	v_mfma_f32_16x16x32_bf16 v[12:15], v[138:141], v[234:237], v[12:15]
	v_mfma_f32_16x16x32_bf16 v[4:7], v[150:153], v[234:237], v[4:7]
	v_mfma_f32_16x16x32_bf16 v[60:63], v[146:149], v[196:199], v[60:63]
	v_mfma_f32_16x16x32_bf16 v[52:55], v[154:157], v[196:199], v[52:55]
	v_mfma_f32_16x16x32_bf16 v[44:47], v[146:149], v[204:207], v[44:47]
	v_mfma_f32_16x16x32_bf16 v[36:39], v[154:157], v[204:207], v[36:39]
	v_mfma_f32_16x16x32_bf16 v[28:31], v[146:149], v[230:233], v[28:31]
	v_mfma_f32_16x16x32_bf16 v[20:23], v[154:157], v[230:233], v[20:23]
	v_mfma_f32_16x16x32_bf16 v[12:15], v[146:149], v[238:241], v[12:15]
	v_mfma_f32_16x16x32_bf16 v[4:7], v[154:157], v[238:241], v[4:7]
	v_mfma_f32_16x16x32_bf16 v[56:59], v[158:161], v[192:195], v[56:59]
	v_mfma_f32_16x16x32_bf16 v[48:51], v[184:187], v[192:195], v[48:51]
	v_mfma_f32_16x16x32_bf16 v[40:43], v[158:161], v[200:203], v[40:43]
	v_mfma_f32_16x16x32_bf16 v[32:35], v[184:187], v[200:203], v[32:35]
	v_mfma_f32_16x16x32_bf16 v[24:27], v[158:161], v[208:211], v[24:27]
	v_mfma_f32_16x16x32_bf16 v[16:19], v[184:187], v[208:211], v[16:19]
	v_mfma_f32_16x16x32_bf16 v[8:11], v[158:161], v[234:237], v[8:11]
	v_mfma_f32_16x16x32_bf16 v[0:3], v[184:187], v[234:237], v[0:3]
	v_mfma_f32_16x16x32_bf16 v[56:59], v[162:165], v[196:199], v[56:59]
	v_mfma_f32_16x16x32_bf16 v[48:51], v[188:191], v[196:199], v[48:51]
	v_mfma_f32_16x16x32_bf16 v[40:43], v[162:165], v[204:207], v[40:43]
	v_mfma_f32_16x16x32_bf16 v[32:35], v[188:191], v[204:207], v[32:35]
	v_mfma_f32_16x16x32_bf16 v[24:27], v[162:165], v[230:233], v[24:27]
	v_mfma_f32_16x16x32_bf16 v[16:19], v[188:191], v[230:233], v[16:19]
	v_mfma_f32_16x16x32_bf16 v[8:11], v[162:165], v[238:241], v[8:11]
	v_mfma_f32_16x16x32_bf16 v[0:3], v[188:191], v[238:241], v[0:3]
	s_barrier
; #define PG8_STAGE(bufoff, gbase, voff) do { _Pragma("unroll") for (int _i = 0; _i < 2; ++_i) \
;         __builtin_amdgcn_global_load_lds((const unsigned*)((const char*)(gbase) + (voff)[_i]), (LAS unsigned*)(lds + (bufoff) + ldsw + _i * 8192), 16, 0, 0); } while (0)
; #define PG8_LDA(dst, b, h) do { _Pragma("unroll") for (int m = 0; m < 4; ++m) _Pragma("unroll") for (int k = 0; k < 2; ++k) dst[m][k] = *(const LAS bf16x8*)(lds + PG8_SA(b, h) + aoff + m * 2048 + k * 1024); } while (0)
; #define PG8_LDB(dst, b, h) do { _Pragma("unroll") for (int n = 0; n < 2; ++n) _Pragma("unroll") for (int k = 0; k < 2; ++k) dst[n][k] = *(const LAS bf16x8*)(lds + PG8_SB(b, h) + boff + n * 2048 + k * 1024); } while (0)
; #define PG8_MMA(ai, bj, At, Bt) do { __builtin_amdgcn_s_setprio(1); _Pragma("unroll") for (int m = 0; m < 4; ++m) _Pragma("unroll") for (int n = 0; n < 2; ++n) _Pragma("unroll") for (int k = 0; k < 2; ++k) \
;         acc[ai][bj][m][n] = __builtin_amdgcn_mfma_f32_16x16x32_bf16(Bt[n][k], At[m][k], acc[ai][bj][m][n], 0, 0, 0); __builtin_amdgcn_s_setprio(0); } while (0)
; #define PG8_WAIT_V(n) asm volatile("s_waitcnt vmcnt(" #n ")" ::: "memory")
; #define PG8_WAIT_L(n) asm volatile("s_waitcnt lgkmcnt(" #n ")" ::: "memory")
; #define PG8_BAR __builtin_amdgcn_s_barrier()
; #define PG8_SCHED __builtin_amdgcn_sched_barrier(0)
; template <class Epi>
; __device__ __forceinline__ void gemm_phase(LAS unsigned char* lds, const Gemm g, const StaticOrder& S, const Epi& E, const int tid) {
;     ...
;             PG8_LDB(B0, 1, 0); PG8_LDB(B1, 1, 1); PG8_SCHED; PG8_LDA(At, 1, 0); PG8_STAGE(PG8_SA(0, 1), a2 + hsA, voffA);
;             PG8_WAIT_V(8); PG8_WAIT_L(0); PG8_BAR; PG8_MMA(0, 0, At, B0); PG8_MMA(0, 1, At, B1); PG8_BAR; PG8_SCHED;
	s_add_i32 s2, 0, 0x18000
	s_add_i32 s55, 0, 0x1c000
	v_add_u32_e32 v154, s2, v143
	v_add_u32_e32 v188, s55, v143
	ds_read_b128 v[138:141], v154
	ds_read_b128 v[146:149], v154 offset:1024
	ds_read_b128 v[150:153], v154 offset:2048
	ds_read_b128 v[154:157], v154 offset:3072
	ds_read_b128 v[158:161], v188
	ds_read_b128 v[162:165], v188 offset:1024
	ds_read_b128 v[184:187], v188 offset:2048
	ds_read_b128 v[188:191], v188 offset:3072
	s_add_u32 s24, s34, 0x80000
	s_addc_u32 s25, s35, 0
	s_mov_b32 m0, s42
	v_lshl_add_u64 v[242:243], s[24:25], 0, v[128:129]
	ds_read_b128 v[192:195], v145 offset:32768
	ds_read_b128 v[196:199], v145 offset:33792
	ds_read_b128 v[200:203], v145 offset:34816
	ds_read_b128 v[204:207], v145 offset:35840
	ds_read_b128 v[208:211], v145 offset:36864
	ds_read_b128 v[230:233], v145 offset:37888
	ds_read_b128 v[234:237], v145 offset:38912
	ds_read_b128 v[238:241], v145 offset:39936
	global_load_lds_dwordx4 v[242:243], off
	v_lshl_add_u64 v[242:243], s[24:25], 0, v[130:131]
	s_mov_b32 m0, s43
	s_nop 0
	global_load_lds_dwordx4 v[242:243], off
	s_waitcnt vmcnt(8)
	s_waitcnt lgkmcnt(0)
	s_barrier
	v_mfma_f32_16x16x32_bf16 v[124:127], v[138:141], v[192:195], v[124:127]
	v_mfma_f32_16x16x32_bf16 v[116:119], v[150:153], v[192:195], v[116:119]
	v_mfma_f32_16x16x32_bf16 v[108:111], v[138:141], v[200:203], v[108:111]
	v_mfma_f32_16x16x32_bf16 v[100:103], v[150:153], v[200:203], v[100:103]
	v_mfma_f32_16x16x32_bf16 v[92:95], v[138:141], v[208:211], v[92:95]
	v_mfma_f32_16x16x32_bf16 v[84:87], v[150:153], v[208:211], v[84:87]
	v_mfma_f32_16x16x32_bf16 v[76:79], v[138:141], v[234:237], v[76:79]
	v_mfma_f32_16x16x32_bf16 v[68:71], v[150:153], v[234:237], v[68:71]
	v_mfma_f32_16x16x32_bf16 v[124:127], v[146:149], v[196:199], v[124:127]
	v_mfma_f32_16x16x32_bf16 v[116:119], v[154:157], v[196:199], v[116:119]
	v_mfma_f32_16x16x32_bf16 v[108:111], v[146:149], v[204:207], v[108:111]
	v_mfma_f32_16x16x32_bf16 v[100:103], v[154:157], v[204:207], v[100:103]
	v_mfma_f32_16x16x32_bf16 v[92:95], v[146:149], v[230:233], v[92:95]
	v_mfma_f32_16x16x32_bf16 v[84:87], v[154:157], v[230:233], v[84:87]
	v_mfma_f32_16x16x32_bf16 v[76:79], v[146:149], v[238:241], v[76:79]
	v_mfma_f32_16x16x32_bf16 v[68:71], v[154:157], v[238:241], v[68:71]
	v_mfma_f32_16x16x32_bf16 v[120:123], v[158:161], v[192:195], v[120:123]
	v_mfma_f32_16x16x32_bf16 v[112:115], v[184:187], v[192:195], v[112:115]
	v_mfma_f32_16x16x32_bf16 v[104:107], v[158:161], v[200:203], v[104:107]
	v_mfma_f32_16x16x32_bf16 v[96:99], v[184:187], v[200:203], v[96:99]
	v_mfma_f32_16x16x32_bf16 v[88:91], v[158:161], v[208:211], v[88:91]
	v_mfma_f32_16x16x32_bf16 v[80:83], v[184:187], v[208:211], v[80:83]
	v_mfma_f32_16x16x32_bf16 v[72:75], v[158:161], v[234:237], v[72:75]
	v_mfma_f32_16x16x32_bf16 v[64:67], v[184:187], v[234:237], v[64:67]
	v_mfma_f32_16x16x32_bf16 v[120:123], v[162:165], v[196:199], v[120:123]
	v_mfma_f32_16x16x32_bf16 v[112:115], v[188:191], v[196:199], v[112:115]
	v_mfma_f32_16x16x32_bf16 v[104:107], v[162:165], v[204:207], v[104:107]
	v_mfma_f32_16x16x32_bf16 v[96:99], v[188:191], v[204:207], v[96:99]
	v_mfma_f32_16x16x32_bf16 v[88:91], v[162:165], v[230:233], v[88:91]
	v_mfma_f32_16x16x32_bf16 v[80:83], v[188:191], v[230:233], v[80:83]
	v_mfma_f32_16x16x32_bf16 v[72:75], v[162:165], v[238:241], v[72:75]
	v_mfma_f32_16x16x32_bf16 v[64:67], v[188:191], v[238:241], v[64:67]
	s_barrier
; #define PG8_STAGE(bufoff, gbase, voff) do { _Pragma("unroll") for (int _i = 0; _i < 2; ++_i) \
;         __builtin_amdgcn_global_load_lds((const unsigned*)((const char*)(gbase) + (voff)[_i]), (LAS unsigned*)(lds + (bufoff) + ldsw + _i * 8192), 16, 0, 0); } while (0)
; #define PG8_LDA(dst, b, h) do { _Pragma("unroll") for (int m = 0; m < 4; ++m) _Pragma("unroll") for (int k = 0; k < 2; ++k) dst[m][k] = *(const LAS bf16x8*)(lds + PG8_SA(b, h) + aoff + m * 2048 + k * 1024); } while (0)
; #define PG8_LDB(dst, b, h) do { _Pragma("unroll") for (int n = 0; n < 2; ++n) _Pragma("unroll") for (int k = 0; k < 2; ++k) dst[n][k] = *(const LAS bf16x8*)(lds + PG8_SB(b, h) + boff + n * 2048 + k * 1024); } while (0)
; #define PG8_WAIT_V(n) asm volatile("s_waitcnt vmcnt(" #n ")" ::: "memory")
; #define PG8_WAIT_L(n) asm volatile("s_waitcnt lgkmcnt(" #n ")" ::: "memory")
; template <class Epi>
; __device__ __forceinline__ void gemm_phase(LAS unsigned char* lds, const Gemm g, const StaticOrder& S, const Epi& E, const int tid) {
;     ...
;         for (int t = 0; t < nt; t += 2) {
;             const bool last = (t == nt - 2);
;             const char* a1 = cA + (size_t)(t + 1) * kstep;
;             const char* a2 = last ? nA : cA + (size_t)(t + 2) * kstep; const char* b2 = last ? nB : cB + (size_t)(t + 2) * kstep;
;             const char* a3 = a2 + kstep; const char* b3 = b2 + kstep;
;             PG8_LDB(B0, 0, 0); PG8_LDB(B1, 0, 1); PG8_SCHED; PG8_LDA(At, 0, 0); PG8_STAGE(PG8_SA(1, 1), a1 + hsA, voffA);
;             PG8_WAIT_V(8); PG8_WAIT_L(0); PG8_BAR; PG8_MMA(0, 0, At, B0); PG8_MMA(0, 1, At, B1); PG8_BAR; PG8_SCHED;
;             PG8_LDA(At, 0, 1); PG8_STAGE(PG8_SB(0, 0), b2, voffB); PG8_STAGE(PG8_SB(0, 1), b2 + hsB, voffB); PG8_STAGE(PG8_SA(0, 0), a2, voffA);
;             PG8_WAIT_V(8); PG8_WAIT_L(0); PG8_BAR; PG8_MMA(1, 0, At, B0); PG8_MMA(1, 1, At, B1); PG8_BAR; PG8_SCHED;
;             PG8_LDB(B0, 1, 0); PG8_LDB(B1, 1, 1); PG8_SCHED; PG8_LDA(At, 1, 0); PG8_STAGE(PG8_SA(0, 1), a2 + hsA, voffA);
;             PG8_WAIT_V(8); PG8_WAIT_L(0); PG8_BAR; PG8_MMA(0, 0, At, B0); PG8_MMA(0, 1, At, B1); PG8_BAR; PG8_SCHED;
;             PG8_LDA(At, 1, 1); PG8_STAGE(PG8_SB(1, 0), b3, voffB); PG8_STAGE(PG8_SB(1, 1), b3 + hsB, voffB); PG8_STAGE(PG8_SA(1, 0), a3, voffA);
;             PG8_WAIT_V(8); PG8_WAIT_L(0); PG8_BAR; PG8_MMA(1, 0, At, B0); PG8_MMA(1, 1, At, B1); PG8_BAR; PG8_SCHED;
	s_add_i32 s2, s2, s27
	v_lshl_add_u64 v[166:167], v[166:167], 0, s[28:29]
	s_mov_b32 m0, s2
	ds_read_b128 v[192:195], v145 offset:49152
	ds_read_b128 v[196:199], v145 offset:50176
	ds_read_b128 v[200:203], v145 offset:51200
	ds_read_b128 v[204:207], v145 offset:52224
	ds_read_b128 v[208:211], v145 offset:53248
	ds_read_b128 v[230:233], v145 offset:54272
	ds_read_b128 v[234:237], v145 offset:55296
	ds_read_b128 v[238:241], v145 offset:56320
	global_load_lds_dwordx4 v[166:167], off
	s_add_i32 m0, s2, 0x2000
	s_add_u32 s0, s0, 0x80080
	v_lshl_add_u64 v[166:167], v[170:171], 0, s[28:29]
	s_addc_u32 s1, s1, 0
	s_add_i32 s2, s55, s27
	global_load_lds_dwordx4 v[166:167], off
	v_lshl_add_u64 v[166:167], s[0:1], 0, v[168:169]
	s_mov_b32 m0, s2
	s_nop 0
	global_load_lds_dwordx4 v[166:167], off
	v_lshl_add_u64 v[166:167], s[0:1], 0, v[132:133]
	s_add_i32 m0, s2, 0x2000
	s_nop 0
	global_load_lds_dwordx4 v[166:167], off
	v_lshl_add_u64 v[166:167], v[172:173], 0, s[28:29]
	s_mov_b32 m0, s44
	s_nop 0
	global_load_lds_dwordx4 v[166:167], off
	v_lshl_add_u64 v[166:167], v[212:213], 0, s[28:29]
	s_mov_b32 m0, s45
	s_nop 0
	global_load_lds_dwordx4 v[166:167], off
	s_waitcnt vmcnt(8)
	s_waitcnt lgkmcnt(0)
	s_barrier
	v_mfma_f32_16x16x32_bf16 v[60:63], v[138:141], v[192:195], v[60:63]
	s_add_i32 s57, s57, 2
	s_add_u32 s18, s18, 0x100
	s_addc_u32 s19, s19, 0
	s_add_u32 s53, s53, 0x100
	v_mfma_f32_16x16x32_bf16 v[52:55], v[150:153], v[192:195], v[52:55]
	s_addc_u32 s56, s56, 0
	s_add_u32 s0, s18, 0xfff80080
	s_addc_u32 s1, s19, -1
	s_add_i32 s2, 0, 0x10000
	v_mfma_f32_16x16x32_bf16 v[44:47], v[138:141], v[200:203], v[44:47]
	s_cmp_eq_u32 s57, 28
	s_cselect_b32 s35, s13, s1
	s_cselect_b32 s34, s49, s0
	s_cselect_b32 s1, s11, s56
	v_mfma_f32_16x16x32_bf16 v[36:39], v[150:153], v[200:203], v[36:39]
	s_cselect_b32 s0, s52, s53
	s_add_i32 s55, 0, 0x14000
	s_cmp_gt_u32 s57, 29
	v_mfma_f32_16x16x32_bf16 v[28:31], v[138:141], v[208:211], v[28:31]
	v_mfma_f32_16x16x32_bf16 v[20:23], v[150:153], v[208:211], v[20:23]
	v_mfma_f32_16x16x32_bf16 v[12:15], v[138:141], v[234:237], v[12:15]
	v_mfma_f32_16x16x32_bf16 v[4:7], v[150:153], v[234:237], v[4:7]
	v_mfma_f32_16x16x32_bf16 v[60:63], v[146:149], v[196:199], v[60:63]
	v_mfma_f32_16x16x32_bf16 v[52:55], v[154:157], v[196:199], v[52:55]
	v_mfma_f32_16x16x32_bf16 v[44:47], v[146:149], v[204:207], v[44:47]
	v_mfma_f32_16x16x32_bf16 v[36:39], v[154:157], v[204:207], v[36:39]
	v_mfma_f32_16x16x32_bf16 v[28:31], v[146:149], v[230:233], v[28:31]
	v_mfma_f32_16x16x32_bf16 v[20:23], v[154:157], v[230:233], v[20:23]
	v_mfma_f32_16x16x32_bf16 v[12:15], v[146:149], v[238:241], v[12:15]
	v_mfma_f32_16x16x32_bf16 v[4:7], v[154:157], v[238:241], v[4:7]
	v_mfma_f32_16x16x32_bf16 v[56:59], v[158:161], v[192:195], v[56:59]
	v_mfma_f32_16x16x32_bf16 v[48:51], v[184:187], v[192:195], v[48:51]
	v_mfma_f32_16x16x32_bf16 v[40:43], v[158:161], v[200:203], v[40:43]
	v_mfma_f32_16x16x32_bf16 v[32:35], v[184:187], v[200:203], v[32:35]
	v_mfma_f32_16x16x32_bf16 v[24:27], v[158:161], v[208:211], v[24:27]
	v_mfma_f32_16x16x32_bf16 v[16:19], v[184:187], v[208:211], v[16:19]
	v_mfma_f32_16x16x32_bf16 v[8:11], v[158:161], v[234:237], v[8:11]
	v_mfma_f32_16x16x32_bf16 v[0:3], v[184:187], v[234:237], v[0:3]
	v_mfma_f32_16x16x32_bf16 v[56:59], v[162:165], v[196:199], v[56:59]
	v_mfma_f32_16x16x32_bf16 v[48:51], v[188:191], v[196:199], v[48:51]
	v_mfma_f32_16x16x32_bf16 v[40:43], v[162:165], v[204:207], v[40:43]
	v_mfma_f32_16x16x32_bf16 v[32:35], v[188:191], v[204:207], v[32:35]
	v_mfma_f32_16x16x32_bf16 v[24:27], v[162:165], v[230:233], v[24:27]
	v_mfma_f32_16x16x32_bf16 v[16:19], v[188:191], v[230:233], v[16:19]
	v_mfma_f32_16x16x32_bf16 v[8:11], v[162:165], v[238:241], v[8:11]
	v_mfma_f32_16x16x32_bf16 v[0:3], v[188:191], v[238:241], v[0:3]
	s_barrier
	s_cbranch_scc0 .Lkrot_f
	s_and_b64 vcc, exec, s[8:9]
	s_cbranch_vccz .LBB0_1007
	s_barrier

; #define PG8_STAGE(bufoff, gbase, voff) do { _Pragma("unroll") for (int _i = 0; _i < 2; ++_i) \
;         __builtin_amdgcn_global_load_lds((const unsigned*)((const char*)(gbase) + (voff)[_i]), (LAS unsigned*)(lds + (bufoff) + ldsw + _i * 8192), 16, 0, 0); } while (0)
; #define PG8_LDA(dst, b, h) do { _Pragma("unroll") for (int m = 0; m < 4; ++m) _Pragma("unroll") for (int k = 0; k < 2; ++k) dst[m][k] = *(const LAS bf16x8*)(lds + PG8_SA(b, h) + aoff + m * 2048 + k * 1024); } while (0)
; #define PG8_LDB(dst, b, h) do { _Pragma("unroll") for (int n = 0; n < 2; ++n) _Pragma("unroll") for (int k = 0; k < 2; ++k) dst[n][k] = *(const LAS bf16x8*)(lds + PG8_SB(b, h) + boff + n * 2048 + k * 1024); } while (0)
; #define PG8_MMA(ai, bj, At, Bt) do { __builtin_amdgcn_s_setprio(1); _Pragma("unroll") for (int m = 0; m < 4; ++m) _Pragma("unroll") for (int n = 0; n < 2; ++n) _Pragma("unroll") for (int k = 0; k < 2; ++k) \
;         acc[ai][bj][m][n] = __builtin_amdgcn_mfma_f32_16x16x32_bf16(Bt[n][k], At[m][k], acc[ai][bj][m][n], 0, 0, 0); __builtin_amdgcn_s_setprio(0); } while (0)
; #define PG8_WAIT_V(n) asm volatile("s_waitcnt vmcnt(" #n ")" ::: "memory")
; #define PG8_WAIT_L(n) asm volatile("s_waitcnt lgkmcnt(" #n ")" ::: "memory")
; #define PG8_BAR __builtin_amdgcn_s_barrier()
; #define PG8_SCHED __builtin_amdgcn_sched_barrier(0)
; template <class Epi>
; __device__ __forceinline__ void gemm_phase(LAS unsigned char* lds, const Gemm g, const StaticOrder& S, const Epi& E, const int tid) {
;     ...
;             PG8_LDB(B0, 0, 0); PG8_LDB(B1, 0, 1); PG8_SCHED; PG8_LDA(At, 0, 0); PG8_STAGE(PG8_SA(1, 1), a1 + hsA, voffA);
;             PG8_WAIT_V(8); PG8_WAIT_L(0); PG8_BAR; PG8_MMA(0, 0, At, B0); PG8_MMA(0, 1, At, B1); PG8_BAR; PG8_SCHED;
;             PG8_LDA(At, 0, 1); PG8_STAGE(PG8_SB(0, 0), b2, voffB); PG8_STAGE(PG8_SB(0, 1), b2 + hsB, voffB); PG8_STAGE(PG8_SA(0, 0), a2, voffA);
;             PG8_WAIT_V(8); PG8_WAIT_L(0); PG8_BAR; PG8_MMA(1, 0, At, B0); PG8_MMA(1, 1, At, B1); PG8_BAR; PG8_SCHED;
.Lkrot_g:
	v_add_u32_e32 v152, s2, v184
	v_add_u32_e32 v170, s24, v184
	ds_read_b128 v[128:131], v152
	ds_read_b128 v[144:147], v152 offset:1024
	ds_read_b128 v[148:151], v152 offset:2048
	ds_read_b128 v[152:155], v152 offset:3072
	ds_read_b128 v[156:159], v170
	ds_read_b128 v[160:163], v170 offset:1024
	ds_read_b128 v[164:167], v170 offset:2048
	ds_read_b128 v[190:193], v170 offset:3072
	v_lshl_add_u64 v[170:171], s[12:13], 0, v[140:141]
	s_add_i32 m0, s34, 0xc000
	ds_read_b128 v[194:197], v189
	ds_read_b128 v[198:201], v189 offset:1024
	ds_read_b128 v[202:205], v189 offset:2048
	ds_read_b128 v[206:209], v189 offset:3072
	ds_read_b128 v[210:213], v189 offset:4096
	ds_read_b128 v[230:233], v189 offset:5120
	ds_read_b128 v[234:237], v189 offset:6144
	ds_read_b128 v[238:241], v189 offset:7168
	global_load_lds_dwordx4 v[170:171], off
	v_lshl_add_u64 v[170:171], s[12:13], 0, v[142:143]
	s_add_i32 m0, s34, 0xe000
	s_nop 0
	global_load_lds_dwordx4 v[170:171], off
	s_waitcnt vmcnt(8)
	s_waitcnt lgkmcnt(0)
	s_barrier
	v_mfma_f32_16x16x32_bf16 v[124:127], v[128:131], v[194:197], v[124:127]
	v_mfma_f32_16x16x32_bf16 v[120:123], v[148:151], v[194:197], v[120:123]
	v_mfma_f32_16x16x32_bf16 v[108:111], v[128:131], v[202:205], v[108:111]
	v_mfma_f32_16x16x32_bf16 v[104:107], v[148:151], v[202:205], v[104:107]
	v_mfma_f32_16x16x32_bf16 v[92:95], v[128:131], v[210:213], v[92:95]
	v_mfma_f32_16x16x32_bf16 v[88:91], v[148:151], v[210:213], v[88:91]
	v_mfma_f32_16x16x32_bf16 v[80:83], v[128:131], v[234:237], v[80:83]
	v_mfma_f32_16x16x32_bf16 v[72:75], v[148:151], v[234:237], v[72:75]
	v_mfma_f32_16x16x32_bf16 v[124:127], v[144:147], v[198:201], v[124:127]
	v_mfma_f32_16x16x32_bf16 v[120:123], v[152:155], v[198:201], v[120:123]
	v_mfma_f32_16x16x32_bf16 v[108:111], v[144:147], v[206:209], v[108:111]
	v_mfma_f32_16x16x32_bf16 v[104:107], v[152:155], v[206:209], v[104:107]
	v_mfma_f32_16x16x32_bf16 v[92:95], v[144:147], v[230:233], v[92:95]
	v_mfma_f32_16x16x32_bf16 v[88:91], v[152:155], v[230:233], v[88:91]
	v_mfma_f32_16x16x32_bf16 v[80:83], v[144:147], v[238:241], v[80:83]
	v_mfma_f32_16x16x32_bf16 v[72:75], v[152:155], v[238:241], v[72:75]
	v_mfma_f32_16x16x32_bf16 v[116:119], v[156:159], v[194:197], v[116:119]
	v_mfma_f32_16x16x32_bf16 v[112:115], v[164:167], v[194:197], v[112:115]
	v_mfma_f32_16x16x32_bf16 v[100:103], v[156:159], v[202:205], v[100:103]
	v_mfma_f32_16x16x32_bf16 v[96:99], v[164:167], v[202:205], v[96:99]
	v_mfma_f32_16x16x32_bf16 v[84:87], v[156:159], v[210:213], v[84:87]
	v_mfma_f32_16x16x32_bf16 v[76:79], v[164:167], v[210:213], v[76:79]
	v_mfma_f32_16x16x32_bf16 v[68:71], v[156:159], v[234:237], v[68:71]
	v_mfma_f32_16x16x32_bf16 v[64:67], v[164:167], v[234:237], v[64:67]
	v_mfma_f32_16x16x32_bf16 v[116:119], v[160:163], v[198:201], v[116:119]
	v_mfma_f32_16x16x32_bf16 v[112:115], v[190:193], v[198:201], v[112:115]
	v_mfma_f32_16x16x32_bf16 v[100:103], v[160:163], v[206:209], v[100:103]
	v_mfma_f32_16x16x32_bf16 v[96:99], v[190:193], v[206:209], v[96:99]
	v_mfma_f32_16x16x32_bf16 v[84:87], v[160:163], v[230:233], v[84:87]
	v_mfma_f32_16x16x32_bf16 v[76:79], v[190:193], v[230:233], v[76:79]
	v_mfma_f32_16x16x32_bf16 v[68:71], v[160:163], v[238:241], v[68:71]
	v_mfma_f32_16x16x32_bf16 v[64:67], v[190:193], v[238:241], v[64:67]
	s_barrier
	s_add_i32 s2, s2, s27
	v_lshl_add_u64 v[170:171], s[14:15], 0, v[136:137]
	s_mov_b32 m0, s2
	ds_read_b128 v[194:197], v189 offset:16384
	ds_read_b128 v[198:201], v189 offset:17408
	ds_read_b128 v[202:205], v189 offset:18432
	ds_read_b128 v[206:209], v189 offset:19456
	ds_read_b128 v[210:213], v189 offset:20480
	ds_read_b128 v[230:233], v189 offset:21504
	ds_read_b128 v[234:237], v189 offset:22528
	ds_read_b128 v[238:241], v189 offset:23552
	global_load_lds_dwordx4 v[170:171], off
	s_add_i32 m0, s2, 0x2000
	s_add_u32 s12, s14, 0x160000
	v_lshl_add_u64 v[172:173], s[14:15], 0, v[132:133]
	s_addc_u32 s13, s15, 0
	s_add_i32 s2, s24, s27
	global_load_lds_dwordx4 v[172:173], off
	v_lshl_add_u64 v[242:243], s[12:13], 0, v[136:137]
	s_mov_b32 m0, s2
	v_lshl_add_u64 v[244:245], s[16:17], 0, v[134:135]
	global_load_lds_dwordx4 v[242:243], off
	v_lshl_add_u64 v[242:243], s[12:13], 0, v[132:133]
	s_add_i32 m0, s2, 0x2000
	s_nop 0
	global_load_lds_dwordx4 v[242:243], off
	v_lshl_add_u64 v[242:243], s[16:17], 0, v[138:139]
	s_mov_b32 m0, s34
	s_nop 0
	global_load_lds_dwordx4 v[242:243], off
	s_mov_b32 m0, s35
	s_nop 0
	global_load_lds_dwordx4 v[244:245], off
	s_waitcnt vmcnt(8)
	s_waitcnt lgkmcnt(0)
	s_barrier
	v_mfma_f32_16x16x32_bf16 v[60:63], v[128:131], v[194:197], v[60:63]
	v_mfma_f32_16x16x32_bf16 v[56:59], v[148:151], v[194:197], v[56:59]
	v_mfma_f32_16x16x32_bf16 v[44:47], v[128:131], v[202:205], v[44:47]
	v_mfma_f32_16x16x32_bf16 v[40:43], v[148:151], v[202:205], v[40:43]
	v_mfma_f32_16x16x32_bf16 v[28:31], v[128:131], v[210:213], v[28:31]
	v_mfma_f32_16x16x32_bf16 v[24:27], v[148:151], v[210:213], v[24:27]
	v_mfma_f32_16x16x32_bf16 v[12:15], v[128:131], v[234:237], v[12:15]
	v_mfma_f32_16x16x32_bf16 v[8:11], v[148:151], v[234:237], v[8:11]
	v_mfma_f32_16x16x32_bf16 v[60:63], v[144:147], v[198:201], v[60:63]
	v_mfma_f32_16x16x32_bf16 v[56:59], v[152:155], v[198:201], v[56:59]
	v_mfma_f32_16x16x32_bf16 v[44:47], v[144:147], v[206:209], v[44:47]
	v_mfma_f32_16x16x32_bf16 v[40:43], v[152:155], v[206:209], v[40:43]
	v_mfma_f32_16x16x32_bf16 v[28:31], v[144:147], v[230:233], v[28:31]
	v_mfma_f32_16x16x32_bf16 v[24:27], v[152:155], v[230:233], v[24:27]
	v_mfma_f32_16x16x32_bf16 v[12:15], v[144:147], v[238:241], v[12:15]
	v_mfma_f32_16x16x32_bf16 v[8:11], v[152:155], v[238:241], v[8:11]
	v_mfma_f32_16x16x32_bf16 v[52:55], v[156:159], v[194:197], v[52:55]
	v_mfma_f32_16x16x32_bf16 v[48:51], v[164:167], v[194:197], v[48:51]
	v_mfma_f32_16x16x32_bf16 v[36:39], v[156:159], v[202:205], v[36:39]
	v_mfma_f32_16x16x32_bf16 v[32:35], v[164:167], v[202:205], v[32:35]
	v_mfma_f32_16x16x32_bf16 v[20:23], v[156:159], v[210:213], v[20:23]
	v_mfma_f32_16x16x32_bf16 v[16:19], v[164:167], v[210:213], v[16:19]
	v_mfma_f32_16x16x32_bf16 v[4:7], v[156:159], v[234:237], v[4:7]
	v_mfma_f32_16x16x32_bf16 v[0:3], v[164:167], v[234:237], v[0:3]
	v_mfma_f32_16x16x32_bf16 v[52:55], v[160:163], v[198:201], v[52:55]
	v_mfma_f32_16x16x32_bf16 v[48:51], v[190:193], v[198:201], v[48:51]
	v_mfma_f32_16x16x32_bf16 v[36:39], v[160:163], v[206:209], v[36:39]
	v_mfma_f32_16x16x32_bf16 v[32:35], v[190:193], v[206:209], v[32:35]
	v_mfma_f32_16x16x32_bf16 v[20:23], v[160:163], v[230:233], v[20:23]
	v_mfma_f32_16x16x32_bf16 v[16:19], v[190:193], v[230:233], v[16:19]
	v_mfma_f32_16x16x32_bf16 v[4:7], v[160:163], v[238:241], v[4:7]
	v_mfma_f32_16x16x32_bf16 v[0:3], v[190:193], v[238:241], v[0:3]
	s_barrier
; #define PG8_STAGE(bufoff, gbase, voff) do { _Pragma("unroll") for (int _i = 0; _i < 2; ++_i) \
;         __builtin_amdgcn_global_load_lds((const unsigned*)((const char*)(gbase) + (voff)[_i]), (LAS unsigned*)(lds + (bufoff) + ldsw + _i * 8192), 16, 0, 0); } while (0)
; #define PG8_LDA(dst, b, h) do { _Pragma("unroll") for (int m = 0; m < 4; ++m) _Pragma("unroll") for (int k = 0; k < 2; ++k) dst[m][k] = *(const LAS bf16x8*)(lds + PG8_SA(b, h) + aoff + m * 2048 + k * 1024); } while (0)
; #define PG8_LDB(dst, b, h) do { _Pragma("unroll") for (int n = 0; n < 2; ++n) _Pragma("unroll") for (int k = 0; k < 2; ++k) dst[n][k] = *(const LAS bf16x8*)(lds + PG8_SB(b, h) + boff + n * 2048 + k * 1024); } while (0)
; #define PG8_MMA(ai, bj, At, Bt) do { __builtin_amdgcn_s_setprio(1); _Pragma("unroll") for (int m = 0; m < 4; ++m) _Pragma("unroll") for (int n = 0; n < 2; ++n) _Pragma("unroll") for (int k = 0; k < 2; ++k) \
;         acc[ai][bj][m][n] = __builtin_amdgcn_mfma_f32_16x16x32_bf16(Bt[n][k], At[m][k], acc[ai][bj][m][n], 0, 0, 0); __builtin_amdgcn_s_setprio(0); } while (0)
; #define PG8_WAIT_V(n) asm volatile("s_waitcnt vmcnt(" #n ")" ::: "memory")
; #define PG8_WAIT_L(n) asm volatile("s_waitcnt lgkmcnt(" #n ")" ::: "memory")
; #define PG8_BAR __builtin_amdgcn_s_barrier()
; #define PG8_SCHED __builtin_amdgcn_sched_barrier(0)
; template <class Epi>
; __device__ __forceinline__ void gemm_phase(LAS unsigned char* lds, const Gemm g, const StaticOrder& S, const Epi& E, const int tid) {
;     ...
;             PG8_LDB(B0, 1, 0); PG8_LDB(B1, 1, 1); PG8_SCHED; PG8_LDA(At, 1, 0); PG8_STAGE(PG8_SA(0, 1), a2 + hsA, voffA);
;             PG8_WAIT_V(8); PG8_WAIT_L(0); PG8_BAR; PG8_MMA(0, 0, At, B0); PG8_MMA(0, 1, At, B1); PG8_BAR; PG8_SCHED;
	s_add_i32 s2, 0, 0x18000
	s_add_i32 s24, 0, 0x1c000
	v_add_u32_e32 v152, s2, v184
	v_add_u32_e32 v190, s24, v184
	ds_read_b128 v[128:131], v152
	ds_read_b128 v[144:147], v152 offset:1024
	ds_read_b128 v[148:151], v152 offset:2048
	ds_read_b128 v[152:155], v152 offset:3072
	ds_read_b128 v[156:159], v190
	ds_read_b128 v[160:163], v190 offset:1024
	ds_read_b128 v[164:167], v190 offset:2048
	ds_read_b128 v[190:193], v190 offset:3072
	s_add_u32 s12, s16, 0x160000
	s_addc_u32 s13, s17, 0
	s_mov_b32 m0, s40
	v_lshl_add_u64 v[246:247], s[12:13], 0, v[138:139]
	ds_read_b128 v[194:197], v189 offset:32768
	ds_read_b128 v[198:201], v189 offset:33792
	ds_read_b128 v[202:205], v189 offset:34816
	ds_read_b128 v[206:209], v189 offset:35840
	ds_read_b128 v[210:213], v189 offset:36864
	ds_read_b128 v[230:233], v189 offset:37888
	ds_read_b128 v[234:237], v189 offset:38912
	ds_read_b128 v[238:241], v189 offset:39936
	global_load_lds_dwordx4 v[246:247], off
	v_lshl_add_u64 v[246:247], s[12:13], 0, v[134:135]
	s_mov_b32 m0, s41
	s_nop 0
	global_load_lds_dwordx4 v[246:247], off
	s_waitcnt vmcnt(8)
	s_waitcnt lgkmcnt(0)
	s_barrier
	v_mfma_f32_16x16x32_bf16 v[124:127], v[128:131], v[194:197], v[124:127]
	v_mfma_f32_16x16x32_bf16 v[120:123], v[148:151], v[194:197], v[120:123]
	v_mfma_f32_16x16x32_bf16 v[108:111], v[128:131], v[202:205], v[108:111]
	v_mfma_f32_16x16x32_bf16 v[104:107], v[148:151], v[202:205], v[104:107]
	v_mfma_f32_16x16x32_bf16 v[92:95], v[128:131], v[210:213], v[92:95]
	v_mfma_f32_16x16x32_bf16 v[88:91], v[148:151], v[210:213], v[88:91]
	v_mfma_f32_16x16x32_bf16 v[80:83], v[128:131], v[234:237], v[80:83]
	v_mfma_f32_16x16x32_bf16 v[72:75], v[148:151], v[234:237], v[72:75]
	v_mfma_f32_16x16x32_bf16 v[124:127], v[144:147], v[198:201], v[124:127]
	v_mfma_f32_16x16x32_bf16 v[120:123], v[152:155], v[198:201], v[120:123]
	v_mfma_f32_16x16x32_bf16 v[108:111], v[144:147], v[206:209], v[108:111]
	v_mfma_f32_16x16x32_bf16 v[104:107], v[152:155], v[206:209], v[104:107]
	v_mfma_f32_16x16x32_bf16 v[92:95], v[144:147], v[230:233], v[92:95]
	v_mfma_f32_16x16x32_bf16 v[88:91], v[152:155], v[230:233], v[88:91]
	v_mfma_f32_16x16x32_bf16 v[80:83], v[144:147], v[238:241], v[80:83]
	v_mfma_f32_16x16x32_bf16 v[72:75], v[152:155], v[238:241], v[72:75]
	v_mfma_f32_16x16x32_bf16 v[116:119], v[156:159], v[194:197], v[116:119]
	v_mfma_f32_16x16x32_bf16 v[112:115], v[164:167], v[194:197], v[112:115]
	v_mfma_f32_16x16x32_bf16 v[100:103], v[156:159], v[202:205], v[100:103]
	v_mfma_f32_16x16x32_bf16 v[96:99], v[164:167], v[202:205], v[96:99]
	v_mfma_f32_16x16x32_bf16 v[84:87], v[156:159], v[210:213], v[84:87]
	v_mfma_f32_16x16x32_bf16 v[76:79], v[164:167], v[210:213], v[76:79]
	v_mfma_f32_16x16x32_bf16 v[68:71], v[156:159], v[234:237], v[68:71]
	v_mfma_f32_16x16x32_bf16 v[64:67], v[164:167], v[234:237], v[64:67]
	v_mfma_f32_16x16x32_bf16 v[116:119], v[160:163], v[198:201], v[116:119]
	v_mfma_f32_16x16x32_bf16 v[112:115], v[190:193], v[198:201], v[112:115]
	v_mfma_f32_16x16x32_bf16 v[100:103], v[160:163], v[206:209], v[100:103]
	v_mfma_f32_16x16x32_bf16 v[96:99], v[190:193], v[206:209], v[96:99]
	v_mfma_f32_16x16x32_bf16 v[84:87], v[160:163], v[230:233], v[84:87]
	v_mfma_f32_16x16x32_bf16 v[76:79], v[190:193], v[230:233], v[76:79]
	v_mfma_f32_16x16x32_bf16 v[68:71], v[160:163], v[238:241], v[68:71]
	v_mfma_f32_16x16x32_bf16 v[64:67], v[190:193], v[238:241], v[64:67]
	s_barrier
; #define PG8_STAGE(bufoff, gbase, voff) do { _Pragma("unroll") for (int _i = 0; _i < 2; ++_i) \
;         __builtin_amdgcn_global_load_lds((const unsigned*)((const char*)(gbase) + (voff)[_i]), (LAS unsigned*)(lds + (bufoff) + ldsw + _i * 8192), 16, 0, 0); } while (0)
; #define PG8_LDA(dst, b, h) do { _Pragma("unroll") for (int m = 0; m < 4; ++m) _Pragma("unroll") for (int k = 0; k < 2; ++k) dst[m][k] = *(const LAS bf16x8*)(lds + PG8_SA(b, h) + aoff + m * 2048 + k * 1024); } while (0)
; #define PG8_LDB(dst, b, h) do { _Pragma("unroll") for (int n = 0; n < 2; ++n) _Pragma("unroll") for (int k = 0; k < 2; ++k) dst[n][k] = *(const LAS bf16x8*)(lds + PG8_SB(b, h) + boff + n * 2048 + k * 1024); } while (0)
; #define PG8_WAIT_V(n) asm volatile("s_waitcnt vmcnt(" #n ")" ::: "memory")
; #define PG8_WAIT_L(n) asm volatile("s_waitcnt lgkmcnt(" #n ")" ::: "memory")
; template <class Epi>
; __device__ __forceinline__ void gemm_phase(LAS unsigned char* lds, const Gemm g, const StaticOrder& S, const Epi& E, const int tid) {
;     ...
;         for (int t = 0; t < nt; t += 2) {
;             const bool last = (t == nt - 2);
;             const char* a1 = cA + (size_t)(t + 1) * kstep;
;             const char* a2 = last ? nA : cA + (size_t)(t + 2) * kstep; const char* b2 = last ? nB : cB + (size_t)(t + 2) * kstep;
;             const char* a3 = a2 + kstep; const char* b3 = b2 + kstep;
;             PG8_LDB(B0, 0, 0); PG8_LDB(B1, 0, 1); PG8_SCHED; PG8_LDA(At, 0, 0); PG8_STAGE(PG8_SA(1, 1), a1 + hsA, voffA);
;             PG8_WAIT_V(8); PG8_WAIT_L(0); PG8_BAR; PG8_MMA(0, 0, At, B0); PG8_MMA(0, 1, At, B1); PG8_BAR; PG8_SCHED;
;             PG8_LDA(At, 0, 1); PG8_STAGE(PG8_SB(0, 0), b2, voffB); PG8_STAGE(PG8_SB(0, 1), b2 + hsB, voffB); PG8_STAGE(PG8_SA(0, 0), a2, voffA);
;             PG8_WAIT_V(8); PG8_WAIT_L(0); PG8_BAR; PG8_MMA(1, 0, At, B0); PG8_MMA(1, 1, At, B1); PG8_BAR; PG8_SCHED;
;             PG8_LDB(B0, 1, 0); PG8_LDB(B1, 1, 1); PG8_SCHED; PG8_LDA(At, 1, 0); PG8_STAGE(PG8_SA(0, 1), a2 + hsA, voffA);
;             PG8_WAIT_V(8); PG8_WAIT_L(0); PG8_BAR; PG8_MMA(0, 0, At, B0); PG8_MMA(0, 1, At, B1); PG8_BAR; PG8_SCHED;
;             PG8_LDA(At, 1, 1); PG8_STAGE(PG8_SB(1, 0), b3, voffB); PG8_STAGE(PG8_SB(1, 1), b3 + hsB, voffB); PG8_STAGE(PG8_SA(1, 0), a3, voffA);
;             PG8_WAIT_V(8); PG8_WAIT_L(0); PG8_BAR; PG8_MMA(1, 0, At, B0); PG8_MMA(1, 1, At, B1); PG8_BAR; PG8_SCHED;
	s_add_i32 s2, s2, s27
	v_lshl_add_u64 v[170:171], v[170:171], 0, s[28:29]
	s_mov_b32 m0, s2
	ds_read_b128 v[194:197], v189 offset:49152
	ds_read_b128 v[198:201], v189 offset:50176
	ds_read_b128 v[202:205], v189 offset:51200
	ds_read_b128 v[206:209], v189 offset:52224
	ds_read_b128 v[210:213], v189 offset:53248
	ds_read_b128 v[230:233], v189 offset:54272
	ds_read_b128 v[234:237], v189 offset:55296
	ds_read_b128 v[238:241], v189 offset:56320
	global_load_lds_dwordx4 v[170:171], off
	s_add_i32 m0, s2, 0x2000
	s_add_u32 s12, s14, 0x160080
	v_lshl_add_u64 v[170:171], v[172:173], 0, s[28:29]
	s_addc_u32 s13, s15, 0
	s_add_i32 s2, s24, s27
	global_load_lds_dwordx4 v[170:171], off
	v_lshl_add_u64 v[170:171], s[12:13], 0, v[136:137]
	s_mov_b32 m0, s2
	s_nop 0
	global_load_lds_dwordx4 v[170:171], off
	v_lshl_add_u64 v[170:171], s[12:13], 0, v[132:133]
	s_add_i32 m0, s2, 0x2000
	s_nop 0
	global_load_lds_dwordx4 v[170:171], off
	v_lshl_add_u64 v[170:171], v[242:243], 0, s[28:29]
	s_mov_b32 m0, s44
	s_nop 0
	global_load_lds_dwordx4 v[170:171], off
	v_lshl_add_u64 v[170:171], v[244:245], 0, s[28:29]
	s_mov_b32 m0, s45
	s_nop 0
	global_load_lds_dwordx4 v[170:171], off
	s_waitcnt vmcnt(8)
	s_waitcnt lgkmcnt(0)
	s_barrier
	v_mfma_f32_16x16x32_bf16 v[60:63], v[128:131], v[194:197], v[60:63]
	s_add_i32 s53, s53, 2
	s_add_u32 s38, s38, 0x100
	s_addc_u32 s39, s39, 0
	s_mov_b64 s[12:13], s[0:1]
	v_mfma_f32_16x16x32_bf16 v[56:59], v[148:151], v[194:197], v[56:59]
	s_add_u32 s0, s12, 0x100
	s_addc_u32 s1, s13, 0
	s_add_i32 s2, 0, 0x10000
	s_cmpk_eq_i32 s53, 0x54
	v_mfma_f32_16x16x32_bf16 v[44:47], v[128:131], v[202:205], v[44:47]
	s_cselect_b32 s17, s9, s1
	s_cselect_b32 s16, s8, s0
	s_cselect_b32 s15, s11, s39
	s_cselect_b32 s14, s10, s38
	v_mfma_f32_16x16x32_bf16 v[40:43], v[148:151], v[202:205], v[40:43]
	s_add_i32 s24, 0, 0x14000
	s_cmpk_gt_u32 s53, 0x55
	v_mfma_f32_16x16x32_bf16 v[28:31], v[128:131], v[210:213], v[28:31]
	v_mfma_f32_16x16x32_bf16 v[24:27], v[148:151], v[210:213], v[24:27]
	v_mfma_f32_16x16x32_bf16 v[12:15], v[128:131], v[234:237], v[12:15]
	v_mfma_f32_16x16x32_bf16 v[8:11], v[148:151], v[234:237], v[8:11]
	v_mfma_f32_16x16x32_bf16 v[60:63], v[144:147], v[198:201], v[60:63]
	v_mfma_f32_16x16x32_bf16 v[56:59], v[152:155], v[198:201], v[56:59]
	v_mfma_f32_16x16x32_bf16 v[44:47], v[144:147], v[206:209], v[44:47]
	v_mfma_f32_16x16x32_bf16 v[40:43], v[152:155], v[206:209], v[40:43]
	v_mfma_f32_16x16x32_bf16 v[28:31], v[144:147], v[230:233], v[28:31]
	v_mfma_f32_16x16x32_bf16 v[24:27], v[152:155], v[230:233], v[24:27]
	v_mfma_f32_16x16x32_bf16 v[12:15], v[144:147], v[238:241], v[12:15]
	v_mfma_f32_16x16x32_bf16 v[8:11], v[152:155], v[238:241], v[8:11]
	v_mfma_f32_16x16x32_bf16 v[52:55], v[156:159], v[194:197], v[52:55]
	v_mfma_f32_16x16x32_bf16 v[48:51], v[164:167], v[194:197], v[48:51]
	v_mfma_f32_16x16x32_bf16 v[36:39], v[156:159], v[202:205], v[36:39]
	v_mfma_f32_16x16x32_bf16 v[32:35], v[164:167], v[202:205], v[32:35]
	v_mfma_f32_16x16x32_bf16 v[20:23], v[156:159], v[210:213], v[20:23]
	v_mfma_f32_16x16x32_bf16 v[16:19], v[164:167], v[210:213], v[16:19]
	v_mfma_f32_16x16x32_bf16 v[4:7], v[156:159], v[234:237], v[4:7]
	v_mfma_f32_16x16x32_bf16 v[0:3], v[164:167], v[234:237], v[0:3]
	v_mfma_f32_16x16x32_bf16 v[52:55], v[160:163], v[198:201], v[52:55]
	v_mfma_f32_16x16x32_bf16 v[48:51], v[190:193], v[198:201], v[48:51]
	v_mfma_f32_16x16x32_bf16 v[36:39], v[160:163], v[206:209], v[36:39]
	v_mfma_f32_16x16x32_bf16 v[32:35], v[190:193], v[206:209], v[32:35]
	v_mfma_f32_16x16x32_bf16 v[20:23], v[160:163], v[230:233], v[20:23]
	v_mfma_f32_16x16x32_bf16 v[16:19], v[190:193], v[230:233], v[16:19]
	v_mfma_f32_16x16x32_bf16 v[4:7], v[160:163], v[238:241], v[4:7]
	v_mfma_f32_16x16x32_bf16 v[0:3], v[190:193], v[238:241], v[0:3]
	s_barrier
	s_cbranch_scc0 .Lkrot_g
	s_and_b64 vcc, exec, s[6:7]
	s_cbranch_vccz .LBB0_1079
	s_barrier
